# division sequences in the mixer phases: range-rescale steps dropped and the constant 1.0 numerator used inline (no staging v_mov)
# baseline (speedup 1.0000x reference)
; DI float sigmoidf_(float z) { return 1.f / (1.f + __expf(-z)); }
; DI void rec_setup_lb(const Params& p, int l, int h, unsigned char* smem, int tid) {
;   float* LB = (float*)(smem + L_LB);
;   __syncthreads();
;   if (tid < 64) LB[tid] = (l == 1) ? sigmoidf_(p.hg_lb[256 + h * 64 + tid] - p.hg_lb[h * 64 + tid]) : 0.f;
;   __syncthreads();
; }
.LBB0_509:
	s_and_b64 vcc, exec, s[6:7]
	s_cbranch_vccz .LBB0_566
	v_readlane_b32 s2, v253, 39
	s_waitcnt vmcnt(0)
	v_mbcnt_lo_u32_b32 v68, -1, 0
	v_mbcnt_hi_u32_b32 v68, -1, v68
	s_waitcnt lgkmcnt(0)
	s_barrier
	v_or_b32_e32 v56, s2, v68
	v_cmp_gt_i32_e64 s[4:5], 64, v56
	s_and_saveexec_b64 s[6:7], s[4:5]
	s_cbranch_execz .LBB0_514
	v_readlane_b32 s8, v254, 19
	v_readlane_b32 s9, v254, 20
	v_mov_b32_e32 v0, 0
	s_andn2_b64 vcc, exec, s[8:9]
	s_cbranch_vccnz .LBB0_513
	s_lshl_b32 s2, s50, 6
	v_ashrrev_i32_e32 v57, 31, v56
	v_readlane_b32 s72, v253, 23
	v_lshl_add_u64 v[0:1], s[2:3], 0, v[56:57]
	v_readlane_b32 s78, v253, 29
	v_readlane_b32 s79, v253, 30
	v_readlane_b32 s73, v253, 24
	v_readlane_b32 s72, v254, 15
	v_lshl_add_u64 v[0:1], v[0:1], 2, s[78:79]
	global_load_dword v2, v[0:1], off offset:1024
	v_add_u32_e32 v0, s2, v56
	v_ashrrev_i32_e32 v1, 31, v0
	v_lshl_add_u64 v[0:1], v[0:1], 2, s[78:79]
	global_load_dword v0, v[0:1], off
	v_readlane_b32 s73, v254, 16
	v_readlane_b32 s74, v253, 25
	v_readlane_b32 s75, v253, 26
	v_readlane_b32 s76, v253, 27
	v_readlane_b32 s77, v253, 28
	v_readlane_b32 s80, v253, 31
	v_readlane_b32 s81, v253, 32
	v_readlane_b32 s82, v253, 33
	v_readlane_b32 s83, v253, 34
	v_readlane_b32 s84, v253, 35
	v_readlane_b32 s85, v253, 36
	v_readlane_b32 s86, v253, 37
	v_readlane_b32 s87, v253, 38
	s_waitcnt vmcnt(0)
	v_sub_f32_e32 v0, v2, v0
	v_mul_f32_e32 v0, 0xbfb8aa3b, v0
	v_exp_f32_e32 v0, v0
	s_nop 0
	v_add_f32_e32 v0, 1.0, v0
	v_rcp_f32_e32 v2, v0
	s_nop 0
	v_fma_f32 v3, -v0, v2, 1.0
	v_fmac_f32_e32 v2, v3, v2
	v_mul_f32_e32 v4, 1.0, v2
	v_fma_f32 v5, -v0, v4, 1.0
	v_fmac_f32_e32 v4, v5, v2
	v_fma_f32 v1, -v0, v4, 1.0
	v_fma_f32 v1, v1, v2, v4
	v_div_fixup_f32 v0, v1, v0, 1.0

; template <int MX>
; DI RecRaw rec_load(const Params& p, int b, int h, int dir, int T0, int tid) {
;     ...
;     w.a0 = *(const uint4*)(rp + fcol); w.a1 = *(const uint4*)(rp + fcol + 8);
;     w.b0 = *(const uint4*)(rp + B_Q + h * 64 + k0); w.b1 = *(const uint4*)(rp + B_Q + h * 64 + k0 + 8);
;     w.c0 = *(const uint4*)(rp + B_I + h * 64 + k0); w.c1 = *(const uint4*)(rp + B_I + h * 64 + k0 + 8);
; template <int MX, bool OUT>
; DI void rec_chunk(const Params& p, int l, int b, int h, int dir, int T0, unsigned char* smem, f32x4 (&St)[4], float& nst, float& dtot, int tid, const RecRaw& raw) {
;     ...
;     if (MX == 0) {
; #pragma unroll
;       for (int i = 0; i < 8; ++i) {
; #pragma unroll
;         for (int hh = 0; hh < 2; ++hh) {
;           const int k = 2 * i + hh;
;           float z = __uint_as_float(hh ? (au[i] & 0xffff0000u) : (au[i] << 16));
;           z = fminf(fmaxf(z, -30.f), 30.f);
;           const float e = __expf(-z);
;           const float sg = 1.f / (1.f + e);
;           const float lb = LB[k0 + k];
;           lf[k] = __log2f(lb + (1.f - lb) * sg);
;           kin[k] = (1.f - lb) * (e * sg);
;           qv[k] = __uint_as_float(hh ? (bu[i] & 0xffff0000u) : (bu[i] << 16)) * 0.125f;
;           vv[k] = __uint_as_float(hh ? (cu[i] & 0xffff0000u) : (cu[i] << 16));
;         }
;       }
.LBB0_515:
	s_cmp_eq_u32 s25, -1
	s_cselect_b32 s26, 3, s28
	s_cselect_b32 s27, 0, s25
	s_and_b64 s[22:23], s[0:1], exec
	s_cselect_b32 s22, s26, s27
	s_lshl_b32 s22, s22, 6
	s_add_i32 s22, s22, s24
	s_ashr_i32 s23, s22, 31
	s_waitcnt vmcnt(0) lgkmcnt(0)
	v_mov_b64_e32 v[90:91], v[2:3]
	v_mov_b64_e32 v[92:93], v[0:1]
	v_lshl_add_u64 v[0:1], v[60:61], 0, s[22:23]
	v_mov_b64_e32 v[2:3], s[12:13]
	v_mad_u64_u32 v[20:21], s[22:23], v0, s33, v[2:3]
	v_lshlrev_b32_e32 v0, 16, v92
	v_max_f32_e32 v0, v0, v0
	v_med3_f32 v0, v0, s17, v190
	v_mul_f32_e32 v0, 0xbfb8aa3b, v0
	v_exp_f32_e32 v116, v0
	v_mad_i32_i24 v21, v1, s33, v21
	v_mov_b64_e32 v[66:67], v[4:5]
	v_lshl_add_u64 v[4:5], v[20:21], 0, v[160:161]
	v_add_f32_e32 v40, 1.0, v116
	v_rcp_f32_e32 v42, v40
	v_lshl_add_u64 v[20:21], v[20:21], 0, s[2:3]
	v_mov_b32_e32 v63, v161
	v_lshl_add_u64 v[20:21], v[20:21], 0, v[62:63]
	v_fma_f32 v43, -v40, v42, 1.0
	v_fmac_f32_e32 v42, v43, v42
	v_mul_f32_e32 v44, 1.0, v42
	v_fma_f32 v45, -v40, v44, 1.0
	v_fmac_f32_e32 v44, v45, v42
	v_fma_f32 v41, -v40, v44, 1.0
	v_fma_f32 v41, v41, v42, v44
	v_div_fixup_f32 v122, v41, v40, 1.0
	v_and_b32_e32 v40, 0xffff0000, v92
	v_max_f32_e32 v40, v40, v40
	v_med3_f32 v40, v40, s17, v190
	v_mul_f32_e32 v40, 0xbfb8aa3b, v40
	v_exp_f32_e32 v109, v40
	v_mov_b64_e32 v[64:65], v[6:7]
	global_load_dwordx4 v[0:3], v[4:5], off
	s_nop 0
	global_load_dwordx4 v[4:7], v[4:5], off offset:16
	s_nop 0
	global_load_dwordx4 v[24:27], v[20:21], off offset:3072
	s_nop 0
	global_load_dwordx4 v[20:23], v[20:21], off offset:3088
	v_add_f32_e32 v63, 1.0, v109
	v_rcp_f32_e32 v94, v63
	ds_read_b128 v[44:47], v69
	ds_read_b128 v[52:55], v69 offset:16
	ds_read_b128 v[48:51], v69 offset:32
	ds_read_b128 v[40:43], v69 offset:48
	s_waitcnt lgkmcnt(0)
	v_sub_f32_e32 v125, 1.0, v44
	v_fma_f32 v95, -v63, v94, 1.0
	v_fmac_f32_e32 v94, v95, v94
	v_mul_f32_e32 v96, 1.0, v94
	v_fma_f32 v97, -v63, v96, 1.0
	v_fmac_f32_e32 v96, v97, v94
	v_fma_f32 v92, -v63, v96, 1.0
	v_lshlrev_b32_e32 v95, 16, v93
	v_max_f32_e32 v95, v95, v95
	v_med3_f32 v95, v95, s17, v190
	v_mul_f32_e32 v95, 0xbfb8aa3b, v95
	v_exp_f32_e32 v117, v95
	v_fma_f32 v92, v92, v94, v96
	v_div_fixup_f32 v118, v92, v63, 1.0
	v_and_b32_e32 v93, 0xffff0000, v93
	v_add_f32_e32 v63, 1.0, v117
	v_rcp_f32_e32 v94, v63
	v_max_f32_e32 v93, v93, v93
	v_med3_f32 v93, v93, s17, v190
	v_mul_f32_e32 v93, 0xbfb8aa3b, v93
	v_fma_f32 v95, -v63, v94, 1.0
	v_fmac_f32_e32 v94, v95, v94
	v_mul_f32_e32 v96, 1.0, v94
	v_fma_f32 v97, -v63, v96, 1.0
	v_exp_f32_e32 v103, v93
	v_fmac_f32_e32 v96, v97, v94
	v_fma_f32 v92, -v63, v96, 1.0
	v_fma_f32 v92, v92, v94, v96
	v_div_fixup_f32 v124, v92, v63, 1.0
	v_add_f32_e32 v63, 1.0, v103
	v_rcp_f32_e32 v93, v63
	v_sub_f32_e32 v107, 1.0, v48
	v_sub_f32_e32 v101, 1.0, v50
	v_sub_f32_e32 v120, 1.0, v45
	v_fma_f32 v94, -v63, v93, 1.0
	v_fmac_f32_e32 v93, v94, v93
	v_mul_f32_e32 v95, 1.0, v93
	v_fma_f32 v96, -v63, v95, 1.0
	v_fmac_f32_e32 v95, v96, v93
	v_fma_f32 v92, -v63, v95, 1.0
	v_lshlrev_b32_e32 v94, 16, v90
	v_max_f32_e32 v94, v94, v94
	v_med3_f32 v94, v94, s17, v190
	v_mul_f32_e32 v94, 0xbfb8aa3b, v94
	v_exp_f32_e32 v111, v94
	v_fma_f32 v92, v92, v93, v95
	v_div_fixup_f32 v112, v92, v63, 1.0
	v_and_b32_e32 v90, 0xffff0000, v90
	v_add_f32_e32 v63, 1.0, v111
	v_rcp_f32_e32 v93, v63
	v_max_f32_e32 v90, v90, v90
	v_med3_f32 v90, v90, s17, v190
	v_mul_f32_e32 v90, 0xbfb8aa3b, v90
	v_fma_f32 v94, -v63, v93, 1.0
	v_fmac_f32_e32 v93, v94, v93
	v_mul_f32_e32 v95, 1.0, v93
	v_fma_f32 v96, -v63, v95, 1.0
	v_exp_f32_e32 v97, v90
	v_fmac_f32_e32 v95, v96, v93
	v_fma_f32 v92, -v63, v95, 1.0
	v_fma_f32 v90, v92, v93, v95
	v_div_fixup_f32 v121, v90, v63, 1.0
	v_add_f32_e32 v63, 1.0, v97
	v_rcp_f32_e32 v92, v63
	v_sub_f32_e32 v96, 1.0, v49
	v_sub_f32_e32 v123, 1.0, v46
	v_sub_f32_e32 v114, 1.0, v47
	v_fma_f32 v93, -v63, v92, 1.0
	v_fmac_f32_e32 v92, v93, v92
	v_mul_f32_e32 v94, 1.0, v92
	v_fma_f32 v95, -v63, v94, 1.0
	v_fmac_f32_e32 v94, v95, v92
	v_fma_f32 v90, -v63, v94, 1.0
	v_lshlrev_b32_e32 v93, 16, v91
	v_max_f32_e32 v93, v93, v93
	v_med3_f32 v93, v93, s17, v190
	v_mul_f32_e32 v93, 0xbfb8aa3b, v93
	v_exp_f32_e32 v105, v93
	v_fma_f32 v90, v90, v92, v94
	v_div_fixup_f32 v106, v90, v63, 1.0
	v_and_b32_e32 v91, 0xffff0000, v91
	v_add_f32_e32 v63, 1.0, v105
	v_rcp_f32_e32 v93, v63
	v_max_f32_e32 v91, v91, v91
	v_med3_f32 v91, v91, s17, v190
	v_mul_f32_e32 v91, 0xbfb8aa3b, v91
	v_fma_f32 v92, -v63, v93, 1.0
	v_fmac_f32_e32 v93, v92, v93
	v_mul_f32_e32 v94, 1.0, v93
	v_fma_f32 v95, -v63, v94, 1.0
	v_fmac_f32_e32 v94, v95, v93
	v_fma_f32 v90, -v63, v94, 1.0
	v_exp_f32_e32 v92, v91
	v_fma_f32 v90, v90, v93, v94
	v_div_fixup_f32 v115, v90, v63, 1.0
	v_fma_f32 v44, v122, v125, v44
	v_add_f32_e32 v63, 1.0, v92
	v_rcp_f32_e32 v91, v63
	v_fma_f32 v45, v118, v120, v45
	v_fma_f32 v46, v124, v123, v46
	v_fmac_f32_e32 v47, v112, v114
	v_fma_f32 v93, -v63, v91, 1.0
	v_fmac_f32_e32 v91, v93, v91
	v_mul_f32_e32 v94, 1.0, v91
	v_fma_f32 v95, -v63, v94, 1.0
	v_fmac_f32_e32 v94, v95, v91
	v_fma_f32 v90, -v63, v94, 1.0
	v_lshlrev_b32_e32 v93, 16, v66
	v_max_f32_e32 v93, v93, v93
	v_med3_f32 v93, v93, s17, v190
	v_mul_f32_e32 v93, 0xbfb8aa3b, v93
	v_exp_f32_e32 v99, v93
	v_fma_f32 v90, v90, v91, v94
	v_div_fixup_f32 v100, v90, v63, 1.0
	v_and_b32_e32 v66, 0xffff0000, v66
	v_add_f32_e32 v63, 1.0, v99
	v_rcp_f32_e32 v91, v63
	v_max_f32_e32 v66, v66, v66
	v_med3_f32 v66, v66, s17, v190
	v_mul_f32_e32 v66, 0xbfb8aa3b, v66
	v_fma_f32 v93, -v63, v91, 1.0
	v_fmac_f32_e32 v91, v93, v91
	v_mul_f32_e32 v94, 1.0, v91
	v_fma_f32 v95, -v63, v94, 1.0
; template <int MX, bool OUT>
; DI void rec_chunk(const Params& p, int l, int b, int h, int dir, int T0, unsigned char* smem, f32x4 (&St)[4], float& nst, float& dtot, int tid, const RecRaw& raw) {
;     ...
;           float z = __uint_as_float(hh ? (au[i] & 0xffff0000u) : (au[i] << 16));
;           z = fminf(fmaxf(z, -30.f), 30.f);
;           const float e = __expf(-z);
;           const float sg = 1.f / (1.f + e);
;           const float lb = LB[k0 + k];
;           lf[k] = __log2f(lb + (1.f - lb) * sg);
;           kin[k] = (1.f - lb) * (e * sg);
;           qv[k] = __uint_as_float(hh ? (bu[i] & 0xffff0000u) : (bu[i] << 16)) * 0.125f;
;           vv[k] = __uint_as_float(hh ? (cu[i] & 0xffff0000u) : (cu[i] << 16));
;         }
;       }
;     } else {
;       const float ig = raw.ig, fg = raw.fg;
;       const float lfs = (fg < -20.f) ? fg * 1.4426950408889634f : -__log2f(1.f + __expf(-fg));
;       const float ei = __expf(ig) * 0.125f;
; #pragma unroll
;       for (int i = 0; i < 8; ++i) {
; #pragma unroll
;         for (int hh = 0; hh < 2; ++hh) {
;           const int k = 2 * i + hh;
;           lf[k] = lfs;
;           kin[k] = __uint_as_float(hh ? (au[i] & 0xffff0000u) : (au[i] << 16)) * ei;
;           qv[k] = __uint_as_float(hh ? (bu[i] & 0xffff0000u) : (bu[i] << 16));
;           vv[k] = __uint_as_float(hh ? (cu[i] & 0xffff0000u) : (cu[i] << 16));
;         }
;       }
;     }
; #pragma unroll
;     for (int i = 0; i < 4; ++i) { if (MX == 0) *(float4*)(CUM + tt * 64 + k0 + 4 * i) = make_float4(lf[4 * i], lf[4 * i + 1], lf[4 * i + 2], lf[4 * i + 3]); }
;     if (MX == 1 && grp == 0) CUM[tt * 64] = lf[0];
;   }
;   __syncthreads();
;   if (MX == 1) {
;     if (w == 0) {
;       float x = CUM[lane * 64];
; #pragma unroll
;       for (int o = 1; o < 64; o <<= 1) {
;         const float y = dir == 0 ? __shfl_up(x, o) : __shfl_down(x, o);
;         const bool ok = dir == 0 ? (lane >= o) : (lane + o < 64);
;         x += ok ? y : 0.f;
;       }
;       CUM[lane * 64] = x;
;     }
;     __syncthreads();
;   } else {
;     const int k = tid & 63, part = tid >> 6;
;     float x[16];
;     float acc = 0.f;
;     if (dir == 0) {
; #pragma unroll
;       for (int i = 0; i < 16; ++i) { acc += CUM[(part * 16 + i) * 64 + k]; x[i] = acc; }
;     } else {
; #pragma unroll
;       for (int i = 15; i >= 0; --i) { acc += CUM[(part * 16 + i) * 64 + k]; x[i] = acc; }
;     }
	v_exp_f32_e32 v66, v66
	v_fmac_f32_e32 v94, v95, v91
	v_fma_f32 v90, -v63, v94, 1.0
	v_fma_f32 v90, v90, v91, v94
	v_div_fixup_f32 v110, v90, v63, 1.0
	v_add_f32_e32 v63, 1.0, v66
	v_rcp_f32_e32 v91, v63
	v_fma_f32 v48, v110, v107, v48
	v_log_f32_e32 v126, v48
	v_sub_f32_e32 v119, 1.0, v52
	v_fma_f32 v48, -v63, v91, 1.0
	v_fmac_f32_e32 v91, v48, v91
	v_mul_f32_e32 v94, 1.0, v91
	v_fma_f32 v93, -v63, v94, 1.0
	v_fmac_f32_e32 v94, v93, v91
	v_fma_f32 v48, -v63, v94, 1.0
	v_lshlrev_b32_e32 v90, 16, v67
	v_max_f32_e32 v90, v90, v90
	v_med3_f32 v90, v90, s17, v190
	v_mul_f32_e32 v90, 0xbfb8aa3b, v90
	v_exp_f32_e32 v93, v90
	v_fma_f32 v48, v48, v91, v94
	v_div_fixup_f32 v94, v48, v63, 1.0
	v_fma_f32 v49, v94, v96, v49
	v_add_f32_e32 v48, 1.0, v93
	v_rcp_f32_e32 v90, v48
	v_log_f32_e32 v127, v49
	v_sub_f32_e32 v108, 1.0, v53
	v_sub_f32_e32 v113, 1.0, v54
	v_fma_f32 v49, -v48, v90, 1.0
	v_fmac_f32_e32 v90, v49, v90
	v_mul_f32_e32 v91, 1.0, v90
	v_fma_f32 v95, -v48, v91, 1.0
	v_fmac_f32_e32 v91, v95, v90
	v_fma_f32 v63, -v48, v91, 1.0
	v_and_b32_e32 v49, 0xffff0000, v67
	v_max_f32_e32 v49, v49, v49
	v_med3_f32 v49, v49, s17, v190
	v_mul_f32_e32 v49, 0xbfb8aa3b, v49
	v_exp_f32_e32 v49, v49
	v_fma_f32 v63, v63, v90, v91
	v_div_fixup_f32 v104, v63, v48, 1.0
	v_fma_f32 v50, v104, v101, v50
	v_add_f32_e32 v48, 1.0, v49
	v_rcp_f32_e32 v90, v48
	v_log_f32_e32 v128, v50
	v_sub_f32_e32 v102, 1.0, v55
	v_log_f32_e32 v44, v44
	v_fma_f32 v50, -v48, v90, 1.0
	v_fmac_f32_e32 v90, v50, v90
	v_mul_f32_e32 v91, 1.0, v90
	v_fma_f32 v67, -v48, v91, 1.0
	v_fmac_f32_e32 v91, v67, v90
	v_fma_f32 v50, -v48, v91, 1.0
	v_lshlrev_b32_e32 v63, 16, v64
	v_max_f32_e32 v63, v63, v63
	v_med3_f32 v63, v63, s17, v190
	v_mul_f32_e32 v63, 0xbfb8aa3b, v63
	v_exp_f32_e32 v67, v63
	v_fma_f32 v50, v50, v90, v91
	v_div_fixup_f32 v90, v50, v48, 1.0
	v_sub_f32_e32 v91, 1.0, v51
	v_add_f32_e32 v50, 1.0, v67
	v_rcp_f32_e32 v63, v50
	v_fmac_f32_e32 v51, v90, v91
	v_log_f32_e32 v129, v51
	v_log_f32_e32 v45, v45
	v_fma_f32 v51, -v50, v63, 1.0
	v_fmac_f32_e32 v63, v51, v63
	v_mul_f32_e32 v95, 1.0, v63
	v_fma_f32 v98, -v50, v95, 1.0
	v_fmac_f32_e32 v95, v98, v63
	v_fma_f32 v51, -v50, v95, 1.0
	v_and_b32_e32 v48, 0xffff0000, v64
	v_max_f32_e32 v48, v48, v48
	v_med3_f32 v48, v48, s17, v190
	v_mul_f32_e32 v48, 0xbfb8aa3b, v48
	v_exp_f32_e32 v48, v48
	v_fma_f32 v51, v51, v63, v95
	v_div_fixup_f32 v98, v51, v50, 1.0
	v_sub_f32_e32 v95, 1.0, v40
	v_add_f32_e32 v51, 1.0, v48
	v_rcp_f32_e32 v63, v51
	v_fma_f32 v40, v98, v95, v40
	v_log_f32_e32 v130, v40
	v_log_f32_e32 v46, v46
	v_fma_f32 v40, -v51, v63, 1.0
	v_fmac_f32_e32 v63, v40, v63
	v_mul_f32_e32 v64, 1.0, v63
	v_fma_f32 v131, -v51, v64, 1.0
	v_fmac_f32_e32 v64, v131, v63
	v_fma_f32 v40, -v51, v64, 1.0
	v_lshlrev_b32_e32 v50, 16, v65
	v_max_f32_e32 v50, v50, v50
	v_med3_f32 v50, v50, s17, v190
	v_mul_f32_e32 v50, 0xbfb8aa3b, v50
	v_exp_f32_e32 v50, v50
	v_fma_f32 v40, v40, v63, v64
	v_div_fixup_f32 v51, v40, v51, 1.0
	v_sub_f32_e32 v63, 1.0, v41
	v_add_f32_e32 v64, 1.0, v50
	v_rcp_f32_e32 v132, v64
	v_fma_f32 v41, v51, v63, v41
	v_log_f32_e32 v131, v41
	v_log_f32_e32 v47, v47
	v_fma_f32 v41, -v64, v132, 1.0
	v_fmac_f32_e32 v132, v41, v132
	v_mul_f32_e32 v133, 1.0, v132
	v_fma_f32 v134, -v64, v133, 1.0
	v_fmac_f32_e32 v133, v134, v132
	v_fma_f32 v41, -v64, v133, 1.0
	v_and_b32_e32 v40, 0xffff0000, v65
	v_max_f32_e32 v40, v40, v40
	v_med3_f32 v40, v40, s17, v190
	v_mul_f32_e32 v40, 0xbfb8aa3b, v40
	v_exp_f32_e32 v40, v40
	v_fma_f32 v41, v41, v132, v133
	v_div_fixup_f32 v65, v41, v64, 1.0
	v_sub_f32_e32 v64, 1.0, v42
	v_add_f32_e32 v41, 1.0, v40
	v_rcp_f32_e32 v134, v41
	v_fma_f32 v42, v65, v64, v42
	v_log_f32_e32 v132, v42
	v_fma_f32 v52, v121, v119, v52
	v_fma_f32 v42, -v41, v134, 1.0
	v_fmac_f32_e32 v134, v42, v134
	v_mul_f32_e32 v135, 1.0, v134
	v_fma_f32 v136, -v41, v135, 1.0
	v_fmac_f32_e32 v135, v136, v134
	v_fma_f32 v42, -v41, v135, 1.0
	v_fma_f32 v53, v106, v108, v53
	v_fma_f32 v54, v115, v113, v54
	v_fmac_f32_e32 v55, v100, v102
	v_fma_f32 v42, v42, v134, v135
	v_log_f32_e32 v52, v52
	v_log_f32_e32 v53, v53
	v_log_f32_e32 v54, v54
	v_log_f32_e32 v55, v55
	v_div_fixup_f32 v41, v42, v41, 1.0
	v_sub_f32_e32 v42, 1.0, v43
	v_fmac_f32_e32 v43, v41, v42
	v_log_f32_e32 v133, v43
	s_andn2_b64 vcc, exec, s[20:21]
	s_mov_b64 s[22:23], -1
	ds_write_b128 v70, v[44:47]
	ds_write_b128 v70, v[52:55] offset:16
	ds_write_b128 v70, v[126:129] offset:32
	ds_write_b128 v70, v[130:133] offset:48
	s_waitcnt lgkmcnt(0)
	s_barrier
	s_cbranch_vccnz .LBB0_517
	ds_read2st64_b32 v[44:45], v71 offset0:14 offset1:15
	s_mov_b64 s[22:23], 0
	ds_read2st64_b32 v[126:127], v71 offset0:6 offset1:7
	ds_read2st64_b32 v[132:133], v71 offset0:2 offset1:3
	s_waitcnt lgkmcnt(0)
	v_add_f32_e32 v129, 0, v45
	v_add_f32_e32 v130, v129, v44
	ds_read2st64_b32 v[44:45], v71 offset0:12 offset1:13
	s_waitcnt lgkmcnt(0)
	v_add_f32_e32 v47, v130, v45
	v_add_f32_e32 v52, v47, v44
	ds_read2st64_b32 v[44:45], v71 offset0:10 offset1:11
	s_waitcnt lgkmcnt(0)
	v_add_f32_e32 v53, v52, v45
	v_add_f32_e32 v54, v53, v44
	ds_read2st64_b32 v[44:45], v71 offset0:8 offset1:9
	s_waitcnt lgkmcnt(0)
	v_add_f32_e32 v43, v54, v45
	v_add_f32_e32 v44, v43, v44
	v_add_f32_e32 v45, v44, v127
	v_add_f32_e32 v46, v45, v126
	ds_read2st64_b32 v[126:127], v71 offset0:4 offset1:5
	s_waitcnt lgkmcnt(0)
	v_add_f32_e32 v55, v46, v127
	v_add_f32_e32 v126, v55, v126
	v_add_f32_e32 v127, v126, v133
	v_add_f32_e32 v128, v127, v132
	ds_read2st64_b32 v[132:133], v71 offset1:1
	s_waitcnt lgkmcnt(0)
	v_add_f32_e32 v131, v128, v133
	v_add_f32_e32 v132, v131, v132

; DI size_t kblk(int row, int col, int nrows) { return ((size_t)(col >> 5) * nrows + row) * 32 + (col & 31); }
; DI float bf2f(bf16_t v) { return __uint_as_float(((unsigned)v) << 16); }
; DI unsigned pk2(float a, float b) { hwf32x2 f = {a, b}; hwbf16x2 r = __builtin_convertvector(f, hwbf16x2); return __builtin_bit_cast(unsigned, r); }
; DI float siluf_(float z) { return z / (1.f + __expf(-z)); }
; DI int crow(int reg, int h) { return (reg & 3) + 8 * (reg >> 2) + 4 * h; }
; template <int MODE>
; DI void attn_mfma(const Params& p, int l, int b, int hd, int qb, unsigned char* smem) {
;     ...
;     if (mp == 0) {
;       const float i0 = 1.f / ltot;
;       float ss = 0.f;
; #pragma unroll
;       for (int vt = 0; vt < 2; ++vt)
; #pragma unroll
;         for (int i = 0; i < 16; ++i) { const float o = O[vt][i] * i0 - sO[ql * 65 + vt * 32 + crow(i, h2)]; O[vt][i] = o; ss += o * o; }
;       ss += __shfl_xor(ss, 32);
;       const float rstd = rsqrtf(ss * (1.f / 64.f) + EPS) * (1.f - lam_init);
; #pragma unroll
;       for (int vt = 0; vt < 2; ++vt)
; #pragma unroll
;         for (int g4 = 0; g4 < 4; ++g4) {
;           const int v0 = vt * 32 + 8 * g4 + 4 * h2;
;           const ushort4 gt = *(const ushort4*)(P + qrow * PW + GATE + hd * 64 + v0);
;           const float4 gg = *(const float4*)(p.diff_g + l * 64 + v0);
;           uint2 o;
;           o.x = pk2(O[vt][4 * g4 + 0] * rstd * gg.x * siluf_(bf2f(gt.x)), O[vt][4 * g4 + 1] * rstd * gg.y * siluf_(bf2f(gt.y)));
;           o.y = pk2(O[vt][4 * g4 + 2] * rstd * gg.z * siluf_(bf2f(gt.z)), O[vt][4 * g4 + 3] * rstd * gg.w * siluf_(bf2f(gt.w)));
;           *(uint2*)(MIX + kblk((int)qrow, hd * 64 + v0, ROWS)) = o;
;         }
.LBB0_588:
	s_or_b64 exec, exec, s[0:1]
	s_movk_i32 s0, 0x80
	v_cmp_gt_u32_e32 vcc, s0, v196
	s_waitcnt lgkmcnt(0)
	s_barrier
	s_and_saveexec_b64 s[0:1], vcc
	s_xor_b64 s[0:1], exec, s[0:1]
	s_cbranch_execz .LBB0_590
	s_waitcnt vmcnt(0)
	v_rcp_f32_e32 v33, v160
	s_add_u32 s4, s40, 0x1dc6000
	s_addc_u32 s5, s41, 0
	s_lshl_b32 s2, s7, 1
	v_fma_f32 v34, -v160, v33, 1.0
	v_fmac_f32_e32 v33, v34, v33
	v_mul_f32_e32 v35, 1.0, v33
	v_fma_f32 v36, -v160, v35, 1.0
	v_fmac_f32_e32 v35, v36, v33
	v_fma_f32 v32, -v160, v35, 1.0
	v_fma_f32 v32, v32, v33, v35
	v_div_fixup_f32 v44, v32, v160, 1.0
	ds_read2_b32 v[32:33], v197 offset0:56 offset1:57
	s_mul_i32 s6, s6, 0x9000
	v_add_lshl_u32 v160, v165, s6, 6
	v_mov_b32_e32 v165, v161
	s_mov_b64 s[6:7], 0x1a20
	s_waitcnt lgkmcnt(0)
	v_pk_fma_f32 v[34:35], v[12:13], v[44:45], v[32:33] op_sel_hi:[1,0,1] neg_lo:[0,0,1] neg_hi:[0,0,1]
	ds_read2_b32 v[12:13], v197 offset0:58 offset1:59
	ds_read2_b32 v[82:83], v197 offset0:48 offset1:49
	ds_read2_b32 v[48:49], v197 offset1:1
	v_readlane_b32 s8, v254, 27
	v_readlane_b32 s9, v254, 28
	s_waitcnt lgkmcnt(2)
	v_pk_fma_f32 v[32:33], v[14:15], v[44:45], v[12:13] op_sel_hi:[1,0,1] neg_lo:[0,0,1] neg_hi:[0,0,1]
	ds_read2_b32 v[14:15], v197 offset0:2 offset1:3
	v_lshl_add_u64 v[12:13], v[166:167], 0, s[2:3]
	v_lshl_add_u64 v[12:13], v[12:13], 0, v[164:165]
	v_lshl_add_u64 v[36:37], v[12:13], 0, s[6:7]
	global_load_dwordx2 v[204:205], v[36:37], off
	global_load_dwordx2 v[206:207], v[36:37], off offset:16
	global_load_dwordx2 v[208:209], v[36:37], off offset:32
	global_load_dwordx2 v[210:211], v[36:37], off offset:48
	global_load_dwordx2 v[212:213], v[36:37], off offset:64
	global_load_dwordx2 v[214:215], v[36:37], off offset:80
	global_load_dwordx2 v[216:217], v[36:37], off offset:96
	global_load_dwordx2 v[218:219], v[36:37], off offset:112
	global_load_dwordx4 v[220:223], v171, s[8:9]
	global_load_dwordx4 v[224:227], v171, s[8:9] offset:32
	global_load_dwordx4 v[228:231], v171, s[8:9] offset:64
	global_load_dwordx4 v[232:235], v171, s[8:9] offset:96
	global_load_dwordx4 v[236:239], v171, s[8:9] offset:128
	global_load_dwordx4 v[240:243], v171, s[8:9] offset:160
	global_load_dwordx4 v[244:247], v171, s[8:9] offset:192
	global_load_dwordx4 v[248:251], v171, s[8:9] offset:224
	v_add_co_u32_e32 v12, vcc, s16, v12
	s_waitcnt lgkmcnt(0)
	v_pk_fma_f32 v[46:47], v[18:19], v[44:45], v[14:15] op_sel_hi:[1,0,1] neg_lo:[0,0,1] neg_hi:[0,0,1]
	v_addc_co_u32_e32 v13, vcc, 0, v13, vcc
	s_nop 0
	v_pk_fma_f32 v[48:49], v[16:17], v[44:45], v[48:49] op_sel_hi:[1,0,1] neg_lo:[0,0,1] neg_hi:[0,0,1]
	s_nop 0
	v_pk_mul_f32 v[56:57], v[48:49], v[48:49]
	v_pk_mul_f32 v[52:53], v[46:47], v[46:47]
	v_add_f32_e32 v56, v56, v57
	v_add_f32_e32 v52, v56, v52
	v_add_f32_e32 v52, v52, v53
	v_lshl_add_u64 v[38:39], s[4:5], 0, v[160:161]
	v_add_u32_e32 v160, 0x120000, v160
	v_pk_mul_f32 v[40:41], v[34:35], v[34:35]
	v_pk_mul_f32 v[42:43], v[32:33], v[32:33]
	v_lshl_add_u64 v[38:39], v[38:39], 0, v[164:165]
	s_waitcnt vmcnt(0) lgkmcnt(0)
	v_mov_b32_e32 v18, v204
	v_mov_b32_e32 v19, v205
	v_mov_b32_e32 v12, v220
	v_mov_b32_e32 v13, v221
	v_mov_b32_e32 v14, v222
	v_mov_b32_e32 v15, v223
	v_and_b32_e32 v45, 0xffff0000, v18
	v_lshlrev_b32_e32 v18, 16, v18
	v_mul_f32_e32 v16, 0xbfb8aa3b, v18
	v_mul_f32_e32 v17, 0xbfb8aa3b, v45
	v_exp_f32_e32 v16, v16
	v_exp_f32_e32 v17, v17
	s_nop 0
	v_pk_add_f32 v[16:17], v[16:17], 1.0 op_sel_hi:[1,0]
	s_nop 0
	v_rcp_f32_e32 v51, v17
	s_nop 0
	v_fma_f32 v54, -v17, v51, 1.0
	v_fmac_f32_e32 v51, v54, v51
	v_mul_f32_e32 v55, v45, v51
	v_fma_f32 v58, -v17, v55, v45
	v_fmac_f32_e32 v55, v58, v51
	v_fma_f32 v50, -v17, v55, v45
	v_fma_f32 v50, v50, v51, v55
	v_div_fixup_f32 v51, v50, v17, v45
	v_rcp_f32_e32 v45, v16
	s_nop 0
	v_fma_f32 v50, -v16, v45, 1.0
	v_fmac_f32_e32 v45, v50, v45
	v_mul_f32_e32 v54, v18, v45
	v_fma_f32 v55, -v16, v54, v18
	v_fmac_f32_e32 v54, v55, v45
	v_fma_f32 v17, -v16, v54, v18
	v_fma_f32 v17, v17, v45, v54
	v_div_fixup_f32 v50, v17, v16, v18
	v_and_b32_e32 v18, 0xffff0000, v19
	v_lshlrev_b32_e32 v19, 16, v19
	v_mul_f32_e32 v16, 0xbfb8aa3b, v19
	v_mul_f32_e32 v17, 0xbfb8aa3b, v18
	v_exp_f32_e32 v16, v16
	v_exp_f32_e32 v17, v17
	s_nop 0
	v_pk_add_f32 v[16:17], v[16:17], 1.0 op_sel_hi:[1,0]
	s_nop 0
	v_rcp_f32_e32 v54, v17
	s_nop 0
	v_fma_f32 v55, -v17, v54, 1.0
	v_fmac_f32_e32 v54, v55, v54
	v_mul_f32_e32 v58, v18, v54
	v_fma_f32 v59, -v17, v58, v18
	v_fmac_f32_e32 v58, v59, v54
	v_fma_f32 v45, -v17, v58, v18
	v_fma_f32 v45, v45, v54, v58
	v_div_fixup_f32 v55, v45, v17, v18
	v_rcp_f32_e32 v18, v16
	s_nop 0
	v_fma_f32 v45, -v16, v18, 1.0
	v_fmac_f32_e32 v18, v45, v18
	v_mul_f32_e32 v54, v19, v18
	v_fma_f32 v58, -v16, v54, v19
	v_fmac_f32_e32 v54, v58, v18
	v_fma_f32 v17, -v16, v54, v19
	v_fma_f32 v17, v17, v18, v54
	v_div_fixup_f32 v54, v17, v16, v19
	ds_read2_b32 v[16:17], v197 offset0:10 offset1:11
	ds_read2_b32 v[18:19], v197 offset0:8 offset1:9
	s_waitcnt lgkmcnt(1)
	v_pk_fma_f32 v[60:61], v[22:23], v[44:45], v[16:17] op_sel_hi:[1,0,1] neg_lo:[0,0,1] neg_hi:[0,0,1]
	s_nop 0
	s_waitcnt lgkmcnt(0)
; DI size_t kblk(int row, int col, int nrows) { return ((size_t)(col >> 5) * nrows + row) * 32 + (col & 31); }
; DI float bf2f(bf16_t v) { return __uint_as_float(((unsigned)v) << 16); }
; DI unsigned pk2(float a, float b) { hwf32x2 f = {a, b}; hwbf16x2 r = __builtin_convertvector(f, hwbf16x2); return __builtin_bit_cast(unsigned, r); }
; DI float siluf_(float z) { return z / (1.f + __expf(-z)); }
; DI int crow(int reg, int h) { return (reg & 3) + 8 * (reg >> 2) + 4 * h; }
; template <int MODE>
; DI void attn_mfma(const Params& p, int l, int b, int hd, int qb, unsigned char* smem) {
;     ...
;     if (mp == 0) {
;       const float i0 = 1.f / ltot;
;       float ss = 0.f;
; #pragma unroll
;       for (int vt = 0; vt < 2; ++vt)
; #pragma unroll
;         for (int i = 0; i < 16; ++i) { const float o = O[vt][i] * i0 - sO[ql * 65 + vt * 32 + crow(i, h2)]; O[vt][i] = o; ss += o * o; }
;       ss += __shfl_xor(ss, 32);
;       const float rstd = rsqrtf(ss * (1.f / 64.f) + EPS) * (1.f - lam_init);
; #pragma unroll
;       for (int vt = 0; vt < 2; ++vt)
; #pragma unroll
;         for (int g4 = 0; g4 < 4; ++g4) {
;           const int v0 = vt * 32 + 8 * g4 + 4 * h2;
;           const ushort4 gt = *(const ushort4*)(P + qrow * PW + GATE + hd * 64 + v0);
;           const float4 gg = *(const float4*)(p.diff_g + l * 64 + v0);
;           uint2 o;
;           o.x = pk2(O[vt][4 * g4 + 0] * rstd * gg.x * siluf_(bf2f(gt.x)), O[vt][4 * g4 + 1] * rstd * gg.y * siluf_(bf2f(gt.y)));
;           o.y = pk2(O[vt][4 * g4 + 2] * rstd * gg.z * siluf_(bf2f(gt.z)), O[vt][4 * g4 + 3] * rstd * gg.w * siluf_(bf2f(gt.w)));
;           *(uint2*)(MIX + kblk((int)qrow, hd * 64 + v0, ROWS)) = o;
;         }
	v_pk_fma_f32 v[62:63], v[20:21], v[44:45], v[18:19] op_sel_hi:[1,0,1] neg_lo:[0,0,1] neg_hi:[0,0,1]
	v_pk_mul_f32 v[68:69], v[60:61], v[60:61]
	v_pk_mul_f32 v[70:71], v[62:63], v[62:63]
	s_nop 0
	v_mov_b32_e32 v16, v206
	v_mov_b32_e32 v17, v207
	v_and_b32_e32 v20, 0xffff0000, v16
	v_lshlrev_b32_e32 v16, 16, v16
	v_mul_f32_e32 v18, 0xbfb8aa3b, v16
	v_mul_f32_e32 v19, 0xbfb8aa3b, v20
	v_exp_f32_e32 v18, v18
	v_exp_f32_e32 v19, v19
	v_add_f32_e32 v52, v52, v70
	v_add_f32_e32 v52, v52, v71
	v_add_f32_e32 v52, v52, v68
	v_pk_add_f32 v[18:19], v[18:19], 1.0 op_sel_hi:[1,0]
	v_add_f32_e32 v52, v52, v69
	v_rcp_f32_e32 v22, v19
	s_nop 0
	v_fma_f32 v23, -v19, v22, 1.0
	v_fmac_f32_e32 v22, v23, v22
	v_mul_f32_e32 v45, v20, v22
	v_fma_f32 v58, -v19, v45, v20
	v_fmac_f32_e32 v45, v58, v22
	v_fma_f32 v21, -v19, v45, v20
	v_fma_f32 v21, v21, v22, v45
	v_div_fixup_f32 v65, v21, v19, v20
	v_rcp_f32_e32 v20, v18
	s_nop 0
	v_fma_f32 v21, -v18, v20, 1.0
	v_fmac_f32_e32 v20, v21, v20
	v_mul_f32_e32 v22, v16, v20
	v_fma_f32 v23, -v18, v22, v16
	v_fmac_f32_e32 v22, v23, v20
	v_fma_f32 v19, -v18, v22, v16
	v_fma_f32 v19, v19, v20, v22
	v_div_fixup_f32 v64, v19, v18, v16
	v_and_b32_e32 v18, 0xffff0000, v17
	v_lshlrev_b32_e32 v19, 16, v17
	v_mul_f32_e32 v16, 0xbfb8aa3b, v19
	v_mul_f32_e32 v17, 0xbfb8aa3b, v18
	v_exp_f32_e32 v16, v16
	v_exp_f32_e32 v17, v17
	s_nop 0
	v_pk_add_f32 v[16:17], v[16:17], 1.0 op_sel_hi:[1,0]
	s_nop 0
	v_rcp_f32_e32 v21, v17
	s_nop 0
	v_fma_f32 v22, -v17, v21, 1.0
	v_fmac_f32_e32 v21, v22, v21
	v_mul_f32_e32 v23, v18, v21
	v_fma_f32 v45, -v17, v23, v18
	v_fmac_f32_e32 v23, v45, v21
	v_fma_f32 v20, -v17, v23, v18
	v_fma_f32 v20, v20, v21, v23
	v_div_fixup_f32 v67, v20, v17, v18
	v_rcp_f32_e32 v18, v16
	v_pk_fma_f32 v[8:9], v[8:9], v[44:45], v[82:83] op_sel_hi:[1,0,1] neg_lo:[0,0,1] neg_hi:[0,0,1]
	v_fma_f32 v20, -v16, v18, 1.0
	v_fmac_f32_e32 v18, v20, v18
	v_mul_f32_e32 v21, v19, v18
	v_fma_f32 v22, -v16, v21, v19
	v_fmac_f32_e32 v21, v22, v18
	v_fma_f32 v17, -v16, v21, v19
	v_fma_f32 v17, v17, v18, v21
	v_div_fixup_f32 v66, v17, v16, v19
	ds_read2_b32 v[16:17], v197 offset0:18 offset1:19
	ds_read2_b32 v[18:19], v197 offset0:34 offset1:35
	s_waitcnt lgkmcnt(1)
	v_pk_fma_f32 v[26:27], v[26:27], v[44:45], v[16:17] op_sel_hi:[1,0,1] neg_lo:[0,0,1] neg_hi:[0,0,1]
	ds_read2_b32 v[16:17], v197 offset0:16 offset1:17
	s_waitcnt lgkmcnt(1)
	v_pk_fma_f32 v[18:19], v[2:3], v[44:45], v[18:19] op_sel_hi:[1,0,1] neg_lo:[0,0,1] neg_hi:[0,0,1]
	ds_read2_b32 v[2:3], v197 offset0:32 offset1:33
	v_pk_mul_f32 v[72:73], v[26:27], v[26:27]
	s_waitcnt lgkmcnt(1)
	v_pk_fma_f32 v[58:59], v[24:25], v[44:45], v[16:17] op_sel_hi:[1,0,1] neg_lo:[0,0,1] neg_hi:[0,0,1]
	ds_read2_b32 v[16:17], v197 offset0:26 offset1:27
	s_waitcnt lgkmcnt(1)
	v_pk_fma_f32 v[20:21], v[0:1], v[44:45], v[2:3] op_sel_hi:[1,0,1] neg_lo:[0,0,1] neg_hi:[0,0,1]
	ds_read2_b32 v[2:3], v197 offset0:42 offset1:43
	v_pk_mul_f32 v[74:75], v[58:59], v[58:59]
	v_pk_mul_f32 v[80:81], v[20:21], v[20:21]
	s_waitcnt lgkmcnt(1)
	v_pk_fma_f32 v[22:23], v[30:31], v[44:45], v[16:17] op_sel_hi:[1,0,1] neg_lo:[0,0,1] neg_hi:[0,0,1]
	ds_read2_b32 v[16:17], v197 offset0:24 offset1:25
	v_add_f32_e32 v52, v52, v74
	v_add_f32_e32 v52, v52, v75
	s_waitcnt lgkmcnt(1)
	v_pk_fma_f32 v[6:7], v[6:7], v[44:45], v[2:3] op_sel_hi:[1,0,1] neg_lo:[0,0,1] neg_hi:[0,0,1]
	ds_read2_b32 v[2:3], v197 offset0:40 offset1:41
	s_waitcnt lgkmcnt(1)
	v_pk_fma_f32 v[24:25], v[28:29], v[44:45], v[16:17] op_sel_hi:[1,0,1] neg_lo:[0,0,1] neg_hi:[0,0,1]
	v_add_f32_e32 v52, v52, v72
	v_pk_mul_f32 v[76:77], v[24:25], v[24:25]
	v_add_f32_e32 v52, v52, v73
	v_add_f32_e32 v52, v52, v76
	v_pk_mul_f32 v[30:31], v[22:23], v[22:23]
	v_add_f32_e32 v52, v52, v77
	v_add_f32_e32 v30, v52, v30
	v_add_f32_e32 v30, v30, v31
	v_add_f32_e32 v30, v30, v80
	v_lshl_add_u64 v[16:17], s[4:5], 0, v[160:161]
	v_pk_mul_f32 v[28:29], v[18:19], v[18:19]
	v_add_f32_e32 v30, v30, v81
	v_lshl_add_u64 v[0:1], v[16:17], 0, v[164:165]
	s_waitcnt lgkmcnt(0)
	v_pk_fma_f32 v[16:17], v[4:5], v[44:45], v[2:3] op_sel_hi:[1,0,1] neg_lo:[0,0,1] neg_hi:[0,0,1]
	ds_read2_b32 v[2:3], v197 offset0:50 offset1:51
	v_add_f32_e32 v28, v30, v28
	v_pk_mul_f32 v[4:5], v[16:17], v[16:17]
	v_add_f32_e32 v28, v28, v29
	v_add_f32_e32 v4, v28, v4
	v_pk_mul_f32 v[78:79], v[6:7], v[6:7]
	v_add_f32_e32 v4, v4, v5
	v_add_f32_e32 v4, v4, v78
	s_waitcnt lgkmcnt(0)
	v_pk_fma_f32 v[2:3], v[10:11], v[44:45], v[2:3] op_sel_hi:[1,0,1] neg_lo:[0,0,1] neg_hi:[0,0,1]
	v_pk_mul_f32 v[44:45], v[8:9], v[8:9]
	v_add_f32_e32 v4, v4, v79
	v_add_f32_e32 v4, v4, v44
	v_pk_mul_f32 v[10:11], v[2:3], v[2:3]
	v_add_f32_e32 v4, v4, v45
	v_add_f32_e32 v4, v4, v10
	v_add_f32_e32 v4, v4, v11
	v_add_f32_e32 v4, v4, v40
	v_add_f32_e32 v4, v4, v41
	v_add_f32_e32 v4, v4, v42
	v_add_f32_e32 v4, v4, v43
	ds_bpermute_b32 v5, v170, v4
	s_waitcnt lgkmcnt(0)
	v_add_f32_e32 v4, v4, v5
	v_fmamk_f32 v4, v4, 0x3c800000, v162
	v_cmp_gt_f32_e32 vcc, s38, v4
	v_mul_f32_e32 v5, 0x4b800000, v4
	s_nop 0
	v_cndmask_b32_e32 v4, v4, v5, vcc
	v_rsq_f32_e32 v4, v4
	s_nop 0
	v_mul_f32_e32 v5, 0x45800000, v4
	v_cndmask_b32_e32 v4, v4, v5, vcc
	v_mul_f32_e32 v4, v169, v4
	v_pk_mul_f32 v[10:11], v[48:49], v[4:5] op_sel_hi:[1,0]
	s_nop 0
	v_pk_mul_f32 v[10:11], v[12:13], v[10:11]
	v_pk_mul_f32 v[12:13], v[46:47], v[4:5] op_sel_hi:[1,0]
	v_pk_mul_f32 v[10:11], v[50:51], v[10:11]
	v_pk_mul_f32 v[12:13], v[14:15], v[12:13]
	v_cvt_pk_bf16_f32 v10, v10, v11
	v_pk_mul_f32 v[12:13], v[54:55], v[12:13]
	v_pk_mul_f32 v[14:15], v[62:63], v[4:5] op_sel_hi:[1,0]
	v_cvt_pk_bf16_f32 v11, v12, v13
	global_store_dwordx2 v[38:39], v[10:11], off
	s_nop 0
	s_nop 0
	v_mov_b32_e32 v10, v224
	v_mov_b32_e32 v11, v225
	v_mov_b32_e32 v12, v226
	v_mov_b32_e32 v13, v227
	v_pk_mul_f32 v[10:11], v[14:15], v[10:11]
	v_pk_mul_f32 v[14:15], v[60:61], v[4:5] op_sel_hi:[1,0]
	v_pk_mul_f32 v[10:11], v[10:11], v[64:65]
	v_pk_mul_f32 v[12:13], v[14:15], v[12:13]
	v_cvt_pk_bf16_f32 v10, v10, v11
	v_pk_mul_f32 v[12:13], v[12:13], v[66:67]
	s_nop 0
	v_cvt_pk_bf16_f32 v11, v12, v13
	global_store_dwordx2 v[38:39], v[10:11], off offset:16
	s_nop 0
	s_nop 0
	s_nop 0
	s_waitcnt lgkmcnt(0)
; DI size_t kblk(int row, int col, int nrows) { return ((size_t)(col >> 5) * nrows + row) * 32 + (col & 31); }
; DI float bf2f(bf16_t v) { return __uint_as_float(((unsigned)v) << 16); }
; DI unsigned pk2(float a, float b) { hwf32x2 f = {a, b}; hwbf16x2 r = __builtin_convertvector(f, hwbf16x2); return __builtin_bit_cast(unsigned, r); }
; DI float siluf_(float z) { return z / (1.f + __expf(-z)); }
; template <int MODE>
; DI void attn_mfma(const Params& p, int l, int b, int hd, int qb, unsigned char* smem) {
;     ...
; #pragma unroll
;       for (int vt = 0; vt < 2; ++vt)
; #pragma unroll
;         for (int g4 = 0; g4 < 4; ++g4) {
;           const int v0 = vt * 32 + 8 * g4 + 4 * h2;
;           const ushort4 gt = *(const ushort4*)(P + qrow * PW + GATE + hd * 64 + v0);
;           const float4 gg = *(const float4*)(p.diff_g + l * 64 + v0);
;           uint2 o;
;           o.x = pk2(O[vt][4 * g4 + 0] * rstd * gg.x * siluf_(bf2f(gt.x)), O[vt][4 * g4 + 1] * rstd * gg.y * siluf_(bf2f(gt.y)));
;           o.y = pk2(O[vt][4 * g4 + 2] * rstd * gg.z * siluf_(bf2f(gt.z)), O[vt][4 * g4 + 3] * rstd * gg.w * siluf_(bf2f(gt.w)));
;           *(uint2*)(MIX + kblk((int)qrow, hd * 64 + v0, ROWS)) = o;
;         }
	v_mov_b32_e32 v14, v208
	v_mov_b32_e32 v15, v209
	v_mov_b32_e32 v10, v228
	v_mov_b32_e32 v11, v229
	v_mov_b32_e32 v12, v230
	v_mov_b32_e32 v13, v231
	v_and_b32_e32 v5, 0xffff0000, v14
	v_lshlrev_b32_e32 v14, 16, v14
	v_mul_f32_e32 v28, 0xbfb8aa3b, v14
	v_mul_f32_e32 v29, 0xbfb8aa3b, v5
	v_exp_f32_e32 v28, v28
	v_exp_f32_e32 v29, v29
	v_pk_mul_f32 v[30:31], v[58:59], v[4:5] op_sel_hi:[1,0]
	v_pk_add_f32 v[28:29], v[28:29], 1.0 op_sel_hi:[1,0]
	v_pk_mul_f32 v[10:11], v[30:31], v[10:11]
	v_rcp_f32_e32 v31, v29
	s_nop 0
	v_fma_f32 v40, -v29, v31, 1.0
	v_fmac_f32_e32 v31, v40, v31
	v_mul_f32_e32 v41, v5, v31
	v_fma_f32 v42, -v29, v41, v5
	v_fmac_f32_e32 v41, v42, v31
	v_fma_f32 v30, -v29, v41, v5
	v_fma_f32 v30, v30, v31, v41
	v_div_fixup_f32 v29, v30, v29, v5
	v_rcp_f32_e32 v30, v28
	s_nop 0
	v_fma_f32 v31, -v28, v30, 1.0
	v_fmac_f32_e32 v30, v31, v30
	v_mul_f32_e32 v40, v14, v30
	v_fma_f32 v41, -v28, v40, v14
	v_fmac_f32_e32 v40, v41, v30
	v_fma_f32 v5, -v28, v40, v14
	v_fma_f32 v5, v5, v30, v40
	v_div_fixup_f32 v28, v5, v28, v14
	v_pk_mul_f32 v[10:11], v[10:11], v[28:29]
	v_and_b32_e32 v5, 0xffff0000, v15
	v_cvt_pk_bf16_f32 v10, v10, v11
	v_lshlrev_b32_e32 v11, 16, v15
	v_mul_f32_e32 v14, 0xbfb8aa3b, v11
	v_mul_f32_e32 v15, 0xbfb8aa3b, v5
	v_exp_f32_e32 v14, v14
	v_exp_f32_e32 v15, v15
	v_pk_mul_f32 v[26:27], v[26:27], v[4:5] op_sel_hi:[1,0]
	v_pk_add_f32 v[14:15], v[14:15], 1.0 op_sel_hi:[1,0]
	v_pk_mul_f32 v[12:13], v[26:27], v[12:13]
	v_rcp_f32_e32 v27, v15
	s_nop 0
	v_fma_f32 v28, -v15, v27, 1.0
	v_fmac_f32_e32 v27, v28, v27
	v_mul_f32_e32 v29, v5, v27
	v_fma_f32 v30, -v15, v29, v5
	v_fmac_f32_e32 v29, v30, v27
	v_fma_f32 v26, -v15, v29, v5
	v_fma_f32 v26, v26, v27, v29
	v_div_fixup_f32 v15, v26, v15, v5
	v_rcp_f32_e32 v26, v14
	s_nop 0
	v_fma_f32 v27, -v14, v26, 1.0
	v_fmac_f32_e32 v26, v27, v26
	v_mul_f32_e32 v28, v11, v26
	v_fma_f32 v29, -v14, v28, v11
	v_fmac_f32_e32 v28, v29, v26
	v_fma_f32 v5, -v14, v28, v11
	v_fma_f32 v5, v5, v26, v28
	v_div_fixup_f32 v14, v5, v14, v11
	v_pk_mul_f32 v[12:13], v[12:13], v[14:15]
	s_nop 0
	v_cvt_pk_bf16_f32 v11, v12, v13
	global_store_dwordx2 v[38:39], v[10:11], off offset:32
	s_nop 0
	s_nop 0
	s_nop 0
	s_waitcnt lgkmcnt(0)
	v_mov_b32_e32 v14, v210
	v_mov_b32_e32 v15, v211
	v_mov_b32_e32 v10, v232
	v_mov_b32_e32 v11, v233
	v_mov_b32_e32 v12, v234
	v_mov_b32_e32 v13, v235
	v_and_b32_e32 v5, 0xffff0000, v14
	v_lshlrev_b32_e32 v14, 16, v14
	v_pk_mul_f32 v[24:25], v[24:25], v[4:5] op_sel_hi:[1,0]
	v_mul_f32_e32 v26, 0xbfb8aa3b, v14
	v_pk_mul_f32 v[10:11], v[24:25], v[10:11]
	v_mul_f32_e32 v24, 0xbfb8aa3b, v5
	v_exp_f32_e32 v26, v26
	v_exp_f32_e32 v27, v24
	s_nop 0
	v_pk_add_f32 v[24:25], v[26:27], 1.0 op_sel_hi:[1,0]
	s_nop 0
	v_rcp_f32_e32 v27, v25
	s_nop 0
	v_fma_f32 v28, -v25, v27, 1.0
	v_fmac_f32_e32 v27, v28, v27
	v_mul_f32_e32 v29, v5, v27
	v_fma_f32 v30, -v25, v29, v5
	v_fmac_f32_e32 v29, v30, v27
	v_fma_f32 v26, -v25, v29, v5
	v_fma_f32 v26, v26, v27, v29
	v_div_fixup_f32 v25, v26, v25, v5
	v_rcp_f32_e32 v26, v24
	s_nop 0
	v_fma_f32 v27, -v24, v26, 1.0
	v_fmac_f32_e32 v26, v27, v26
	v_mul_f32_e32 v28, v14, v26
	v_fma_f32 v29, -v24, v28, v14
	v_fmac_f32_e32 v28, v29, v26
	v_fma_f32 v5, -v24, v28, v14
	v_fma_f32 v5, v5, v26, v28
	v_div_fixup_f32 v24, v5, v24, v14
	v_pk_mul_f32 v[10:11], v[10:11], v[24:25]
	v_and_b32_e32 v5, 0xffff0000, v15
	v_cvt_pk_bf16_f32 v10, v10, v11
	v_lshlrev_b32_e32 v11, 16, v15
	v_mul_f32_e32 v14, 0xbfb8aa3b, v11
	v_mul_f32_e32 v15, 0xbfb8aa3b, v5
	v_exp_f32_e32 v14, v14
	v_exp_f32_e32 v15, v15
	v_pk_mul_f32 v[22:23], v[22:23], v[4:5] op_sel_hi:[1,0]
	v_pk_add_f32 v[14:15], v[14:15], 1.0 op_sel_hi:[1,0]
	v_pk_mul_f32 v[12:13], v[22:23], v[12:13]
	v_rcp_f32_e32 v23, v15
	s_nop 0
	v_fma_f32 v24, -v15, v23, 1.0
	v_fmac_f32_e32 v23, v24, v23
	v_mul_f32_e32 v25, v5, v23
	v_fma_f32 v26, -v15, v25, v5
	v_fmac_f32_e32 v25, v26, v23
	v_fma_f32 v22, -v15, v25, v5
	v_fma_f32 v22, v22, v23, v25
	v_div_fixup_f32 v15, v22, v15, v5
	v_rcp_f32_e32 v22, v14
	s_nop 0
	v_fma_f32 v23, -v14, v22, 1.0
	v_fmac_f32_e32 v22, v23, v22
	v_mul_f32_e32 v24, v11, v22
	v_fma_f32 v25, -v14, v24, v11
	v_fmac_f32_e32 v24, v25, v22
	v_fma_f32 v5, -v14, v24, v11
	v_fma_f32 v5, v5, v22, v24
	v_div_fixup_f32 v14, v5, v14, v11
	v_pk_mul_f32 v[12:13], v[12:13], v[14:15]
	s_nop 0
	v_cvt_pk_bf16_f32 v11, v12, v13
	global_store_dwordx2 v[38:39], v[10:11], off offset:48
	s_nop 0
	s_nop 0
	s_nop 0
	s_waitcnt lgkmcnt(0)
	v_mov_b32_e32 v10, v212
	v_mov_b32_e32 v11, v213
	v_mov_b32_e32 v12, v236
	v_mov_b32_e32 v13, v237
	v_mov_b32_e32 v14, v238
	v_mov_b32_e32 v15, v239
	v_and_b32_e32 v5, 0xffff0000, v10
	v_lshlrev_b32_e32 v10, 16, v10
	v_pk_mul_f32 v[20:21], v[20:21], v[4:5] op_sel_hi:[1,0]
	v_mul_f32_e32 v22, 0xbfb8aa3b, v10
	v_pk_mul_f32 v[12:13], v[20:21], v[12:13]
	v_mul_f32_e32 v20, 0xbfb8aa3b, v5
	v_exp_f32_e32 v22, v22
	v_exp_f32_e32 v23, v20
	s_nop 0
	v_pk_add_f32 v[20:21], v[22:23], 1.0 op_sel_hi:[1,0]
	s_nop 0
	v_rcp_f32_e32 v23, v21
	s_nop 0
	v_fma_f32 v24, -v21, v23, 1.0
	v_fmac_f32_e32 v23, v24, v23
	v_mul_f32_e32 v25, v5, v23
	v_fma_f32 v26, -v21, v25, v5
	v_fmac_f32_e32 v25, v26, v23
	v_fma_f32 v22, -v21, v25, v5
	v_fma_f32 v22, v22, v23, v25
	v_div_fixup_f32 v21, v22, v21, v5
	v_rcp_f32_e32 v22, v20
	s_nop 0
	v_fma_f32 v23, -v20, v22, 1.0
	v_fmac_f32_e32 v22, v23, v22
	v_mul_f32_e32 v24, v10, v22
	v_fma_f32 v25, -v20, v24, v10
	v_fmac_f32_e32 v24, v25, v22
	v_fma_f32 v5, -v20, v24, v10
	v_fma_f32 v5, v5, v22, v24
	v_div_fixup_f32 v20, v5, v20, v10
	v_pk_mul_f32 v[12:13], v[12:13], v[20:21]
	v_and_b32_e32 v5, 0xffff0000, v11
	v_lshlrev_b32_e32 v11, 16, v11
	v_cvt_pk_bf16_f32 v10, v12, v13
	v_mul_f32_e32 v12, 0xbfb8aa3b, v11
	v_mul_f32_e32 v13, 0xbfb8aa3b, v5
	v_exp_f32_e32 v12, v12
	v_exp_f32_e32 v13, v13
	v_pk_mul_f32 v[18:19], v[18:19], v[4:5] op_sel_hi:[1,0]
	v_pk_add_f32 v[12:13], v[12:13], 1.0 op_sel_hi:[1,0]
	v_pk_mul_f32 v[14:15], v[18:19], v[14:15]
	v_rcp_f32_e32 v19, v13
	s_nop 0
	v_fma_f32 v20, -v13, v19, 1.0
	v_fmac_f32_e32 v19, v20, v19
	v_mul_f32_e32 v21, v5, v19
	v_fma_f32 v22, -v13, v21, v5
	v_fmac_f32_e32 v21, v22, v19
	v_fma_f32 v18, -v13, v21, v5
	v_fma_f32 v18, v18, v19, v21
	v_div_fixup_f32 v13, v18, v13, v5
	v_rcp_f32_e32 v18, v12
	s_nop 0
	v_fma_f32 v19, -v12, v18, 1.0
	v_fmac_f32_e32 v18, v19, v18
	v_mul_f32_e32 v20, v11, v18
	v_fma_f32 v21, -v12, v20, v11
	v_fmac_f32_e32 v20, v21, v18
	v_fma_f32 v5, -v12, v20, v11
	v_fma_f32 v5, v5, v18, v20
	v_div_fixup_f32 v12, v5, v12, v11
	v_pk_mul_f32 v[12:13], v[14:15], v[12:13]
	s_nop 0
	v_cvt_pk_bf16_f32 v11, v12, v13
	global_store_dwordx2 v[0:1], v[10:11], off
	s_nop 0
	s_nop 0
	s_nop 0
	s_waitcnt lgkmcnt(0)
; DI size_t kblk(int row, int col, int nrows) { return ((size_t)(col >> 5) * nrows + row) * 32 + (col & 31); }
; DI float bf2f(bf16_t v) { return __uint_as_float(((unsigned)v) << 16); }
; DI unsigned pk2(float a, float b) { hwf32x2 f = {a, b}; hwbf16x2 r = __builtin_convertvector(f, hwbf16x2); return __builtin_bit_cast(unsigned, r); }
; DI float siluf_(float z) { return z / (1.f + __expf(-z)); }
; template <int MODE>
; DI void attn_mfma(const Params& p, int l, int b, int hd, int qb, unsigned char* smem) {
;     ...
; #pragma unroll
;       for (int vt = 0; vt < 2; ++vt)
; #pragma unroll
;         for (int g4 = 0; g4 < 4; ++g4) {
;           const int v0 = vt * 32 + 8 * g4 + 4 * h2;
;           const ushort4 gt = *(const ushort4*)(P + qrow * PW + GATE + hd * 64 + v0);
;           const float4 gg = *(const float4*)(p.diff_g + l * 64 + v0);
;           uint2 o;
;           o.x = pk2(O[vt][4 * g4 + 0] * rstd * gg.x * siluf_(bf2f(gt.x)), O[vt][4 * g4 + 1] * rstd * gg.y * siluf_(bf2f(gt.y)));
;           o.y = pk2(O[vt][4 * g4 + 2] * rstd * gg.z * siluf_(bf2f(gt.z)), O[vt][4 * g4 + 3] * rstd * gg.w * siluf_(bf2f(gt.w)));
;           *(uint2*)(MIX + kblk((int)qrow, hd * 64 + v0, ROWS)) = o;
;         }
	v_mov_b32_e32 v14, v214
	v_mov_b32_e32 v15, v215
	v_mov_b32_e32 v10, v240
	v_mov_b32_e32 v11, v241
	v_mov_b32_e32 v12, v242
	v_mov_b32_e32 v13, v243
	v_and_b32_e32 v5, 0xffff0000, v14
	v_lshlrev_b32_e32 v14, 16, v14
	v_pk_mul_f32 v[16:17], v[16:17], v[4:5] op_sel_hi:[1,0]
	v_mul_f32_e32 v18, 0xbfb8aa3b, v14
	v_pk_mul_f32 v[10:11], v[16:17], v[10:11]
	v_mul_f32_e32 v16, 0xbfb8aa3b, v5
	v_exp_f32_e32 v18, v18
	v_exp_f32_e32 v19, v16
	s_nop 0
	v_pk_add_f32 v[16:17], v[18:19], 1.0 op_sel_hi:[1,0]
	s_nop 0
	v_rcp_f32_e32 v19, v17
	s_nop 0
	v_fma_f32 v20, -v17, v19, 1.0
	v_fmac_f32_e32 v19, v20, v19
	v_mul_f32_e32 v21, v5, v19
	v_fma_f32 v22, -v17, v21, v5
	v_fmac_f32_e32 v21, v22, v19
	v_fma_f32 v18, -v17, v21, v5
	v_fma_f32 v18, v18, v19, v21
	v_div_fixup_f32 v17, v18, v17, v5
	v_rcp_f32_e32 v18, v16
	s_nop 0
	v_fma_f32 v19, -v16, v18, 1.0
	v_fmac_f32_e32 v18, v19, v18
	v_mul_f32_e32 v20, v14, v18
	v_fma_f32 v21, -v16, v20, v14
	v_fmac_f32_e32 v20, v21, v18
	v_fma_f32 v5, -v16, v20, v14
	v_fma_f32 v5, v5, v18, v20
	v_div_fixup_f32 v16, v5, v16, v14
	v_pk_mul_f32 v[10:11], v[10:11], v[16:17]
	v_and_b32_e32 v5, 0xffff0000, v15
	v_cvt_pk_bf16_f32 v10, v10, v11
	v_lshlrev_b32_e32 v11, 16, v15
	v_pk_mul_f32 v[6:7], v[6:7], v[4:5] op_sel_hi:[1,0]
	v_mul_f32_e32 v14, 0xbfb8aa3b, v11
	v_pk_mul_f32 v[6:7], v[6:7], v[12:13]
	v_mul_f32_e32 v12, 0xbfb8aa3b, v5
	v_exp_f32_e32 v14, v14
	v_exp_f32_e32 v15, v12
	s_nop 0
	v_pk_add_f32 v[12:13], v[14:15], 1.0 op_sel_hi:[1,0]
	s_nop 0
	v_rcp_f32_e32 v15, v13
	s_nop 0
	v_fma_f32 v16, -v13, v15, 1.0
	v_fmac_f32_e32 v15, v16, v15
	v_mul_f32_e32 v17, v5, v15
	v_fma_f32 v18, -v13, v17, v5
	v_fmac_f32_e32 v17, v18, v15
	v_fma_f32 v14, -v13, v17, v5
	v_fma_f32 v14, v14, v15, v17
	v_div_fixup_f32 v13, v14, v13, v5
	v_rcp_f32_e32 v14, v12
	s_nop 0
	v_fma_f32 v15, -v12, v14, 1.0
	v_fmac_f32_e32 v14, v15, v14
	v_mul_f32_e32 v16, v11, v14
	v_fma_f32 v17, -v12, v16, v11
	v_fmac_f32_e32 v16, v17, v14
	v_fma_f32 v5, -v12, v16, v11
	v_fma_f32 v5, v5, v14, v16
	v_div_fixup_f32 v12, v5, v12, v11
	v_pk_mul_f32 v[6:7], v[6:7], v[12:13]
	s_nop 0
	v_cvt_pk_bf16_f32 v11, v6, v7
	global_store_dwordx2 v[0:1], v[10:11], off offset:16
	s_nop 0
	s_nop 0
	s_nop 0
	s_waitcnt lgkmcnt(0)
	v_mov_b32_e32 v6, v216
	v_mov_b32_e32 v7, v217
	v_mov_b32_e32 v10, v244
	v_mov_b32_e32 v11, v245
	v_mov_b32_e32 v12, v246
	v_mov_b32_e32 v13, v247
	v_and_b32_e32 v5, 0xffff0000, v6
	v_lshlrev_b32_e32 v6, 16, v6
	v_pk_mul_f32 v[8:9], v[8:9], v[4:5] op_sel_hi:[1,0]
	v_mul_f32_e32 v14, 0xbfb8aa3b, v6
	v_pk_mul_f32 v[8:9], v[8:9], v[10:11]
	v_mul_f32_e32 v10, 0xbfb8aa3b, v5
	v_exp_f32_e32 v14, v14
	v_exp_f32_e32 v15, v10
	s_nop 0
	v_pk_add_f32 v[10:11], v[14:15], 1.0 op_sel_hi:[1,0]
	s_nop 0
	v_rcp_f32_e32 v15, v11
	s_nop 0
	v_fma_f32 v16, -v11, v15, 1.0
	v_fmac_f32_e32 v15, v16, v15
	v_mul_f32_e32 v17, v5, v15
	v_fma_f32 v18, -v11, v17, v5
	v_fmac_f32_e32 v17, v18, v15
	v_fma_f32 v14, -v11, v17, v5
	v_fma_f32 v14, v14, v15, v17
	v_div_fixup_f32 v11, v14, v11, v5
	v_rcp_f32_e32 v14, v10
	s_nop 0
	v_fma_f32 v15, -v10, v14, 1.0
	v_fmac_f32_e32 v14, v15, v14
	v_mul_f32_e32 v16, v6, v14
	v_fma_f32 v17, -v10, v16, v6
	v_fmac_f32_e32 v16, v17, v14
	v_fma_f32 v5, -v10, v16, v6
	v_fma_f32 v5, v5, v14, v16
	v_div_fixup_f32 v10, v5, v10, v6
	v_pk_mul_f32 v[8:9], v[8:9], v[10:11]
	v_and_b32_e32 v5, 0xffff0000, v7
	v_lshlrev_b32_e32 v7, 16, v7
	v_cvt_pk_bf16_f32 v6, v8, v9
	v_mul_f32_e32 v8, 0xbfb8aa3b, v7
	v_mul_f32_e32 v9, 0xbfb8aa3b, v5
	v_exp_f32_e32 v8, v8
	v_exp_f32_e32 v9, v9
	v_pk_mul_f32 v[2:3], v[2:3], v[4:5] op_sel_hi:[1,0]
	v_pk_add_f32 v[8:9], v[8:9], 1.0 op_sel_hi:[1,0]
	s_nop 0
	v_rcp_f32_e32 v11, v9
	v_pk_mul_f32 v[2:3], v[2:3], v[12:13]
	v_fma_f32 v12, -v9, v11, 1.0
	v_fmac_f32_e32 v11, v12, v11
	v_mul_f32_e32 v13, v5, v11
	v_fma_f32 v14, -v9, v13, v5
	v_fmac_f32_e32 v13, v14, v11
	v_fma_f32 v10, -v9, v13, v5
	v_fma_f32 v10, v10, v11, v13
	v_div_fixup_f32 v9, v10, v9, v5
	v_rcp_f32_e32 v10, v8
	s_nop 0
	v_fma_f32 v11, -v8, v10, 1.0
	v_fmac_f32_e32 v10, v11, v10
	v_mul_f32_e32 v12, v7, v10
	v_fma_f32 v13, -v8, v12, v7
	v_fmac_f32_e32 v12, v13, v10
	v_fma_f32 v5, -v8, v12, v7
	v_fma_f32 v5, v5, v10, v12
	v_div_fixup_f32 v8, v5, v8, v7
	v_pk_mul_f32 v[2:3], v[2:3], v[8:9]
	s_nop 0
	v_cvt_pk_bf16_f32 v7, v2, v3
	global_store_dwordx2 v[0:1], v[6:7], off offset:32
	s_nop 0
	s_nop 0
	s_nop 0
	s_waitcnt lgkmcnt(0)
	v_mov_b32_e32 v2, v218
	v_mov_b32_e32 v3, v219
	v_mov_b32_e32 v6, v248
	v_mov_b32_e32 v7, v249
	v_mov_b32_e32 v8, v250
	v_mov_b32_e32 v9, v251
	v_and_b32_e32 v5, 0xffff0000, v2
	v_lshlrev_b32_e32 v2, 16, v2
	v_mul_f32_e32 v10, 0xbfb8aa3b, v2
	v_mul_f32_e32 v11, 0xbfb8aa3b, v5
	v_exp_f32_e32 v10, v10
	v_exp_f32_e32 v11, v11
	v_pk_mul_f32 v[12:13], v[34:35], v[4:5] op_sel_hi:[1,0]
	v_pk_add_f32 v[10:11], v[10:11], 1.0 op_sel_hi:[1,0]
	v_pk_mul_f32 v[6:7], v[12:13], v[6:7]
	v_rcp_f32_e32 v13, v11
	s_nop 0
	v_fma_f32 v14, -v11, v13, 1.0
	v_fmac_f32_e32 v13, v14, v13
	v_mul_f32_e32 v15, v5, v13
	v_fma_f32 v16, -v11, v15, v5
	v_fmac_f32_e32 v15, v16, v13
	v_fma_f32 v12, -v11, v15, v5
	v_fma_f32 v12, v12, v13, v15
	v_div_fixup_f32 v11, v12, v11, v5
	v_rcp_f32_e32 v12, v10
	s_nop 0
	v_fma_f32 v13, -v10, v12, 1.0
	v_fmac_f32_e32 v12, v13, v12
	v_mul_f32_e32 v14, v2, v12
	v_fma_f32 v15, -v10, v14, v2
	v_fmac_f32_e32 v14, v15, v12
	v_fma_f32 v5, -v10, v14, v2
	v_fma_f32 v5, v5, v12, v14
	v_div_fixup_f32 v10, v5, v10, v2
	v_pk_mul_f32 v[6:7], v[6:7], v[10:11]
	v_and_b32_e32 v10, 0xffff0000, v3
	v_lshlrev_b32_e32 v3, 16, v3
	v_cvt_pk_bf16_f32 v2, v6, v7
	v_mul_f32_e32 v5, 0xbfb8aa3b, v3
	v_mul_f32_e32 v7, 0xbfb8aa3b, v10
	v_exp_f32_e32 v6, v5
	v_exp_f32_e32 v7, v7
	v_pk_mul_f32 v[4:5], v[32:33], v[4:5] op_sel_hi:[1,0]
	v_pk_add_f32 v[6:7], v[6:7], 1.0 op_sel_hi:[1,0]
	v_pk_mul_f32 v[4:5], v[4:5], v[8:9]
	v_rcp_f32_e32 v9, v7
	s_nop 0
	v_fma_f32 v11, -v7, v9, 1.0
	v_fmac_f32_e32 v9, v11, v9
	v_mul_f32_e32 v12, v10, v9
	v_fma_f32 v13, -v7, v12, v10
	v_fmac_f32_e32 v12, v13, v9
	v_fma_f32 v8, -v7, v12, v10
	v_fma_f32 v8, v8, v9, v12
	v_div_fixup_f32 v7, v8, v7, v10
	v_rcp_f32_e32 v9, v6
	s_nop 0
	v_fma_f32 v10, -v6, v9, 1.0
	v_fmac_f32_e32 v9, v10, v9
	v_mul_f32_e32 v11, v3, v9
	v_fma_f32 v12, -v6, v11, v3
	v_fmac_f32_e32 v11, v12, v9
	v_fma_f32 v8, -v6, v11, v3
	v_fma_f32 v8, v8, v9, v11
	v_div_fixup_f32 v6, v8, v6, v3
	v_pk_mul_f32 v[4:5], v[4:5], v[6:7]
	s_nop 0
	v_cvt_pk_bf16_f32 v3, v4, v5
	global_store_dwordx2 v[0:1], v[2:3], off offset:48

; template <int MX, bool OUT>
; DI void rec_chunk(const Params& p, int l, int b, int h, int dir, int T0, unsigned char* smem, f32x4 (&St)[4], float& nst, float& dtot, int tid, const RecRaw& raw) {
;     ...
; #pragma unroll
;     for (int ks = 0; ks < 2; ++ks) {
;       const bf16x8 fb = *(const bf16x8*)(smem + L_QS + swz(t, ks * 4 + g));
; #pragma unroll
;       for (int a = 0; a < 4; ++a) {
;         const bf16x8 fa = *(const bf16x8*)(smem + L_STT + swz(16 * a + col, ks * 4 + g));
;         O[a] = MFMA16(fa, fb, O[a]);
;       }
;     }
;     if (MX == 1) {
;       const float inv = 1.f / fmaxf(fabsf(den), 1.f);
; #pragma unroll
;       for (int a = 0; a < 4; ++a)
; #pragma unroll
;         for (int j = 0; j < 4; ++j) O[a][j] *= inv;
;     }
;     if (dir == 0) {
; #pragma unroll
;       for (int a = 0; a < 4; ++a) *(uint2*)(MIX + kblk((int)orow, cb + 16 * a + 4 * g, ROWS)) = make_uint2(pk2(O[a][0], O[a][1]), pk2(O[a][2], O[a][3]));
;     } else {
;       float ss = 0.f;
; #pragma unroll
;       for (int a = 0; a < 4; ++a) {
;         const uint2 u = *(const uint2*)(MIX + kblk((int)orow, cb + 16 * a + 4 * g, ROWS));
;         O[a][0] += __uint_as_float(u.x << 16); O[a][1] += __uint_as_float(u.x & 0xffff0000u);
;         O[a][2] += __uint_as_float(u.y << 16); O[a][3] += __uint_as_float(u.y & 0xffff0000u);
; #pragma unroll
;         for (int j = 0; j < 4; ++j) ss += O[a][j] * O[a][j];
;       }
;       ss += __shfl_xor(ss, 16);
;       ss += __shfl_xor(ss, 32);
;       const float rstd = rsqrtf(ss * (1.f / 64.f) + EPS);
;       const float* gvec = (MX ? p.ml_g : p.hg_g) + l * 64;
; #pragma unroll
;       for (int a = 0; a < 4; ++a) {
;         const int v0 = 16 * a + 4 * g;
;         const uint2 gt = *(const uint2*)(prow + GATE + cb + v0);
;         const float4 gg = *(const float4*)(gvec + v0);
;         float y0 = O[a][0] * rstd * gg.x * siluf_(__uint_as_float(gt.x << 16));
;         float y1 = O[a][1] * rstd * gg.y * siluf_(__uint_as_float(gt.x & 0xffff0000u));
;         float y2 = O[a][2] * rstd * gg.z * siluf_(__uint_as_float(gt.y << 16));
;         float y3 = O[a][3] * rstd * gg.w * siluf_(__uint_as_float(gt.y & 0xffff0000u));
;         if (MX == 1) {
;           const uint2 og = *(const uint2*)(prow + D_OG + h * 64 + v0);
;           y0 *= sigmoidf_(__uint_as_float(og.x << 16)); y1 *= sigmoidf_(__uint_as_float(og.x & 0xffff0000u));
.LBB0_683:
	s_or_b64 exec, exec, s[0:1]
	ds_read_b128 v[42:45], v240 offset:32768
	ds_read_b128 v[46:49], v238 offset:57344
	ds_read_b128 v[50:53], v238 offset:59392
	s_add_i32 s0, s13, -1
	v_mov_b32_e32 v40, s0
	v_cndmask_b32_e64 v40, v91, v40, s[24:25]
	s_waitcnt lgkmcnt(1)
	v_mfma_f32_16x16x32_bf16 v[46:49], v[46:49], v[42:45], v[56:59]
	v_lshlrev_b32_e32 v40, 6, v40
	v_add_u32_e32 v160, s12, v40
	v_lshl_add_u64 v[40:41], v[160:161], 0, v[82:83]
	ds_read_b128 v[54:57], v238 offset:61440
	s_waitcnt lgkmcnt(1)
	v_mfma_f32_16x16x32_bf16 v[50:53], v[50:53], v[42:45], v[60:63]
	s_nop 2
	ds_read_b128 v[58:61], v238 offset:63488
	s_waitcnt lgkmcnt(1)
	v_mfma_f32_16x16x32_bf16 v[54:57], v[54:57], v[42:45], v[64:67]
	s_waitcnt lgkmcnt(0)
	v_mfma_f32_16x16x32_bf16 v[42:45], v[58:61], v[42:45], v[72:75]
	ds_read_b128 v[58:61], v239 offset:32768
	ds_read_b128 v[62:65], v237 offset:57344
	s_waitcnt lgkmcnt(0)
	v_mfma_f32_16x16x32_bf16 v[46:49], v[62:65], v[58:61], v[46:49]
	ds_read_b128 v[62:65], v237 offset:59392
	s_waitcnt lgkmcnt(0)
	v_mfma_f32_16x16x32_bf16 v[50:53], v[62:65], v[58:61], v[50:53]
	ds_read_b128 v[62:65], v237 offset:61440
	s_waitcnt lgkmcnt(0)
	v_mfma_f32_16x16x32_bf16 v[62:65], v[62:65], v[58:61], v[54:57]
	s_nop 2
	ds_read_b128 v[54:57], v237 offset:63488
	s_waitcnt lgkmcnt(0)
	v_mfma_f32_16x16x32_bf16 v[42:45], v[54:57], v[58:61], v[42:45]
	v_add_f32_e32 v54, v93, v96
	v_max_f32_e64 v54, |v54|, 1.0
	v_rcp_f32_e32 v56, v54
	s_mov_b64 s[0:1], -1
	v_fma_f32 v57, -v54, v56, 1.0
	v_fmac_f32_e32 v56, v57, v56
	v_mul_f32_e32 v58, 1.0, v56
	v_fma_f32 v59, -v54, v58, 1.0
	v_fmac_f32_e32 v58, v59, v56
	v_fma_f32 v55, -v54, v58, 1.0
	v_fma_f32 v55, v55, v56, v58
	v_div_fixup_f32 v60, v55, v54, 1.0
	v_pk_mul_f32 v[54:55], v[60:61], v[46:47] op_sel_hi:[0,1]
	v_pk_mul_f32 v[46:47], v[60:61], v[42:43] op_sel_hi:[0,1]
	v_ashrrev_i32_e32 v43, 31, v40
	v_mov_b32_e32 v42, v40
	v_pk_mul_f32 v[58:59], v[60:61], v[48:49] op_sel_hi:[0,1]
	v_pk_mul_f32 v[50:51], v[60:61], v[50:51] op_sel_hi:[0,1]
	v_pk_mul_f32 v[56:57], v[60:61], v[52:53] op_sel_hi:[0,1]
	v_pk_mul_f32 v[48:49], v[60:61], v[62:63] op_sel_hi:[0,1]
	v_pk_mul_f32 v[52:53], v[60:61], v[64:65] op_sel_hi:[0,1]
	v_pk_mul_f32 v[44:45], v[60:61], v[44:45] op_sel_hi:[0,1]
	v_lshl_add_u64 v[60:61], v[42:43], 0, s[28:29]
	v_lshl_add_u64 v[62:63], v[42:43], 0, s[30:31]
	v_lshl_add_u64 v[42:43], v[42:43], 0, s[42:43]
	s_andn2_b64 vcc, exec, s[44:45]
	v_lshlrev_b64 v[64:65], 6, v[60:61]
	v_lshlrev_b64 v[62:63], 6, v[62:63]
	v_lshlrev_b64 v[60:61], 6, v[42:43]
	s_cbranch_vccnz .LBB0_685
	v_lshl_add_u64 v[98:99], v[88:89], 0, v[62:63]
	global_load_dwordx2 v[66:67], v[98:99], off
	v_mov_b64_e32 v[42:43], s[18:19]
	v_mad_u64_u32 v[42:43], s[0:1], v40, s33, v[42:43]
	v_mad_i32_i24 v43, v41, s33, v43
	s_mov_b64 s[0:1], 0x1a20
	v_mov_b32_e32 v91, v161
	v_lshl_add_u64 v[74:75], v[42:43], 0, s[0:1]
	v_lshl_add_u64 v[100:101], v[74:75], 0, s[2:3]
	v_lshl_add_u64 v[74:75], v[74:75], 0, v[90:91]
	v_lshl_add_u64 v[102:103], v[84:85], 0, v[64:65]
	v_lshl_add_u64 v[74:75], v[74:75], 0, s[2:3]
	global_load_dwordx2 v[40:41], v[102:103], off
	s_mov_b32 s21, s3
	v_lshl_add_u64 v[42:43], v[42:43], 0, s[20:21]
	v_lshl_add_u64 v[42:43], v[42:43], 0, v[90:91]
	s_mov_b64 s[0:1], 0x1820
	v_lshl_add_u64 v[100:101], v[100:101], 0, v[90:91]
	global_load_dwordx2 v[74:75], v[74:75], off
	s_waitcnt vmcnt(0) lgkmcnt(0)
	v_lshlrev_b32_e32 v96, 16, v66
	v_and_b32_e32 v97, 0xffff0000, v66
	v_lshlrev_b32_e32 v104, 16, v67
	v_and_b32_e32 v105, 0xffff0000, v67
	v_lshl_add_u64 v[66:67], s[22:23], 0, v[60:61]
	v_lshl_add_u64 v[72:73], v[66:67], 0, v[90:91]
	global_load_dwordx2 v[68:69], v[72:73], off
	v_pk_add_f32 v[246:247], v[50:51], v[96:97]
	v_lshlrev_b32_e32 v124, 16, v40
	v_and_b32_e32 v125, 0xffff0000, v40
	v_lshlrev_b32_e32 v40, 16, v41
	v_and_b32_e32 v41, 0xffff0000, v41
	v_pk_add_f32 v[124:125], v[54:55], v[124:125]
	v_pk_mul_f32 v[96:97], v[246:247], v[246:247]
	v_lshlrev_b32_e32 v93, 16, v74
	v_and_b32_e32 v160, 0xffff0000, v74
	v_lshlrev_b32_e32 v126, 16, v75
	v_and_b32_e32 v127, 0xffff0000, v75
	v_lshl_add_u64 v[74:75], v[42:43], 0, s[0:1]
	v_add_co_u32_e32 v42, vcc, s16, v42
	v_mul_f32_e32 v116, 0xbfb8aa3b, v126
	s_nop 0
	v_addc_co_u32_e32 v43, vcc, 0, v43, vcc
	v_mul_f32_e32 v117, 0xbfb8aa3b, v127
	global_load_dwordx2 v[42:43], v[42:43], off offset:2080
	v_exp_f32_e32 v116, v116
	v_exp_f32_e32 v117, v117
	s_waitcnt vmcnt(0) lgkmcnt(0)
; DI size_t kblk(int row, int col, int nrows) { return ((size_t)(col >> 5) * nrows + row) * 32 + (col & 31); }
; DI unsigned pk2(float a, float b) { hwf32x2 f = {a, b}; hwbf16x2 r = __builtin_convertvector(f, hwbf16x2); return __builtin_bit_cast(unsigned, r); }
; DI float sigmoidf_(float z) { return 1.f / (1.f + __expf(-z)); }
; DI float siluf_(float z) { return z / (1.f + __expf(-z)); }
; template <int MX, bool OUT>
; DI void rec_chunk(const Params& p, int l, int b, int h, int dir, int T0, unsigned char* smem, f32x4 (&St)[4], float& nst, float& dtot, int tid, const RecRaw& raw) {
;     ...
;       float ss = 0.f;
; #pragma unroll
;       for (int a = 0; a < 4; ++a) {
;         const uint2 u = *(const uint2*)(MIX + kblk((int)orow, cb + 16 * a + 4 * g, ROWS));
;         O[a][0] += __uint_as_float(u.x << 16); O[a][1] += __uint_as_float(u.x & 0xffff0000u);
;         O[a][2] += __uint_as_float(u.y << 16); O[a][3] += __uint_as_float(u.y & 0xffff0000u);
; #pragma unroll
;         for (int j = 0; j < 4; ++j) ss += O[a][j] * O[a][j];
;       }
;       ss += __shfl_xor(ss, 16);
;       ss += __shfl_xor(ss, 32);
;       const float rstd = rsqrtf(ss * (1.f / 64.f) + EPS);
;       const float* gvec = (MX ? p.ml_g : p.hg_g) + l * 64;
; #pragma unroll
;       for (int a = 0; a < 4; ++a) {
;         const int v0 = 16 * a + 4 * g;
;         const uint2 gt = *(const uint2*)(prow + GATE + cb + v0);
;         const float4 gg = *(const float4*)(gvec + v0);
;         float y0 = O[a][0] * rstd * gg.x * siluf_(__uint_as_float(gt.x << 16));
;         float y1 = O[a][1] * rstd * gg.y * siluf_(__uint_as_float(gt.x & 0xffff0000u));
;         float y2 = O[a][2] * rstd * gg.z * siluf_(__uint_as_float(gt.y << 16));
;         float y3 = O[a][3] * rstd * gg.w * siluf_(__uint_as_float(gt.y & 0xffff0000u));
;         if (MX == 1) {
;           const uint2 og = *(const uint2*)(prow + D_OG + h * 64 + v0);
;           y0 *= sigmoidf_(__uint_as_float(og.x << 16)); y1 *= sigmoidf_(__uint_as_float(og.x & 0xffff0000u));
;           y2 *= sigmoidf_(__uint_as_float(og.y << 16)); y3 *= sigmoidf_(__uint_as_float(og.y & 0xffff0000u));
;         }
;         *(uint2*)(MIX + kblk((int)orow, cb + v0, ROWS)) = make_uint2(pk2(y0, y1), pk2(y2, y3));
	v_lshlrev_b32_e32 v106, 16, v68
	v_and_b32_e32 v107, 0xffff0000, v68
	v_pk_add_f32 v[116:117], v[116:117], 1.0 op_sel_hi:[1,0]
	v_lshlrev_b32_e32 v108, 16, v69
	v_rcp_f32_e32 v129, v117
	v_and_b32_e32 v109, 0xffff0000, v69
	global_load_dwordx2 v[68:69], v[72:73], off offset:32
	v_pk_add_f32 v[106:107], v[48:49], v[106:107]
	v_fma_f32 v241, -v117, v129, 1.0
	v_fmac_f32_e32 v129, v241, v129
	v_mul_f32_e32 v242, v127, v129
	v_fma_f32 v243, -v117, v242, v127
	v_fmac_f32_e32 v242, v243, v129
	v_fma_f32 v128, -v117, v242, v127
	v_fma_f32 v128, v128, v129, v242
	v_div_fixup_f32 v117, v128, v117, v127
	v_rcp_f32_e32 v128, v116
	v_pk_mul_f32 v[248:249], v[106:107], v[106:107]
	v_lshlrev_b32_e32 v114, 16, v42
	v_and_b32_e32 v42, 0xffff0000, v42
	v_fma_f32 v129, -v116, v128, 1.0
	v_fmac_f32_e32 v128, v129, v128
	v_mul_f32_e32 v241, v126, v128
	v_fma_f32 v242, -v116, v241, v126
	v_fmac_f32_e32 v241, v242, v128
	v_fma_f32 v127, -v116, v241, v126
	v_fma_f32 v127, v127, v128, v241
	v_mul_f32_e32 v128, 0xbfb8aa3b, v93
	v_mul_f32_e32 v129, 0xbfb8aa3b, v160
	v_exp_f32_e32 v128, v128
	v_exp_f32_e32 v129, v129
	v_div_fixup_f32 v116, v127, v116, v126
	v_pk_mul_f32 v[126:127], v[124:125], v[124:125]
	v_mul_f32_e32 v114, 0xbfb8aa3b, v114
	v_pk_add_f32 v[128:129], v[128:129], 1.0 op_sel_hi:[1,0]
	v_mul_f32_e32 v42, 0xbfb8aa3b, v42
	v_rcp_f32_e32 v242, v129
	v_add_f32_e32 v91, v126, v127
	v_exp_f32_e32 v122, v114
	v_exp_f32_e32 v123, v42
	v_fma_f32 v243, -v129, v242, 1.0
	v_fmac_f32_e32 v242, v243, v242
	v_mul_f32_e32 v244, v160, v242
	v_fma_f32 v245, -v129, v244, v160
	v_fmac_f32_e32 v244, v245, v242
	v_fma_f32 v241, -v129, v244, v160
	v_fma_f32 v241, v241, v242, v244
	v_div_fixup_f32 v129, v241, v129, v160
	v_rcp_f32_e32 v241, v128
	v_lshlrev_b32_e32 v42, 16, v43
	v_pk_add_f32 v[114:115], v[58:59], v[40:41]
	v_mul_f32_e32 v42, 0xbfb8aa3b, v42
	v_fma_f32 v242, -v128, v241, 1.0
	v_fmac_f32_e32 v241, v242, v241
	v_mul_f32_e32 v243, v93, v241
	v_fma_f32 v244, -v128, v243, v93
	v_fmac_f32_e32 v243, v244, v241
	v_fma_f32 v160, -v128, v243, v93
	v_fma_f32 v160, v160, v241, v243
	v_div_fixup_f32 v128, v160, v128, v93
	v_pk_mul_f32 v[118:119], v[114:115], v[114:115]
	v_exp_f32_e32 v120, v42
	v_and_b32_e32 v42, 0xffff0000, v43
	v_add_f32_e32 v91, v91, v118
	v_mul_f32_e32 v42, 0xbfb8aa3b, v42
	v_add_f32_e32 v91, v119, v91
	v_pk_add_f32 v[122:123], v[122:123], 1.0 op_sel_hi:[1,0]
	v_exp_f32_e32 v121, v42
	global_load_dwordx4 v[40:43], v[86:87], off
	v_rcp_f32_e32 v160, v123
	v_pk_add_f32 v[120:121], v[120:121], 1.0 op_sel_hi:[1,0]
	v_add_f32_e32 v91, v96, v91
	v_add_f32_e32 v91, v97, v91
	v_fma_f32 v241, -v123, v160, 1.0
	v_fmac_f32_e32 v160, v241, v160
	v_mul_f32_e32 v242, 1.0, v160
	v_fma_f32 v243, -v123, v242, 1.0
	v_fmac_f32_e32 v242, v243, v160
	v_fma_f32 v93, -v123, v242, 1.0
	v_fma_f32 v93, v93, v160, v242
	v_div_fixup_f32 v123, v93, v123, 1.0
	v_rcp_f32_e32 v160, v122
	s_waitcnt vmcnt(0) lgkmcnt(0)
	v_lshlrev_b32_e32 v70, 16, v68
	v_and_b32_e32 v71, 0xffff0000, v68
	v_pk_add_f32 v[70:71], v[46:47], v[70:71]
	v_fma_f32 v241, -v122, v160, 1.0
	v_fmac_f32_e32 v160, v241, v160
	v_mul_f32_e32 v242, 1.0, v160
	v_fma_f32 v243, -v122, v242, 1.0
	v_fmac_f32_e32 v242, v243, v160
	v_fma_f32 v93, -v122, v242, 1.0
	v_fma_f32 v93, v93, v160, v242
	v_div_fixup_f32 v122, v93, v122, 1.0
	v_rcp_f32_e32 v160, v121
	v_lshlrev_b32_e32 v68, 16, v69
	v_and_b32_e32 v69, 0xffff0000, v69
	v_pk_mul_f32 v[110:111], v[70:71], v[70:71]
	v_fma_f32 v241, -v121, v160, 1.0
	v_fmac_f32_e32 v160, v241, v160
	v_mul_f32_e32 v242, 1.0, v160
	v_fma_f32 v243, -v121, v242, 1.0
	v_fmac_f32_e32 v242, v243, v160
	v_fma_f32 v93, -v121, v242, 1.0
	v_fma_f32 v93, v93, v160, v242
	v_div_fixup_f32 v121, v93, v121, 1.0
	v_rcp_f32_e32 v160, v120
	v_pk_add_f32 v[68:69], v[44:45], v[68:69]
	v_fma_f32 v241, -v120, v160, 1.0
	v_fmac_f32_e32 v160, v241, v160
	v_mul_f32_e32 v242, 1.0, v160
	v_fma_f32 v243, -v120, v242, 1.0
	v_fmac_f32_e32 v242, v243, v160
	v_fma_f32 v93, -v120, v242, 1.0
	v_fma_f32 v93, v93, v160, v242
	v_pk_add_f32 v[242:243], v[56:57], v[104:105]
	v_pk_add_f32 v[104:105], v[52:53], v[108:109]
	v_pk_mul_f32 v[244:245], v[242:243], v[242:243]
	v_pk_mul_f32 v[108:109], v[104:105], v[104:105]
	v_add_f32_e32 v91, v244, v91
	v_add_f32_e32 v91, v245, v91
	v_add_f32_e32 v91, v248, v91
	v_add_f32_e32 v91, v249, v91
	v_add_f32_e32 v91, v108, v91
	v_add_f32_e32 v91, v109, v91
	v_add_f32_e32 v91, v110, v91
	v_pk_mul_f32 v[112:113], v[68:69], v[68:69]
	v_add_f32_e32 v91, v111, v91
	v_add_f32_e32 v91, v112, v91
	v_add_f32_e32 v91, v113, v91
	v_div_fixup_f32 v120, v93, v120, 1.0
	ds_bpermute_b32 v93, v145, v91
	s_waitcnt lgkmcnt(0)
	v_add_f32_e32 v91, v91, v93
	ds_bpermute_b32 v93, v146, v91
	s_waitcnt lgkmcnt(0)
	v_add_f32_e32 v91, v91, v93
	v_fmamk_f32 v91, v91, 0x3c800000, v162
	v_cmp_gt_f32_e32 vcc, s38, v91
	v_mul_f32_e32 v93, 0x4b800000, v91
	s_nop 0
	v_cndmask_b32_e32 v91, v91, v93, vcc
	v_rsq_f32_e32 v91, v91
	s_nop 0
	v_mul_f32_e32 v93, 0x45800000, v91
	v_cndmask_b32_e32 v96, v91, v93, vcc
	v_pk_mul_f32 v[108:109], v[124:125], v[96:97] op_sel_hi:[1,0]
	s_nop 0
	v_pk_mul_f32 v[40:41], v[40:41], v[108:109]
	v_pk_mul_f32 v[108:109], v[114:115], v[96:97] op_sel_hi:[1,0]
	v_pk_mul_f32 v[40:41], v[128:129], v[40:41]
	v_pk_mul_f32 v[42:43], v[42:43], v[108:109]
	v_pk_mul_f32 v[40:41], v[122:123], v[40:41]
	v_pk_mul_f32 v[42:43], v[116:117], v[42:43]
	v_cvt_pk_bf16_f32 v40, v40, v41
	v_pk_mul_f32 v[42:43], v[120:121], v[42:43]
	s_nop 0
	v_cvt_pk_bf16_f32 v41, v42, v43
	global_store_dwordx2 v[102:103], v[40:41], off
	global_load_dwordx2 v[40:41], v[100:101], off offset:32
	s_nop 0
	global_load_dwordx4 v[108:111], v[86:87], off offset:64
	v_pk_mul_f32 v[102:103], v[246:247], v[96:97] op_sel_hi:[1,0]
	s_waitcnt vmcnt(0) lgkmcnt(0)
; DI size_t kblk(int row, int col, int nrows) { return ((size_t)(col >> 5) * nrows + row) * 32 + (col & 31); }
; DI unsigned pk2(float a, float b) { hwf32x2 f = {a, b}; hwbf16x2 r = __builtin_convertvector(f, hwbf16x2); return __builtin_bit_cast(unsigned, r); }
; DI float sigmoidf_(float z) { return 1.f / (1.f + __expf(-z)); }
; DI float siluf_(float z) { return z / (1.f + __expf(-z)); }
; template <int MX, bool OUT>
; DI void rec_chunk(const Params& p, int l, int b, int h, int dir, int T0, unsigned char* smem, f32x4 (&St)[4], float& nst, float& dtot, int tid, const RecRaw& raw) {
;     ...
;       for (int a = 0; a < 4; ++a) {
;         const int v0 = 16 * a + 4 * g;
;         const uint2 gt = *(const uint2*)(prow + GATE + cb + v0);
;         const float4 gg = *(const float4*)(gvec + v0);
;         float y0 = O[a][0] * rstd * gg.x * siluf_(__uint_as_float(gt.x << 16));
;         float y1 = O[a][1] * rstd * gg.y * siluf_(__uint_as_float(gt.x & 0xffff0000u));
;         float y2 = O[a][2] * rstd * gg.z * siluf_(__uint_as_float(gt.y << 16));
;         float y3 = O[a][3] * rstd * gg.w * siluf_(__uint_as_float(gt.y & 0xffff0000u));
;         if (MX == 1) {
;           const uint2 og = *(const uint2*)(prow + D_OG + h * 64 + v0);
;           y0 *= sigmoidf_(__uint_as_float(og.x << 16)); y1 *= sigmoidf_(__uint_as_float(og.x & 0xffff0000u));
;           y2 *= sigmoidf_(__uint_as_float(og.y << 16)); y3 *= sigmoidf_(__uint_as_float(og.y & 0xffff0000u));
;         }
;         *(uint2*)(MIX + kblk((int)orow, cb + v0, ROWS)) = make_uint2(pk2(y0, y1), pk2(y2, y3));
	v_lshlrev_b32_e32 v91, 16, v40
	v_and_b32_e32 v40, 0xffff0000, v40
	v_mul_f32_e32 v42, 0xbfb8aa3b, v91
	v_mul_f32_e32 v43, 0xbfb8aa3b, v40
	v_exp_f32_e32 v42, v42
	v_exp_f32_e32 v43, v43
	v_pk_mul_f32 v[102:103], v[108:109], v[102:103]
	v_pk_add_f32 v[42:43], v[42:43], 1.0 op_sel_hi:[1,0]
	s_nop 0
	v_rcp_f32_e32 v97, v43
	s_nop 0
	v_fma_f32 v108, -v43, v97, 1.0
	v_fmac_f32_e32 v97, v108, v97
	v_mul_f32_e32 v109, v40, v97
	v_fma_f32 v112, -v43, v109, v40
	v_fmac_f32_e32 v109, v112, v97
	v_fma_f32 v93, -v43, v109, v40
	v_fma_f32 v93, v93, v97, v109
	v_div_fixup_f32 v43, v93, v43, v40
	v_rcp_f32_e32 v93, v42
	s_nop 0
	v_fma_f32 v97, -v42, v93, 1.0
	v_fmac_f32_e32 v93, v97, v93
	v_mul_f32_e32 v108, v91, v93
	v_fma_f32 v109, -v42, v108, v91
	v_fmac_f32_e32 v108, v109, v93
	v_fma_f32 v40, -v42, v108, v91
	v_fma_f32 v40, v40, v93, v108
	v_div_fixup_f32 v42, v40, v42, v91
	v_lshlrev_b32_e32 v91, 16, v41
	v_and_b32_e32 v93, 0xffff0000, v41
	v_mul_f32_e32 v40, 0xbfb8aa3b, v91
	v_mul_f32_e32 v41, 0xbfb8aa3b, v93
	v_exp_f32_e32 v40, v40
	v_exp_f32_e32 v41, v41
	v_pk_mul_f32 v[42:43], v[42:43], v[102:103]
	v_pk_mul_f32 v[102:103], v[242:243], v[96:97] op_sel_hi:[1,0]
	v_pk_add_f32 v[40:41], v[40:41], 1.0 op_sel_hi:[1,0]
	s_nop 0
	v_rcp_f32_e32 v108, v41
	v_pk_mul_f32 v[102:103], v[110:111], v[102:103]
	v_fma_f32 v109, -v41, v108, 1.0
	v_fmac_f32_e32 v108, v109, v108
	v_mul_f32_e32 v110, v93, v108
	v_fma_f32 v111, -v41, v110, v93
	v_fmac_f32_e32 v110, v111, v108
	v_fma_f32 v97, -v41, v110, v93
	v_fma_f32 v97, v97, v108, v110
	v_div_fixup_f32 v41, v97, v41, v93
	v_rcp_f32_e32 v97, v40
	s_nop 0
	v_fma_f32 v108, -v40, v97, 1.0
	v_fmac_f32_e32 v97, v108, v97
	v_mul_f32_e32 v109, v91, v97
	v_fma_f32 v110, -v40, v109, v91
	v_fmac_f32_e32 v109, v110, v97
	v_fma_f32 v93, -v40, v109, v91
	v_fma_f32 v93, v93, v97, v109
	v_div_fixup_f32 v40, v93, v40, v91
	v_pk_mul_f32 v[40:41], v[40:41], v[102:103]
	global_load_dwordx2 v[102:103], v[74:75], off offset:32
	s_waitcnt vmcnt(0) lgkmcnt(0)
	v_lshlrev_b32_e32 v91, 16, v102
	v_mul_f32_e32 v91, 0xbfb8aa3b, v91
	v_exp_f32_e32 v108, v91
	v_and_b32_e32 v91, 0xffff0000, v102
	v_mul_f32_e32 v91, 0xbfb8aa3b, v91
	v_exp_f32_e32 v109, v91
	s_nop 0
	v_pk_add_f32 v[108:109], v[108:109], 1.0 op_sel_hi:[1,0]
	s_nop 0
	v_rcp_f32_e32 v93, v109
	s_nop 0
	v_fma_f32 v97, -v109, v93, 1.0
	v_fmac_f32_e32 v93, v97, v93
	v_mul_f32_e32 v102, 1.0, v93
	v_fma_f32 v110, -v109, v102, 1.0
	v_fmac_f32_e32 v102, v110, v93
	v_fma_f32 v91, -v109, v102, 1.0
	v_fma_f32 v91, v91, v93, v102
	v_div_fixup_f32 v109, v91, v109, 1.0
	v_rcp_f32_e32 v93, v108
	s_nop 0
	v_fma_f32 v97, -v108, v93, 1.0
	v_fmac_f32_e32 v93, v97, v93
	v_mul_f32_e32 v102, 1.0, v93
	v_fma_f32 v110, -v108, v102, 1.0
	v_fmac_f32_e32 v102, v110, v93
	v_fma_f32 v91, -v108, v102, 1.0
	v_fma_f32 v91, v91, v93, v102
	v_div_fixup_f32 v108, v91, v108, 1.0
	v_lshlrev_b32_e32 v91, 16, v103
	v_mul_f32_e32 v91, 0xbfb8aa3b, v91
	v_exp_f32_e32 v102, v91
	v_and_b32_e32 v91, 0xffff0000, v103
	v_mul_f32_e32 v91, 0xbfb8aa3b, v91
	v_exp_f32_e32 v103, v91
	v_pk_mul_f32 v[42:43], v[42:43], v[108:109]
	v_pk_add_f32 v[102:103], v[102:103], 1.0 op_sel_hi:[1,0]
	s_nop 0
	v_rcp_f32_e32 v93, v103
	v_cvt_pk_bf16_f32 v42, v42, v43
	v_fma_f32 v97, -v103, v93, 1.0
	v_fmac_f32_e32 v93, v97, v93
	v_mul_f32_e32 v108, 1.0, v93
	v_fma_f32 v109, -v103, v108, 1.0
	v_fmac_f32_e32 v108, v109, v93
	v_fma_f32 v91, -v103, v108, 1.0
	v_fma_f32 v91, v91, v93, v108
	v_div_fixup_f32 v103, v91, v103, 1.0
	v_rcp_f32_e32 v93, v102
	s_nop 0
	v_fma_f32 v97, -v102, v93, 1.0
	v_fmac_f32_e32 v93, v97, v93
	v_mul_f32_e32 v108, 1.0, v93
	v_fma_f32 v109, -v102, v108, 1.0
	v_fmac_f32_e32 v108, v109, v93
	v_fma_f32 v91, -v102, v108, 1.0
	v_fma_f32 v91, v91, v93, v108
	v_div_fixup_f32 v102, v91, v102, 1.0
	v_pk_mul_f32 v[40:41], v[40:41], v[102:103]
	s_nop 0
	v_cvt_pk_bf16_f32 v43, v40, v41
	global_store_dwordx2 v[98:99], v[42:43], off
	global_load_dwordx2 v[40:41], v[100:101], off offset:64
	global_load_dwordx4 v[108:111], v[86:87], off offset:128
	v_pk_mul_f32 v[98:99], v[106:107], v[96:97] op_sel_hi:[1,0]
	s_waitcnt vmcnt(0) lgkmcnt(0)
	v_lshlrev_b32_e32 v91, 16, v40
	v_and_b32_e32 v40, 0xffff0000, v40
	v_mul_f32_e32 v42, 0xbfb8aa3b, v91
	v_mul_f32_e32 v43, 0xbfb8aa3b, v40
	v_exp_f32_e32 v42, v42
	v_exp_f32_e32 v43, v43
	v_pk_mul_f32 v[98:99], v[98:99], v[108:109]
	v_pk_add_f32 v[42:43], v[42:43], 1.0 op_sel_hi:[1,0]
	s_nop 0
	v_rcp_f32_e32 v97, v43
	s_nop 0
	v_fma_f32 v102, -v43, v97, 1.0
	v_fmac_f32_e32 v97, v102, v97
	v_mul_f32_e32 v103, v40, v97
	v_fma_f32 v106, -v43, v103, v40
	v_fmac_f32_e32 v103, v106, v97
	v_fma_f32 v93, -v43, v103, v40
	v_fma_f32 v93, v93, v97, v103
	v_div_fixup_f32 v43, v93, v43, v40
	v_rcp_f32_e32 v93, v42
	s_nop 0
	v_fma_f32 v97, -v42, v93, 1.0
	v_fmac_f32_e32 v93, v97, v93
	v_mul_f32_e32 v102, v91, v93
	v_fma_f32 v103, -v42, v102, v91
	v_fmac_f32_e32 v102, v103, v93
	v_fma_f32 v40, -v42, v102, v91
	v_fma_f32 v40, v40, v93, v102
	v_div_fixup_f32 v42, v40, v42, v91
	v_lshlrev_b32_e32 v91, 16, v41
	v_and_b32_e32 v93, 0xffff0000, v41
	v_mul_f32_e32 v40, 0xbfb8aa3b, v91
	v_mul_f32_e32 v41, 0xbfb8aa3b, v93
	v_exp_f32_e32 v40, v40
	v_exp_f32_e32 v41, v41
	v_pk_mul_f32 v[42:43], v[98:99], v[42:43]
	v_pk_mul_f32 v[98:99], v[104:105], v[96:97] op_sel_hi:[1,0]
	v_pk_add_f32 v[40:41], v[40:41], 1.0 op_sel_hi:[1,0]
	s_nop 0
	v_rcp_f32_e32 v102, v41
	v_pk_mul_f32 v[98:99], v[98:99], v[110:111]
	v_fma_f32 v103, -v41, v102, 1.0
	v_fmac_f32_e32 v102, v103, v102
	v_mul_f32_e32 v104, v93, v102
	v_fma_f32 v105, -v41, v104, v93
	v_fmac_f32_e32 v104, v105, v102
	v_fma_f32 v97, -v41, v104, v93
	v_fma_f32 v97, v97, v102, v104
	v_div_fixup_f32 v41, v97, v41, v93
	v_rcp_f32_e32 v97, v40
	s_nop 0
	v_fma_f32 v102, -v40, v97, 1.0
	v_fmac_f32_e32 v97, v102, v97
	v_mul_f32_e32 v103, v91, v97
	v_fma_f32 v104, -v40, v103, v91
	v_fmac_f32_e32 v103, v104, v97
	v_fma_f32 v93, -v40, v103, v91
	v_fma_f32 v93, v93, v97, v103
	v_div_fixup_f32 v40, v93, v40, v91
	v_pk_mul_f32 v[40:41], v[98:99], v[40:41]
	global_load_dwordx2 v[98:99], v[74:75], off offset:64
	s_waitcnt vmcnt(0) lgkmcnt(0)
; DI size_t kblk(int row, int col, int nrows) { return ((size_t)(col >> 5) * nrows + row) * 32 + (col & 31); }
; DI unsigned pk2(float a, float b) { hwf32x2 f = {a, b}; hwbf16x2 r = __builtin_convertvector(f, hwbf16x2); return __builtin_bit_cast(unsigned, r); }
; DI float sigmoidf_(float z) { return 1.f / (1.f + __expf(-z)); }
; DI float siluf_(float z) { return z / (1.f + __expf(-z)); }
; template <int MX, bool OUT>
; DI void rec_chunk(const Params& p, int l, int b, int h, int dir, int T0, unsigned char* smem, f32x4 (&St)[4], float& nst, float& dtot, int tid, const RecRaw& raw) {
;     ...
;       for (int a = 0; a < 4; ++a) {
;         const int v0 = 16 * a + 4 * g;
;         const uint2 gt = *(const uint2*)(prow + GATE + cb + v0);
;         const float4 gg = *(const float4*)(gvec + v0);
;         float y0 = O[a][0] * rstd * gg.x * siluf_(__uint_as_float(gt.x << 16));
;         float y1 = O[a][1] * rstd * gg.y * siluf_(__uint_as_float(gt.x & 0xffff0000u));
;         float y2 = O[a][2] * rstd * gg.z * siluf_(__uint_as_float(gt.y << 16));
;         float y3 = O[a][3] * rstd * gg.w * siluf_(__uint_as_float(gt.y & 0xffff0000u));
;         if (MX == 1) {
;           const uint2 og = *(const uint2*)(prow + D_OG + h * 64 + v0);
;           y0 *= sigmoidf_(__uint_as_float(og.x << 16)); y1 *= sigmoidf_(__uint_as_float(og.x & 0xffff0000u));
;           y2 *= sigmoidf_(__uint_as_float(og.y << 16)); y3 *= sigmoidf_(__uint_as_float(og.y & 0xffff0000u));
;         }
;         *(uint2*)(MIX + kblk((int)orow, cb + v0, ROWS)) = make_uint2(pk2(y0, y1), pk2(y2, y3));
	v_lshlrev_b32_e32 v91, 16, v98
	v_mul_f32_e32 v91, 0xbfb8aa3b, v91
	v_exp_f32_e32 v102, v91
	v_and_b32_e32 v91, 0xffff0000, v98
	v_mul_f32_e32 v91, 0xbfb8aa3b, v91
	v_exp_f32_e32 v103, v91
	s_nop 0
	v_pk_add_f32 v[102:103], v[102:103], 1.0 op_sel_hi:[1,0]
	s_nop 0
	v_rcp_f32_e32 v93, v103
	s_nop 0
	v_fma_f32 v97, -v103, v93, 1.0
	v_fmac_f32_e32 v93, v97, v93
	v_mul_f32_e32 v98, 1.0, v93
	v_fma_f32 v104, -v103, v98, 1.0
	v_fmac_f32_e32 v98, v104, v93
	v_fma_f32 v91, -v103, v98, 1.0
	v_fma_f32 v91, v91, v93, v98
	v_div_fixup_f32 v103, v91, v103, 1.0
	v_rcp_f32_e32 v93, v102
	s_nop 0
	v_fma_f32 v97, -v102, v93, 1.0
	v_fmac_f32_e32 v93, v97, v93
	v_mul_f32_e32 v98, 1.0, v93
	v_fma_f32 v104, -v102, v98, 1.0
	v_fmac_f32_e32 v98, v104, v93
	v_fma_f32 v91, -v102, v98, 1.0
	v_fma_f32 v91, v91, v93, v98
	v_div_fixup_f32 v102, v91, v102, 1.0
	v_lshlrev_b32_e32 v91, 16, v99
	v_mul_f32_e32 v91, 0xbfb8aa3b, v91
	v_exp_f32_e32 v98, v91
	v_and_b32_e32 v91, 0xffff0000, v99
	v_mul_f32_e32 v91, 0xbfb8aa3b, v91
	v_exp_f32_e32 v99, v91
	v_pk_mul_f32 v[42:43], v[42:43], v[102:103]
	v_pk_add_f32 v[98:99], v[98:99], 1.0 op_sel_hi:[1,0]
	s_nop 0
	v_rcp_f32_e32 v93, v99
	v_cvt_pk_bf16_f32 v42, v42, v43
	v_fma_f32 v97, -v99, v93, 1.0
	v_fmac_f32_e32 v93, v97, v93
	v_mul_f32_e32 v102, 1.0, v93
	v_fma_f32 v103, -v99, v102, 1.0
	v_fmac_f32_e32 v102, v103, v93
	v_fma_f32 v91, -v99, v102, 1.0
	v_fma_f32 v91, v91, v93, v102
	v_div_fixup_f32 v99, v91, v99, 1.0
	v_rcp_f32_e32 v93, v98
	s_nop 0
	v_fma_f32 v97, -v98, v93, 1.0
	v_fmac_f32_e32 v93, v97, v93
	v_mul_f32_e32 v102, 1.0, v93
	v_fma_f32 v103, -v98, v102, 1.0
	v_fmac_f32_e32 v102, v103, v93
	v_fma_f32 v91, -v98, v102, 1.0
	v_fma_f32 v91, v91, v93, v102
	v_div_fixup_f32 v98, v91, v98, 1.0
	v_pk_mul_f32 v[40:41], v[40:41], v[98:99]
	s_nop 0
	v_cvt_pk_bf16_f32 v43, v40, v41
	global_store_dwordx2 v[72:73], v[42:43], off
	global_load_dwordx2 v[40:41], v[100:101], off offset:96
	s_nop 0
	global_load_dwordx2 v[74:75], v[74:75], off offset:96
	s_waitcnt vmcnt(0) lgkmcnt(0)
	v_lshlrev_b32_e32 v73, 16, v40
	v_and_b32_e32 v91, 0xffff0000, v40
	v_lshlrev_b32_e32 v40, 16, v41
	v_mul_f32_e32 v42, 0xbfb8aa3b, v40
	v_exp_f32_e32 v42, v42
	s_nop 0
	v_add_f32_e32 v42, 1.0, v42
	v_rcp_f32_e32 v72, v42
	s_nop 0
	v_fma_f32 v93, -v42, v72, 1.0
	v_fmac_f32_e32 v72, v93, v72
	v_mul_f32_e32 v97, v40, v72
	v_fma_f32 v98, -v42, v97, v40
	v_fmac_f32_e32 v97, v98, v72
	v_fma_f32 v43, -v42, v97, v40
	v_fma_f32 v43, v43, v72, v97
	v_and_b32_e32 v93, 0xffff0000, v41
	v_div_fixup_f32 v72, v43, v42, v40
	v_mul_f32_e32 v40, 0xbfb8aa3b, v93
	v_exp_f32_e32 v98, v40
	v_lshlrev_b32_e32 v40, 16, v74
	v_mul_f32_e32 v40, 0xbfb8aa3b, v40
	v_exp_f32_e32 v100, v40
	v_and_b32_e32 v40, 0xffff0000, v74
	v_mul_f32_e32 v40, 0xbfb8aa3b, v40
	v_exp_f32_e32 v101, v40
	global_load_dwordx4 v[40:43], v[86:87], off offset:192
	v_pk_mul_f32 v[70:71], v[70:71], v[96:97] op_sel_hi:[1,0]
	v_mul_f32_e32 v74, 0xbfb8aa3b, v73
	v_exp_f32_e32 v102, v74
	s_waitcnt vmcnt(0)
	v_pk_mul_f32 v[40:41], v[70:71], v[40:41]
	v_mul_f32_e32 v70, 0xbfb8aa3b, v91
	v_exp_f32_e32 v103, v70
	s_nop 0
	v_pk_add_f32 v[70:71], v[102:103], 1.0 op_sel_hi:[1,0]
	s_nop 0
	v_rcp_f32_e32 v97, v71
	s_nop 0
	v_fma_f32 v99, -v71, v97, 1.0
	v_fmac_f32_e32 v97, v99, v97
	v_mul_f32_e32 v102, v91, v97
	v_fma_f32 v103, -v71, v102, v91
	v_fmac_f32_e32 v102, v103, v97
	v_fma_f32 v74, -v71, v102, v91
	v_fma_f32 v74, v74, v97, v102
	v_div_fixup_f32 v71, v74, v71, v91
	v_rcp_f32_e32 v91, v70
	s_nop 0
	v_fma_f32 v97, -v70, v91, 1.0
	v_fmac_f32_e32 v91, v97, v91
	v_mul_f32_e32 v99, v73, v91
	v_fma_f32 v102, -v70, v99, v73
	v_fmac_f32_e32 v99, v102, v91
	v_fma_f32 v74, -v70, v99, v73
	v_fma_f32 v74, v74, v91, v99
	v_div_fixup_f32 v70, v74, v70, v73
	v_pk_mul_f32 v[40:41], v[40:41], v[70:71]
	v_pk_add_f32 v[70:71], v[100:101], 1.0 op_sel_hi:[1,0]
	s_nop 0
	v_rcp_f32_e32 v74, v71
	s_nop 0
	v_fma_f32 v91, -v71, v74, 1.0
	v_fmac_f32_e32 v74, v91, v74
	v_mul_f32_e32 v97, 1.0, v74
	v_fma_f32 v99, -v71, v97, 1.0
	v_fmac_f32_e32 v97, v99, v74
	v_fma_f32 v73, -v71, v97, 1.0
	v_fma_f32 v73, v73, v74, v97
	v_div_fixup_f32 v71, v73, v71, 1.0
	v_rcp_f32_e32 v74, v70
	s_nop 0
	v_fma_f32 v91, -v70, v74, 1.0
	v_fmac_f32_e32 v74, v91, v74
	v_mul_f32_e32 v97, 1.0, v74
	v_fma_f32 v99, -v70, v97, 1.0
	v_fmac_f32_e32 v97, v99, v74
	v_fma_f32 v73, -v70, v97, 1.0
	v_fma_f32 v73, v73, v74, v97
	v_div_fixup_f32 v70, v73, v70, 1.0
	v_pk_mul_f32 v[40:41], v[40:41], v[70:71]
	v_lshlrev_b32_e32 v70, 16, v75
	v_mul_f32_e32 v70, 0xbfb8aa3b, v70
	v_exp_f32_e32 v70, v70
	v_cvt_pk_bf16_f32 v40, v40, v41
	v_add_f32_e32 v70, 1.0, v70
	v_rcp_f32_e32 v73, v70
	s_nop 0
	v_fma_f32 v74, -v70, v73, 1.0
	v_fmac_f32_e32 v73, v74, v73
	v_mul_f32_e32 v91, 1.0, v73
	v_fma_f32 v97, -v70, v91, 1.0
	v_fmac_f32_e32 v91, v97, v73
	v_fma_f32 v71, -v70, v91, 1.0
	v_fma_f32 v71, v71, v73, v91
	v_div_fixup_f32 v70, v71, v70, 1.0
	v_and_b32_e32 v71, 0xffff0000, v75
	v_mul_f32_e32 v71, 0xbfb8aa3b, v71
	v_exp_f32_e32 v99, v71
	s_nop 0
	v_pk_add_f32 v[74:75], v[98:99], 1.0 op_sel_hi:[1,0]
	s_nop 0
	v_rcp_f32_e32 v73, v75
	s_nop 0
	v_fma_f32 v91, -v75, v73, 1.0
	v_fmac_f32_e32 v73, v91, v73
	v_mul_f32_e32 v97, 1.0, v73
	v_fma_f32 v98, -v75, v97, 1.0
	v_fmac_f32_e32 v97, v98, v73
	v_fma_f32 v71, -v75, v97, 1.0
	v_fma_f32 v71, v71, v73, v97
	v_div_fixup_f32 v71, v71, v75, 1.0
	v_rcp_f32_e32 v75, v74
	s_mov_b64 s[0:1], 0
	v_fma_f32 v91, -v74, v75, 1.0
	v_fmac_f32_e32 v75, v91, v75
	v_mul_f32_e32 v97, v93, v75
	v_fma_f32 v98, -v74, v97, v93
	v_fmac_f32_e32 v97, v98, v75
	v_fma_f32 v73, -v74, v97, v93
	v_fma_f32 v73, v73, v75, v97
	v_pk_mul_f32 v[68:69], v[68:69], v[96:97] op_sel_hi:[1,0]
	v_div_fixup_f32 v73, v73, v74, v93
	v_pk_mul_f32 v[42:43], v[68:69], v[42:43]
	v_mov_b32_e32 v93, v161
	v_pk_mul_f32 v[42:43], v[42:43], v[72:73]
	v_lshl_add_u64 v[66:67], v[66:67], 0, v[92:93]
	v_pk_mul_f32 v[42:43], v[42:43], v[70:71]
	global_store_dword v[66:67], v40, off

; template <int MX>
; DI RecRaw rec_load(const Params& p, int b, int h, int dir, int T0, int tid) {
;     ...
;     w.a0 = *(const uint4*)(rp + fcol); w.a1 = *(const uint4*)(rp + fcol + 8);
;     w.b0 = *(const uint4*)(rp + B_Q + h * 64 + k0); w.b1 = *(const uint4*)(rp + B_Q + h * 64 + k0 + 8);
;     w.c0 = *(const uint4*)(rp + B_I + h * 64 + k0); w.c1 = *(const uint4*)(rp + B_I + h * 64 + k0 + 8);
; template <int MX, bool OUT>
; DI void rec_chunk(const Params& p, int l, int b, int h, int dir, int T0, unsigned char* smem, f32x4 (&St)[4], float& nst, float& dtot, int tid, const RecRaw& raw) {
;     ...
;     if (MX == 0) {
; #pragma unroll
;       for (int i = 0; i < 8; ++i) {
; #pragma unroll
;         for (int hh = 0; hh < 2; ++hh) {
;           const int k = 2 * i + hh;
;           float z = __uint_as_float(hh ? (au[i] & 0xffff0000u) : (au[i] << 16));
;           z = fminf(fmaxf(z, -30.f), 30.f);
;           const float e = __expf(-z);
;           const float sg = 1.f / (1.f + e);
;           const float lb = LB[k0 + k];
;           lf[k] = __log2f(lb + (1.f - lb) * sg);
;           kin[k] = (1.f - lb) * (e * sg);
;           qv[k] = __uint_as_float(hh ? (bu[i] & 0xffff0000u) : (bu[i] << 16)) * 0.125f;
;           vv[k] = __uint_as_float(hh ? (cu[i] & 0xffff0000u) : (cu[i] << 16));
;         }
;       }
.LBB0_701:
	v_add_co_u32_e64 v91, s[10:11], s81, 1
	s_and_b64 s[10:11], s[10:11], exec
	s_cselect_b32 s14, 3, s13
	s_cselect_b32 s15, 0, s81
	s_and_b64 s[10:11], s[6:7], exec
	s_cselect_b32 s10, s14, s15
	s_lshl_b32 s10, s10, 6
	s_ashr_i32 s11, s10, 31
	v_lshl_add_u64 v[0:1], v[80:81], 0, s[10:11]
	v_mov_b64_e32 v[2:3], s[20:21]
	v_mad_u64_u32 v[8:9], s[10:11], v0, s33, v[2:3]
	s_waitcnt vmcnt(0) lgkmcnt(0)
	v_lshlrev_b32_e32 v2, 16, v60
	v_max_f32_e32 v2, v2, v2
	v_med3_f32 v2, v2, s17, v190
	v_mul_f32_e32 v2, 0xbfb8aa3b, v2
	v_exp_f32_e32 v206, v2
	v_and_b32_e32 v60, 0xffff0000, v60
	v_max_f32_e32 v60, v60, v60
	v_med3_f32 v60, v60, s17, v190
	v_add_f32_e32 v64, 1.0, v206
	v_mul_f32_e32 v60, 0xbfb8aa3b, v60
	v_exp_f32_e32 v209, v60
	v_rcp_f32_e32 v66, v64
	v_mad_i32_i24 v9, v1, s33, v9
	v_lshl_add_u64 v[0:1], v[8:9], 0, v[160:161]
	v_add_f32_e32 v60, 1.0, v209
	v_fma_f32 v67, -v64, v66, 1.0
	v_fmac_f32_e32 v66, v67, v66
	v_rcp_f32_e32 v100, v60
	v_mul_f32_e32 v68, 1.0, v66
	v_fma_f32 v69, -v64, v68, 1.0
	v_fmac_f32_e32 v68, v69, v66
	v_fma_f32 v65, -v64, v68, 1.0
	v_fma_f32 v101, -v60, v100, 1.0
	v_fma_f32 v65, v65, v66, v68
	v_fmac_f32_e32 v100, v101, v100
	v_mul_f32_e32 v102, 1.0, v100
	v_fma_f32 v103, -v60, v102, 1.0
	v_fmac_f32_e32 v102, v103, v100
	v_fma_f32 v93, -v60, v102, 1.0
	v_lshlrev_b32_e32 v101, 16, v61
	v_max_f32_e32 v101, v101, v101
	v_med3_f32 v101, v101, s17, v190
	v_mul_f32_e32 v101, 0xbfb8aa3b, v101
	v_exp_f32_e32 v205, v101
	v_fma_f32 v93, v93, v100, v102
	v_div_fixup_f32 v212, v93, v60, 1.0
	v_and_b32_e32 v61, 0xffff0000, v61
	v_add_f32_e32 v60, 1.0, v205
	v_rcp_f32_e32 v100, v60
	v_max_f32_e32 v61, v61, v61
	v_med3_f32 v61, v61, s17, v190
	v_mul_f32_e32 v61, 0xbfb8aa3b, v61
	v_fma_f32 v101, -v60, v100, 1.0
	v_fmac_f32_e32 v100, v101, v100
	v_mul_f32_e32 v102, 1.0, v100
	v_fma_f32 v103, -v60, v102, 1.0
	v_exp_f32_e32 v202, v61
	v_fmac_f32_e32 v102, v103, v100
	v_fma_f32 v93, -v60, v102, 1.0
	v_fma_f32 v61, v93, v100, v102
	v_div_fixup_f32 v207, v61, v60, 1.0
	v_add_f32_e32 v60, 1.0, v202
	v_rcp_f32_e32 v93, v60
	v_lshl_add_u64 v[8:9], v[8:9], 0, s[26:27]
	v_lshl_add_u64 v[8:9], v[8:9], 0, v[94:95]
	global_load_dwordx4 v[4:7], v[0:1], off
	s_nop 0
	global_load_dwordx4 v[0:3], v[0:1], off offset:16
	v_fma_f32 v100, -v60, v93, 1.0
	v_fmac_f32_e32 v93, v100, v93
	v_mul_f32_e32 v101, 1.0, v93
	v_fma_f32 v102, -v60, v101, 1.0
	v_fmac_f32_e32 v101, v102, v93
	v_fma_f32 v61, -v60, v101, 1.0
	v_lshlrev_b32_e32 v100, 16, v62
	v_max_f32_e32 v100, v100, v100
	v_med3_f32 v100, v100, s17, v190
	v_mul_f32_e32 v100, 0xbfb8aa3b, v100
	v_exp_f32_e32 v199, v100
	v_fma_f32 v61, v61, v93, v101
	v_div_fixup_f32 v203, v61, v60, 1.0
	v_and_b32_e32 v62, 0xffff0000, v62
	v_add_f32_e32 v60, 1.0, v199
	v_rcp_f32_e32 v93, v60
	v_max_f32_e32 v62, v62, v62
	v_med3_f32 v62, v62, s17, v190
	v_mul_f32_e32 v62, 0xbfb8aa3b, v62
	v_fma_f32 v100, -v60, v93, 1.0
	v_fmac_f32_e32 v93, v100, v93
	v_mul_f32_e32 v101, 1.0, v93
	v_fma_f32 v102, -v60, v101, 1.0
	v_exp_f32_e32 v115, v62
	v_fmac_f32_e32 v101, v102, v93
	v_fma_f32 v61, -v60, v101, 1.0
	v_fma_f32 v61, v61, v93, v101
	v_div_fixup_f32 v200, v61, v60, 1.0
	v_add_f32_e32 v61, 1.0, v115
	global_load_dwordx4 v[20:23], v[8:9], off offset:1536
	global_load_dwordx4 v[16:19], v[8:9], off offset:1552
	global_load_dwordx4 v[12:15], v[8:9], off offset:3072
	s_nop 0
	global_load_dwordx4 v[8:11], v[8:9], off offset:3088
	v_div_fixup_f32 v210, v65, v64, 1.0
	ds_read_b128 v[68:71], v79
	ds_read_b128 v[96:99], v79 offset:16
	ds_read_b128 v[72:75], v79 offset:32
	ds_read_b128 v[64:67], v79 offset:48
	v_rcp_f32_e32 v93, v61
	s_waitcnt lgkmcnt(0)
	v_sub_f32_e32 v211, 1.0, v68
	v_sub_f32_e32 v201, 1.0, v96
	v_fma_f32 v60, v200, v201, v96
	v_fma_f32 v96, -v61, v93, 1.0
	v_fmac_f32_e32 v93, v96, v93
	v_mul_f32_e32 v100, 1.0, v93
	v_fma_f32 v101, -v61, v100, 1.0
	v_fmac_f32_e32 v100, v101, v93
	v_fma_f32 v62, -v61, v100, 1.0
	v_lshlrev_b32_e32 v96, 16, v63
	v_max_f32_e32 v96, v96, v96
	v_med3_f32 v96, v96, s17, v190
	v_mul_f32_e32 v96, 0xbfb8aa3b, v96
	v_exp_f32_e32 v112, v96
	v_fma_f32 v62, v62, v93, v100
	v_div_fixup_f32 v116, v62, v61, 1.0
	v_sub_f32_e32 v117, 1.0, v97
	v_add_f32_e32 v62, 1.0, v112
	v_rcp_f32_e32 v96, v62
	v_and_b32_e32 v63, 0xffff0000, v63
	v_fma_f32 v61, v116, v117, v97
	v_max_f32_e32 v63, v63, v63
	v_fma_f32 v97, -v62, v96, 1.0
	v_fmac_f32_e32 v96, v97, v96
	v_med3_f32 v63, v63, s17, v190
	v_mul_f32_e32 v100, 1.0, v96
	v_mul_f32_e32 v63, 0xbfb8aa3b, v63
	v_fma_f32 v101, -v62, v100, 1.0
	v_exp_f32_e32 v109, v63
	v_fmac_f32_e32 v100, v101, v96
	v_fma_f32 v93, -v62, v100, 1.0
	v_fma_f32 v63, v93, v96, v100
	v_div_fixup_f32 v113, v63, v62, 1.0
	v_add_f32_e32 v63, 1.0, v109
	v_rcp_f32_e32 v96, v63
	v_sub_f32_e32 v114, 1.0, v98
	v_fma_f32 v62, v113, v114, v98
	v_sub_f32_e32 v111, 1.0, v99
	v_fma_f32 v97, -v63, v96, 1.0
	v_fmac_f32_e32 v96, v97, v96
	v_mul_f32_e32 v98, 1.0, v96
	v_fma_f32 v100, -v63, v98, 1.0
	v_fmac_f32_e32 v98, v100, v96
	v_fma_f32 v93, -v63, v98, 1.0
	v_lshlrev_b32_e32 v97, 16, v56
	v_max_f32_e32 v97, v97, v97
	v_med3_f32 v97, v97, s17, v190
	v_mul_f32_e32 v97, 0xbfb8aa3b, v97
	v_exp_f32_e32 v106, v97
	v_fma_f32 v93, v93, v96, v98
	v_div_fixup_f32 v110, v93, v63, 1.0
	v_and_b32_e32 v56, 0xffff0000, v56
	v_add_f32_e32 v93, 1.0, v106
	v_rcp_f32_e32 v97, v93
	v_max_f32_e32 v56, v56, v56
	v_fmac_f32_e32 v99, v110, v111
	v_med3_f32 v56, v56, s17, v190
	v_fma_f32 v98, -v93, v97, 1.0
	v_fmac_f32_e32 v97, v98, v97
	v_log_f32_e32 v63, v99
	v_mul_f32_e32 v99, 1.0, v97
	v_mul_f32_e32 v56, 0xbfb8aa3b, v56
	v_fma_f32 v100, -v93, v99, 1.0
	v_exp_f32_e32 v103, v56
; template <int MX, bool OUT>
; DI void rec_chunk(const Params& p, int l, int b, int h, int dir, int T0, unsigned char* smem, f32x4 (&St)[4], float& nst, float& dtot, int tid, const RecRaw& raw) {
;     ...
;           float z = __uint_as_float(hh ? (au[i] & 0xffff0000u) : (au[i] << 16));
;           z = fminf(fmaxf(z, -30.f), 30.f);
;           const float e = __expf(-z);
;           const float sg = 1.f / (1.f + e);
;           const float lb = LB[k0 + k];
;           lf[k] = __log2f(lb + (1.f - lb) * sg);
;           kin[k] = (1.f - lb) * (e * sg);
;           qv[k] = __uint_as_float(hh ? (bu[i] & 0xffff0000u) : (bu[i] << 16)) * 0.125f;
;           vv[k] = __uint_as_float(hh ? (cu[i] & 0xffff0000u) : (cu[i] << 16));
;         }
;       }
;     } else {
;       const float ig = raw.ig, fg = raw.fg;
;       const float lfs = (fg < -20.f) ? fg * 1.4426950408889634f : -__log2f(1.f + __expf(-fg));
;       const float ei = __expf(ig) * 0.125f;
; #pragma unroll
;       for (int i = 0; i < 8; ++i) {
; #pragma unroll
;         for (int hh = 0; hh < 2; ++hh) {
;           const int k = 2 * i + hh;
;           lf[k] = lfs;
;           kin[k] = __uint_as_float(hh ? (au[i] & 0xffff0000u) : (au[i] << 16)) * ei;
;           qv[k] = __uint_as_float(hh ? (bu[i] & 0xffff0000u) : (bu[i] << 16));
;           vv[k] = __uint_as_float(hh ? (cu[i] & 0xffff0000u) : (cu[i] << 16));
;         }
;       }
;     }
; #pragma unroll
;     for (int i = 0; i < 4; ++i) { if (MX == 0) *(float4*)(CUM + tt * 64 + k0 + 4 * i) = make_float4(lf[4 * i], lf[4 * i + 1], lf[4 * i + 2], lf[4 * i + 3]); }
;     if (MX == 1 && grp == 0) CUM[tt * 64] = lf[0];
;   }
;   __syncthreads();
;   if (MX == 1) {
;     if (w == 0) {
;       float x = CUM[lane * 64];
; #pragma unroll
;       for (int o = 1; o < 64; o <<= 1) {
;         const float y = dir == 0 ? __shfl_up(x, o) : __shfl_down(x, o);
;         const bool ok = dir == 0 ? (lane >= o) : (lane + o < 64);
;         x += ok ? y : 0.f;
;       }
;       CUM[lane * 64] = x;
;     }
;     __syncthreads();
;   } else {
;     const int k = tid & 63, part = tid >> 6;
;     float x[16];
;     float acc = 0.f;
;     if (dir == 0) {
; #pragma unroll
;       for (int i = 0; i < 16; ++i) { acc += CUM[(part * 16 + i) * 64 + k]; x[i] = acc; }
;     } else {
; #pragma unroll
;       for (int i = 15; i >= 0; --i) { acc += CUM[(part * 16 + i) * 64 + k]; x[i] = acc; }
;     }
	v_fmac_f32_e32 v99, v100, v97
	v_fma_f32 v96, -v93, v99, 1.0
	v_fma_f32 v56, v96, v97, v99
	v_div_fixup_f32 v107, v56, v93, 1.0
	v_add_f32_e32 v56, 1.0, v103
	v_rcp_f32_e32 v96, v56
	v_sub_f32_e32 v108, 1.0, v72
	v_fma_f32 v72, v107, v108, v72
	v_log_f32_e32 v214, v72
	v_fma_f32 v72, -v56, v96, 1.0
	v_fmac_f32_e32 v96, v72, v96
	v_mul_f32_e32 v97, 1.0, v96
	v_fma_f32 v98, -v56, v97, 1.0
	v_fmac_f32_e32 v97, v98, v96
	v_fma_f32 v72, -v56, v97, 1.0
	v_lshlrev_b32_e32 v93, 16, v57
	v_max_f32_e32 v93, v93, v93
	v_med3_f32 v93, v93, s17, v190
	v_mul_f32_e32 v93, 0xbfb8aa3b, v93
	v_exp_f32_e32 v100, v93
	v_fma_f32 v72, v72, v96, v97
	v_div_fixup_f32 v104, v72, v56, 1.0
	v_sub_f32_e32 v105, 1.0, v73
	v_add_f32_e32 v56, 1.0, v100
	v_rcp_f32_e32 v93, v56
	v_fma_f32 v73, v104, v105, v73
	v_log_f32_e32 v215, v73
	v_and_b32_e32 v57, 0xffff0000, v57
	v_fma_f32 v73, -v56, v93, 1.0
	v_fmac_f32_e32 v93, v73, v93
	v_max_f32_e32 v57, v57, v57
	v_mul_f32_e32 v96, 1.0, v93
	v_med3_f32 v57, v57, s17, v190
	v_fma_f32 v97, -v56, v96, 1.0
	v_mul_f32_e32 v57, 0xbfb8aa3b, v57
	v_fmac_f32_e32 v96, v97, v93
	v_exp_f32_e32 v97, v57
	v_fma_f32 v72, -v56, v96, 1.0
	v_fma_f32 v57, v72, v93, v96
	v_div_fixup_f32 v101, v57, v56, 1.0
	v_add_f32_e32 v56, 1.0, v97
	v_rcp_f32_e32 v72, v56
	v_sub_f32_e32 v102, 1.0, v74
	v_fma_f32 v73, v101, v102, v74
	v_log_f32_e32 v216, v73
	v_fma_f32 v73, -v56, v72, 1.0
	v_fmac_f32_e32 v72, v73, v72
	v_mul_f32_e32 v74, 1.0, v72
	v_fma_f32 v93, -v56, v74, 1.0
	v_fmac_f32_e32 v74, v93, v72
	v_fma_f32 v57, -v56, v74, 1.0
	v_lshlrev_b32_e32 v73, 16, v58
	v_max_f32_e32 v73, v73, v73
	v_med3_f32 v73, v73, s17, v190
	v_mul_f32_e32 v73, 0xbfb8aa3b, v73
	v_exp_f32_e32 v93, v73
	v_fma_f32 v57, v57, v72, v74
	v_div_fixup_f32 v98, v57, v56, 1.0
	v_sub_f32_e32 v99, 1.0, v75
	v_add_f32_e32 v56, 1.0, v93
	v_rcp_f32_e32 v73, v56
	v_and_b32_e32 v58, 0xffff0000, v58
	v_fmac_f32_e32 v75, v98, v99
	v_max_f32_e32 v58, v58, v58
	v_fma_f32 v72, -v56, v73, 1.0
	v_fmac_f32_e32 v73, v72, v73
	v_mul_f32_e32 v74, 1.0, v73
	v_log_f32_e32 v217, v75
	v_fma_f32 v75, -v56, v74, 1.0
	v_med3_f32 v58, v58, s17, v190
	v_fmac_f32_e32 v74, v75, v73
	v_mul_f32_e32 v58, 0xbfb8aa3b, v58
	v_fma_f32 v57, -v56, v74, 1.0
	v_exp_f32_e32 v72, v58
	v_fma_f32 v57, v57, v73, v74
	v_div_fixup_f32 v75, v57, v56, 1.0
	v_sub_f32_e32 v96, 1.0, v64
	v_add_f32_e32 v56, 1.0, v72
	v_rcp_f32_e32 v58, v56
	v_fma_f32 v64, v75, v96, v64
	v_log_f32_e32 v218, v64
	v_sub_f32_e32 v213, 1.0, v69
	v_fma_f32 v64, -v56, v58, 1.0
	v_fmac_f32_e32 v58, v64, v58
	v_mul_f32_e32 v73, 1.0, v58
	v_fma_f32 v74, -v56, v73, 1.0
	v_fmac_f32_e32 v73, v74, v58
	v_fma_f32 v57, -v56, v73, 1.0
	v_lshlrev_b32_e32 v64, 16, v59
	v_max_f32_e32 v64, v64, v64
	v_med3_f32 v64, v64, s17, v190
	v_mul_f32_e32 v64, 0xbfb8aa3b, v64
	v_exp_f32_e32 v64, v64
	v_fma_f32 v57, v57, v58, v73
	v_div_fixup_f32 v73, v57, v56, 1.0
	v_sub_f32_e32 v74, 1.0, v65
	v_add_f32_e32 v57, 1.0, v64
	v_rcp_f32_e32 v58, v57
	v_fma_f32 v65, v73, v74, v65
	v_log_f32_e32 v219, v65
	v_sub_f32_e32 v208, 1.0, v70
	v_fma_f32 v65, -v57, v58, 1.0
	v_fmac_f32_e32 v58, v65, v58
	v_mul_f32_e32 v220, 1.0, v58
	v_fma_f32 v221, -v57, v220, 1.0
	v_fmac_f32_e32 v220, v221, v58
	v_fma_f32 v65, -v57, v220, 1.0
	v_and_b32_e32 v56, 0xffff0000, v59
	v_max_f32_e32 v56, v56, v56
	v_med3_f32 v56, v56, s17, v190
	v_mul_f32_e32 v56, 0xbfb8aa3b, v56
	v_exp_f32_e32 v56, v56
	v_fma_f32 v58, v65, v58, v220
	v_div_fixup_f32 v59, v58, v57, 1.0
	v_sub_f32_e32 v65, 1.0, v66
	v_add_f32_e32 v57, 1.0, v56
	v_rcp_f32_e32 v221, v57
	v_fma_f32 v66, v59, v65, v66
	v_log_f32_e32 v220, v66
	v_sub_f32_e32 v204, 1.0, v71
	v_fma_f32 v66, -v57, v221, 1.0
	v_fmac_f32_e32 v221, v66, v221
	v_mul_f32_e32 v222, 1.0, v221
	v_fma_f32 v223, -v57, v222, 1.0
	v_fmac_f32_e32 v222, v223, v221
	v_fma_f32 v68, v210, v211, v68
	v_fma_f32 v69, v212, v213, v69
	v_fma_f32 v70, v207, v208, v70
	v_fmac_f32_e32 v71, v203, v204
	v_fma_f32 v58, -v57, v222, 1.0
	v_log_f32_e32 v68, v68
	v_log_f32_e32 v69, v69
	v_log_f32_e32 v70, v70
	v_log_f32_e32 v71, v71
	v_fma_f32 v58, v58, v221, v222
	v_log_f32_e32 v60, v60
	v_log_f32_e32 v61, v61
	v_log_f32_e32 v62, v62
	v_div_fixup_f32 v57, v58, v57, 1.0
	v_sub_f32_e32 v58, 1.0, v67
	v_fmac_f32_e32 v67, v57, v58
	v_log_f32_e32 v221, v67
	ds_write_b128 v118, v[68:71]
	ds_write_b128 v118, v[60:63] offset:16
	ds_write_b128 v118, v[214:217] offset:32
	ds_write_b128 v118, v[218:221] offset:48
	v_cndmask_b32_e64 v60, 0, 1, s[8:9]
	v_cmp_ne_u32_e64 s[78:79], 1, v60
	s_andn2_b64 vcc, exec, s[8:9]
	s_mov_b64 s[10:11], -1
	s_waitcnt lgkmcnt(0)
	s_barrier
	s_cbranch_vccnz .LBB0_703
	ds_read2st64_b32 v[60:61], v119 offset0:14 offset1:15
	ds_read2st64_b32 v[214:215], v119 offset0:6 offset1:7
	ds_read2st64_b32 v[216:217], v119 offset0:4 offset1:5
	ds_read2st64_b32 v[218:219], v119 offset0:2 offset1:3
	ds_read2st64_b32 v[220:221], v119 offset1:1
	s_waitcnt lgkmcnt(0)
	v_add_f32_e32 v70, 0, v61
	v_add_f32_e32 v71, v70, v60
	ds_read2st64_b32 v[60:61], v119 offset0:12 offset1:13
	s_mov_b64 s[10:11], 0
	ds_read2st64_b32 v[62:63], v119 offset0:8 offset1:9
	s_waitcnt lgkmcnt(0)
	v_add_f32_e32 v66, v71, v61
	v_add_f32_e32 v67, v66, v60
	ds_read2st64_b32 v[60:61], v119 offset0:10 offset1:11
	s_waitcnt lgkmcnt(0)
	v_add_f32_e32 v68, v67, v61
	v_add_f32_e32 v69, v68, v60
	v_add_f32_e32 v60, v69, v63
	v_add_f32_e32 v61, v60, v62
	v_add_f32_e32 v62, v61, v215
	v_add_f32_e32 v63, v62, v214
	v_add_f32_e32 v214, v63, v217
	v_add_f32_e32 v215, v214, v216
	v_add_f32_e32 v216, v215, v219
	v_add_f32_e32 v217, v216, v218
	v_add_f32_e32 v218, v217, v221
	v_add_f32_e32 v219, v218, v220

; DI size_t kblk(int row, int col, int nrows) { return ((size_t)(col >> 5) * nrows + row) * 32 + (col & 31); }
; DI float bf2f(bf16_t v) { return __uint_as_float(((unsigned)v) << 16); }
; DI unsigned pk2(float a, float b) { hwf32x2 f = {a, b}; hwbf16x2 r = __builtin_convertvector(f, hwbf16x2); return __builtin_bit_cast(unsigned, r); }
; DI float siluf_(float z) { return z / (1.f + __expf(-z)); }
; template <int MODE>
; DI void attn_mfma(const Params& p, int l, int b, int hd, int qb, unsigned char* smem) {
;     ...
;     const float i0 = 1.f / ltot;
; #pragma unroll
;     for (int vt = 0; vt < 2; ++vt)
; #pragma unroll
;       for (int g4 = 0; g4 < 4; ++g4) {
;         const int v0 = vt * 32 + 8 * g4 + 4 * h2;
;         const ushort4 gt = *(const ushort4*)(P + qrow * PW + GATE + 512 + hd * 64 + v0);
;         uint2 o;
;         o.x = pk2(O[vt][4 * g4 + 0] * i0 * siluf_(bf2f(gt.x)), O[vt][4 * g4 + 1] * i0 * siluf_(bf2f(gt.y)));
;         o.y = pk2(O[vt][4 * g4 + 2] * i0 * siluf_(bf2f(gt.z)), O[vt][4 * g4 + 3] * i0 * siluf_(bf2f(gt.w)));
;         *(uint2*)(MIX + kblk((int)qrow, 512 + hd * 64 + v0, ROWS)) = o;
;       }
.LBB0_829:
	v_cmp_lt_i32_e32 vcc, v33, v34
	s_add_u32 s0, s14, 0x1dc6000
	s_addc_u32 s1, s15, 0
	v_cndmask_b32_e32 v32, v32, v33, vcc
	v_lshlrev_b32_e32 v32, 2, v32
	ds_bpermute_b32 v32, v32, v200
	s_lshl_b32 s2, s11, 1
	v_ashrrev_i32_e32 v145, 31, v144
	v_mov_b32_e32 v153, v161
	v_lshlrev_b64 v[38:39], 1, v[152:153]
	s_waitcnt lgkmcnt(0)
	v_add_f32_e32 v32, v200, v32
	v_div_scale_f32 v33, s[4:5], v32, v32, 1.0
	v_rcp_f32_e32 v34, v33
	s_mov_b64 s[4:5], 0x1e20
	v_mov_b32_e32 v151, v161
	v_mov_b32_e32 v149, v161
	v_fma_f32 v35, -v33, v34, 1.0
	v_fmac_f32_e32 v34, v35, v34
	v_div_scale_f32 v35, vcc, 1.0, v32, 1.0
	v_mul_f32_e32 v36, v35, v34
	v_fma_f32 v37, -v33, v36, v35
	v_fmac_f32_e32 v36, v37, v34
	v_fma_f32 v33, -v33, v36, v35
	v_div_fmas_f32 v33, v33, v34, v36
	v_lshl_add_u64 v[34:35], v[154:155], 0, s[2:3]
	v_lshl_add_u64 v[42:43], v[34:35], 0, s[4:5]
	s_mul_i32 s4, s10, 0x9000
	s_add_i32 s2, s4, 0x48000
	v_lshl_add_u64 v[34:35], v[144:145], 0, s[2:3]
	v_lshlrev_b64 v[34:35], 6, v[34:35]
	v_lshl_add_u64 v[40:41], s[0:1], 0, v[34:35]
	v_lshl_add_u64 v[34:35], v[42:43], 0, v[38:39]
	global_load_dwordx2 v[204:205], v[34:35], off
	global_load_dwordx2 v[206:207], v[34:35], off offset:16
	global_load_dwordx2 v[208:209], v[34:35], off offset:32
	global_load_dwordx2 v[210:211], v[34:35], off offset:48
	global_load_dwordx2 v[212:213], v[34:35], off offset:64
	global_load_dwordx2 v[214:215], v[34:35], off offset:80
	global_load_dwordx2 v[216:217], v[34:35], off offset:96
	global_load_dwordx2 v[218:219], v[34:35], off offset:112
	s_nop 0
	v_div_fixup_f32 v32, v33, v32, 1.0
	v_mov_b32_e32 v147, v161
	s_add_i32 s2, s4, 0x4c800
	s_waitcnt vmcnt(0) lgkmcnt(0)
	v_mov_b32_e32 v36, v204
	v_mov_b32_e32 v37, v205
	v_and_b32_e32 v33, 0xffff0000, v36
	v_lshlrev_b32_e32 v36, 16, v36
	v_mul_f32_e32 v44, 0xbfb8aa3b, v36
	v_mul_f32_e32 v45, 0xbfb8aa3b, v33
	v_exp_f32_e32 v44, v44
	v_exp_f32_e32 v45, v45
	v_pk_mul_f32 v[16:17], v[16:17], v[32:33] op_sel_hi:[1,0]
	v_pk_add_f32 v[44:45], v[44:45], 1.0 op_sel_hi:[1,0]
	s_nop 0
	v_rcp_f32_e32 v47, v45
	s_nop 0
	v_fma_f32 v48, -v45, v47, 1.0
	v_fmac_f32_e32 v47, v48, v47
	v_mul_f32_e32 v49, v33, v47
	v_fma_f32 v50, -v45, v49, v33
	v_fmac_f32_e32 v49, v50, v47
	v_fma_f32 v46, -v45, v49, v33
	v_fma_f32 v46, v46, v47, v49
	v_div_fixup_f32 v45, v46, v45, v33
	v_rcp_f32_e32 v46, v44
	s_nop 0
	v_fma_f32 v47, -v44, v46, 1.0
	v_fmac_f32_e32 v46, v47, v46
	v_mul_f32_e32 v48, v36, v46
	v_fma_f32 v49, -v44, v48, v36
	v_fmac_f32_e32 v48, v49, v46
	v_fma_f32 v33, -v44, v48, v36
	v_fma_f32 v33, v33, v46, v48
	v_div_fixup_f32 v44, v33, v44, v36
	v_pk_mul_f32 v[16:17], v[16:17], v[44:45]
	v_lshlrev_b32_e32 v33, 16, v37
	v_cvt_pk_bf16_f32 v16, v16, v17
	v_and_b32_e32 v17, 0xffff0000, v37
	v_mul_f32_e32 v36, 0xbfb8aa3b, v33
	v_mul_f32_e32 v37, 0xbfb8aa3b, v17
	v_exp_f32_e32 v36, v36
	v_exp_f32_e32 v37, v37
	v_pk_mul_f32 v[18:19], v[18:19], v[32:33] op_sel_hi:[1,0]
	v_pk_add_f32 v[36:37], v[36:37], 1.0 op_sel_hi:[1,0]
	s_nop 0
	v_rcp_f32_e32 v45, v37
	s_nop 0
	v_fma_f32 v46, -v37, v45, 1.0
	v_fmac_f32_e32 v45, v46, v45
	v_mul_f32_e32 v47, v17, v45
	v_fma_f32 v48, -v37, v47, v17
	v_fmac_f32_e32 v47, v48, v45
	v_fma_f32 v44, -v37, v47, v17
	v_fma_f32 v44, v44, v45, v47
	v_div_fixup_f32 v37, v44, v37, v17
	v_rcp_f32_e32 v44, v36
	s_nop 0
	v_fma_f32 v45, -v36, v44, 1.0
	v_fmac_f32_e32 v44, v45, v44
	v_mul_f32_e32 v46, v33, v44
	v_fma_f32 v47, -v36, v46, v33
	v_fmac_f32_e32 v46, v47, v44
	v_fma_f32 v17, -v36, v46, v33
	v_fma_f32 v17, v17, v44, v46
	v_div_fixup_f32 v36, v17, v36, v33
	v_pk_mul_f32 v[18:19], v[18:19], v[36:37]
	v_lshlrev_b64 v[36:37], 1, v[150:151]
	v_cvt_pk_bf16_f32 v17, v18, v19
	v_lshl_add_u64 v[18:19], v[40:41], 0, v[38:39]
	global_store_dwordx2 v[18:19], v[16:17], off
	v_lshl_add_u64 v[16:17], v[42:43], 0, v[36:37]
	s_nop 0
	s_waitcnt lgkmcnt(0)
	v_mov_b32_e32 v16, v206
	v_mov_b32_e32 v17, v207
	v_and_b32_e32 v33, 0xffff0000, v16
	v_lshlrev_b32_e32 v16, 16, v16
	v_mul_f32_e32 v18, 0xbfb8aa3b, v16
	v_mul_f32_e32 v19, 0xbfb8aa3b, v33
	v_exp_f32_e32 v18, v18
	v_exp_f32_e32 v19, v19
	v_pk_mul_f32 v[20:21], v[20:21], v[32:33] op_sel_hi:[1,0]
	v_pk_add_f32 v[18:19], v[18:19], 1.0 op_sel_hi:[1,0]
	s_nop 0
	v_rcp_f32_e32 v45, v19
	s_nop 0
	v_fma_f32 v46, -v19, v45, 1.0
	v_fmac_f32_e32 v45, v46, v45
	v_mul_f32_e32 v47, v33, v45
	v_fma_f32 v48, -v19, v47, v33
	v_fmac_f32_e32 v47, v48, v45
	v_fma_f32 v44, -v19, v47, v33
	v_fma_f32 v44, v44, v45, v47
	v_div_fixup_f32 v19, v44, v19, v33
	v_rcp_f32_e32 v44, v18
	s_nop 0
	v_fma_f32 v45, -v18, v44, 1.0
	v_fmac_f32_e32 v44, v45, v44
	v_mul_f32_e32 v46, v16, v44
	v_fma_f32 v47, -v18, v46, v16
	v_fmac_f32_e32 v46, v47, v44
	v_fma_f32 v33, -v18, v46, v16
	v_fma_f32 v33, v33, v44, v46
	v_div_fixup_f32 v18, v33, v18, v16
	v_pk_mul_f32 v[18:19], v[20:21], v[18:19]
	v_and_b32_e32 v33, 0xffff0000, v17
	v_lshlrev_b32_e32 v17, 16, v17
	v_cvt_pk_bf16_f32 v16, v18, v19
	v_mul_f32_e32 v18, 0xbfb8aa3b, v17
	v_mul_f32_e32 v19, 0xbfb8aa3b, v33
	v_exp_f32_e32 v18, v18
	v_exp_f32_e32 v19, v19
	v_pk_mul_f32 v[20:21], v[22:23], v[32:33] op_sel_hi:[1,0]
	v_pk_add_f32 v[18:19], v[18:19], 1.0 op_sel_hi:[1,0]
	s_nop 0
	v_rcp_f32_e32 v23, v19
	s_nop 0
	v_fma_f32 v44, -v19, v23, 1.0
	v_fmac_f32_e32 v23, v44, v23
	v_mul_f32_e32 v45, v33, v23
	v_fma_f32 v46, -v19, v45, v33
	v_fmac_f32_e32 v45, v46, v23
	v_fma_f32 v22, -v19, v45, v33
	v_fma_f32 v22, v22, v23, v45
	v_div_fixup_f32 v19, v22, v19, v33
	v_rcp_f32_e32 v23, v18
	s_nop 0
	v_fma_f32 v33, -v18, v23, 1.0
	v_fmac_f32_e32 v23, v33, v23
	v_mul_f32_e32 v44, v17, v23
	v_fma_f32 v45, -v18, v44, v17
	v_fmac_f32_e32 v44, v45, v23
	v_fma_f32 v22, -v18, v44, v17
	v_fma_f32 v22, v22, v23, v44
	v_div_fixup_f32 v18, v22, v18, v17
	v_pk_mul_f32 v[18:19], v[20:21], v[18:19]
	s_nop 0
	v_cvt_pk_bf16_f32 v17, v18, v19
	v_lshl_add_u64 v[18:19], v[40:41], 0, v[36:37]
	global_store_dwordx2 v[18:19], v[16:17], off
	v_lshlrev_b64 v[18:19], 1, v[148:149]
	v_lshl_add_u64 v[16:17], v[42:43], 0, v[18:19]
	s_nop 0
	s_waitcnt lgkmcnt(0)
; DI size_t kblk(int row, int col, int nrows) { return ((size_t)(col >> 5) * nrows + row) * 32 + (col & 31); }
; DI float bf2f(bf16_t v) { return __uint_as_float(((unsigned)v) << 16); }
; DI unsigned pk2(float a, float b) { hwf32x2 f = {a, b}; hwbf16x2 r = __builtin_convertvector(f, hwbf16x2); return __builtin_bit_cast(unsigned, r); }
; DI float siluf_(float z) { return z / (1.f + __expf(-z)); }
; template <int MODE>
; DI void attn_mfma(const Params& p, int l, int b, int hd, int qb, unsigned char* smem) {
;     ...
;     const float i0 = 1.f / ltot;
; #pragma unroll
;     for (int vt = 0; vt < 2; ++vt)
; #pragma unroll
;       for (int g4 = 0; g4 < 4; ++g4) {
;         const int v0 = vt * 32 + 8 * g4 + 4 * h2;
;         const ushort4 gt = *(const ushort4*)(P + qrow * PW + GATE + 512 + hd * 64 + v0);
;         uint2 o;
;         o.x = pk2(O[vt][4 * g4 + 0] * i0 * siluf_(bf2f(gt.x)), O[vt][4 * g4 + 1] * i0 * siluf_(bf2f(gt.y)));
;         o.y = pk2(O[vt][4 * g4 + 2] * i0 * siluf_(bf2f(gt.z)), O[vt][4 * g4 + 3] * i0 * siluf_(bf2f(gt.w)));
;         *(uint2*)(MIX + kblk((int)qrow, 512 + hd * 64 + v0, ROWS)) = o;
;       }
	v_mov_b32_e32 v16, v208
	v_mov_b32_e32 v17, v209
	v_and_b32_e32 v33, 0xffff0000, v16
	v_lshlrev_b32_e32 v16, 16, v16
	v_mul_f32_e32 v20, 0xbfb8aa3b, v16
	v_mul_f32_e32 v21, 0xbfb8aa3b, v33
	v_exp_f32_e32 v20, v20
	v_exp_f32_e32 v21, v21
	v_pk_mul_f32 v[22:23], v[24:25], v[32:33] op_sel_hi:[1,0]
	v_pk_add_f32 v[20:21], v[20:21], 1.0 op_sel_hi:[1,0]
	s_nop 0
	v_rcp_f32_e32 v25, v21
	s_nop 0
	v_fma_f32 v44, -v21, v25, 1.0
	v_fmac_f32_e32 v25, v44, v25
	v_mul_f32_e32 v45, v33, v25
	v_fma_f32 v46, -v21, v45, v33
	v_fmac_f32_e32 v45, v46, v25
	v_fma_f32 v24, -v21, v45, v33
	v_fma_f32 v24, v24, v25, v45
	v_div_fixup_f32 v21, v24, v21, v33
	v_rcp_f32_e32 v25, v20
	s_nop 0
	v_fma_f32 v33, -v20, v25, 1.0
	v_fmac_f32_e32 v25, v33, v25
	v_mul_f32_e32 v44, v16, v25
	v_fma_f32 v45, -v20, v44, v16
	v_fmac_f32_e32 v44, v45, v25
	v_fma_f32 v24, -v20, v44, v16
	v_fma_f32 v24, v24, v25, v44
	v_div_fixup_f32 v20, v24, v20, v16
	v_pk_mul_f32 v[20:21], v[22:23], v[20:21]
	v_and_b32_e32 v24, 0xffff0000, v17
	v_lshlrev_b32_e32 v17, 16, v17
	v_cvt_pk_bf16_f32 v16, v20, v21
	v_mul_f32_e32 v20, 0xbfb8aa3b, v17
	v_mul_f32_e32 v21, 0xbfb8aa3b, v24
	v_exp_f32_e32 v20, v20
	v_exp_f32_e32 v21, v21
	v_pk_mul_f32 v[22:23], v[26:27], v[32:33] op_sel_hi:[1,0]
	v_pk_add_f32 v[20:21], v[20:21], 1.0 op_sel_hi:[1,0]
	s_nop 0
	v_rcp_f32_e32 v26, v21
	s_nop 0
	v_fma_f32 v27, -v21, v26, 1.0
	v_fmac_f32_e32 v26, v27, v26
	v_mul_f32_e32 v33, v24, v26
	v_fma_f32 v44, -v21, v33, v24
	v_fmac_f32_e32 v33, v44, v26
	v_fma_f32 v25, -v21, v33, v24
	v_fma_f32 v25, v25, v26, v33
	v_div_fixup_f32 v21, v25, v21, v24
	v_rcp_f32_e32 v25, v20
	s_nop 0
	v_fma_f32 v26, -v20, v25, 1.0
	v_fmac_f32_e32 v25, v26, v25
	v_mul_f32_e32 v27, v17, v25
	v_fma_f32 v33, -v20, v27, v17
	v_fmac_f32_e32 v27, v33, v25
	v_fma_f32 v24, -v20, v27, v17
	v_fma_f32 v24, v24, v25, v27
	v_div_fixup_f32 v20, v24, v20, v17
	v_pk_mul_f32 v[20:21], v[22:23], v[20:21]
	v_pk_mul_f32 v[24:25], v[28:29], v[32:33] op_sel_hi:[1,0]
	v_cvt_pk_bf16_f32 v17, v20, v21
	v_lshl_add_u64 v[20:21], v[40:41], 0, v[18:19]
	global_store_dwordx2 v[20:21], v[16:17], off
	v_lshlrev_b64 v[16:17], 1, v[146:147]
	v_lshl_add_u64 v[20:21], v[42:43], 0, v[16:17]
	s_nop 0
	s_waitcnt lgkmcnt(0)
	v_mov_b32_e32 v20, v210
	v_mov_b32_e32 v21, v211
	v_and_b32_e32 v26, 0xffff0000, v20
	v_lshlrev_b32_e32 v20, 16, v20
	v_mul_f32_e32 v22, 0xbfb8aa3b, v20
	v_mul_f32_e32 v23, 0xbfb8aa3b, v26
	v_exp_f32_e32 v22, v22
	v_exp_f32_e32 v23, v23
	s_nop 0
	v_pk_add_f32 v[22:23], v[22:23], 1.0 op_sel_hi:[1,0]
	s_nop 0
	v_rcp_f32_e32 v28, v23
	s_nop 0
	v_fma_f32 v29, -v23, v28, 1.0
	v_fmac_f32_e32 v28, v29, v28
	v_mul_f32_e32 v33, v26, v28
	v_fma_f32 v42, -v23, v33, v26
	v_fmac_f32_e32 v33, v42, v28
	v_fma_f32 v27, -v23, v33, v26
	v_fma_f32 v27, v27, v28, v33
	v_div_fixup_f32 v23, v27, v23, v26
	v_rcp_f32_e32 v27, v22
	s_nop 0
	v_fma_f32 v28, -v22, v27, 1.0
	v_fmac_f32_e32 v27, v28, v27
	v_mul_f32_e32 v29, v20, v27
	v_fma_f32 v33, -v22, v29, v20
	v_fmac_f32_e32 v29, v33, v27
	v_fma_f32 v26, -v22, v29, v20
	v_fma_f32 v26, v26, v27, v29
	v_div_fixup_f32 v22, v26, v22, v20
	v_pk_mul_f32 v[22:23], v[24:25], v[22:23]
	v_and_b32_e32 v26, 0xffff0000, v21
	v_lshlrev_b32_e32 v21, 16, v21
	v_cvt_pk_bf16_f32 v20, v22, v23
	v_mul_f32_e32 v22, 0xbfb8aa3b, v21
	v_mul_f32_e32 v23, 0xbfb8aa3b, v26
	v_exp_f32_e32 v22, v22
	v_exp_f32_e32 v23, v23
	v_pk_mul_f32 v[24:25], v[30:31], v[32:33] op_sel_hi:[1,0]
	v_pk_mul_f32 v[0:1], v[0:1], v[32:33] op_sel_hi:[1,0]
	v_pk_mul_f32 v[2:3], v[2:3], v[32:33] op_sel_hi:[1,0]
	v_pk_add_f32 v[22:23], v[22:23], 1.0 op_sel_hi:[1,0]
	v_pk_mul_f32 v[4:5], v[4:5], v[32:33] op_sel_hi:[1,0]
	v_rcp_f32_e32 v28, v23
	s_nop 0
	v_fma_f32 v29, -v23, v28, 1.0
	v_fmac_f32_e32 v28, v29, v28
	v_mul_f32_e32 v30, v26, v28
	v_fma_f32 v31, -v23, v30, v26
	v_fmac_f32_e32 v30, v31, v28
	v_fma_f32 v27, -v23, v30, v26
	v_fma_f32 v27, v27, v28, v30
	v_div_fixup_f32 v23, v27, v23, v26
	v_rcp_f32_e32 v27, v22
	s_nop 0
	v_fma_f32 v28, -v22, v27, 1.0
	v_fmac_f32_e32 v27, v28, v27
	v_mul_f32_e32 v29, v21, v27
	v_fma_f32 v30, -v22, v29, v21
	v_fmac_f32_e32 v29, v30, v27
	v_fma_f32 v26, -v22, v29, v21
	v_fma_f32 v26, v26, v27, v29
	v_div_fixup_f32 v22, v26, v22, v21
	v_pk_mul_f32 v[22:23], v[24:25], v[22:23]
	s_nop 0
	v_cvt_pk_bf16_f32 v21, v22, v23
	v_lshl_add_u64 v[22:23], v[40:41], 0, v[16:17]
	global_store_dwordx2 v[22:23], v[20:21], off
	s_nop 0
	v_lshl_add_u64 v[20:21], v[144:145], 0, s[2:3]
	v_lshlrev_b64 v[20:21], 6, v[20:21]
	v_lshl_add_u64 v[20:21], s[0:1], 0, v[20:21]
	s_waitcnt lgkmcnt(0)
	v_mov_b32_e32 v22, v212
	v_mov_b32_e32 v23, v213
	v_and_b32_e32 v26, 0xffff0000, v22
	v_lshlrev_b32_e32 v22, 16, v22
	v_mul_f32_e32 v24, 0xbfb8aa3b, v22
	v_mul_f32_e32 v25, 0xbfb8aa3b, v26
	v_exp_f32_e32 v24, v24
	v_exp_f32_e32 v25, v25
	s_nop 0
	v_pk_add_f32 v[24:25], v[24:25], 1.0 op_sel_hi:[1,0]
	s_nop 0
	v_rcp_f32_e32 v28, v25
	s_nop 0
	v_fma_f32 v29, -v25, v28, 1.0
	v_fmac_f32_e32 v28, v29, v28
	v_mul_f32_e32 v30, v26, v28
	v_fma_f32 v31, -v25, v30, v26
	v_fmac_f32_e32 v30, v31, v28
	v_fma_f32 v27, -v25, v30, v26
	v_fma_f32 v27, v27, v28, v30
	v_div_fixup_f32 v25, v27, v25, v26
	v_rcp_f32_e32 v27, v24
	s_nop 0
	v_fma_f32 v28, -v24, v27, 1.0
	v_fmac_f32_e32 v27, v28, v27
	v_mul_f32_e32 v29, v22, v27
	v_fma_f32 v30, -v24, v29, v22
	v_fmac_f32_e32 v29, v30, v27
	v_fma_f32 v26, -v24, v29, v22
	v_fma_f32 v26, v26, v27, v29
	v_div_fixup_f32 v24, v26, v24, v22
	v_pk_mul_f32 v[0:1], v[0:1], v[24:25]
	v_lshlrev_b32_e32 v24, 16, v23
	v_cvt_pk_bf16_f32 v0, v0, v1
	v_and_b32_e32 v1, 0xffff0000, v23
	v_mul_f32_e32 v22, 0xbfb8aa3b, v24
	v_mul_f32_e32 v23, 0xbfb8aa3b, v1
	v_exp_f32_e32 v22, v22
	v_exp_f32_e32 v23, v23
	s_nop 0
	v_pk_add_f32 v[22:23], v[22:23], 1.0 op_sel_hi:[1,0]
	s_nop 0
	v_rcp_f32_e32 v26, v23
	s_nop 0
	v_fma_f32 v27, -v23, v26, 1.0
	v_fmac_f32_e32 v26, v27, v26
	v_mul_f32_e32 v28, v1, v26
	v_fma_f32 v29, -v23, v28, v1
	v_fmac_f32_e32 v28, v29, v26
	v_fma_f32 v25, -v23, v28, v1
	v_fma_f32 v25, v25, v26, v28
	v_div_fixup_f32 v23, v25, v23, v1
	v_rcp_f32_e32 v25, v22
	s_nop 0
	v_fma_f32 v26, -v22, v25, 1.0
	v_fmac_f32_e32 v25, v26, v25
	v_mul_f32_e32 v27, v24, v25
	v_fma_f32 v28, -v22, v27, v24
	v_fmac_f32_e32 v27, v28, v25
	v_fma_f32 v1, -v22, v27, v24
	v_fma_f32 v1, v1, v25, v27
	v_div_fixup_f32 v22, v1, v22, v24
	v_pk_mul_f32 v[2:3], v[2:3], v[22:23]
	s_nop 0
	v_cvt_pk_bf16_f32 v1, v2, v3
	v_lshl_add_u64 v[2:3], v[20:21], 0, v[38:39]
	global_store_dwordx2 v[2:3], v[0:1], off
	s_nop 0
	s_waitcnt lgkmcnt(0)
; DI size_t kblk(int row, int col, int nrows) { return ((size_t)(col >> 5) * nrows + row) * 32 + (col & 31); }
; DI float bf2f(bf16_t v) { return __uint_as_float(((unsigned)v) << 16); }
; DI unsigned pk2(float a, float b) { hwf32x2 f = {a, b}; hwbf16x2 r = __builtin_convertvector(f, hwbf16x2); return __builtin_bit_cast(unsigned, r); }
; DI float siluf_(float z) { return z / (1.f + __expf(-z)); }
; template <int MODE>
; DI void attn_mfma(const Params& p, int l, int b, int hd, int qb, unsigned char* smem) {
;     ...
;     const float i0 = 1.f / ltot;
; #pragma unroll
;     for (int vt = 0; vt < 2; ++vt)
; #pragma unroll
;       for (int g4 = 0; g4 < 4; ++g4) {
;         const int v0 = vt * 32 + 8 * g4 + 4 * h2;
;         const ushort4 gt = *(const ushort4*)(P + qrow * PW + GATE + 512 + hd * 64 + v0);
;         uint2 o;
;         o.x = pk2(O[vt][4 * g4 + 0] * i0 * siluf_(bf2f(gt.x)), O[vt][4 * g4 + 1] * i0 * siluf_(bf2f(gt.y)));
;         o.y = pk2(O[vt][4 * g4 + 2] * i0 * siluf_(bf2f(gt.z)), O[vt][4 * g4 + 3] * i0 * siluf_(bf2f(gt.w)));
;         *(uint2*)(MIX + kblk((int)qrow, 512 + hd * 64 + v0, ROWS)) = o;
;       }
	v_mov_b32_e32 v0, v214
	v_mov_b32_e32 v1, v215
	v_and_b32_e32 v22, 0xffff0000, v0
	v_lshlrev_b32_e32 v0, 16, v0
	v_mul_f32_e32 v2, 0xbfb8aa3b, v0
	v_mul_f32_e32 v3, 0xbfb8aa3b, v22
	v_exp_f32_e32 v2, v2
	v_exp_f32_e32 v3, v3
	s_nop 0
	v_pk_add_f32 v[2:3], v[2:3], 1.0 op_sel_hi:[1,0]
	s_nop 0
	v_rcp_f32_e32 v24, v3
	s_nop 0
	v_fma_f32 v25, -v3, v24, 1.0
	v_fmac_f32_e32 v24, v25, v24
	v_mul_f32_e32 v26, v22, v24
	v_fma_f32 v27, -v3, v26, v22
	v_fmac_f32_e32 v26, v27, v24
	v_fma_f32 v23, -v3, v26, v22
	v_fma_f32 v23, v23, v24, v26
	v_div_fixup_f32 v3, v23, v3, v22
	v_rcp_f32_e32 v23, v2
	s_nop 0
	v_fma_f32 v24, -v2, v23, 1.0
	v_fmac_f32_e32 v23, v24, v23
	v_mul_f32_e32 v25, v0, v23
	v_fma_f32 v26, -v2, v25, v0
	v_fmac_f32_e32 v25, v26, v23
	v_fma_f32 v22, -v2, v25, v0
	v_fma_f32 v22, v22, v23, v25
	v_div_fixup_f32 v2, v22, v2, v0
	v_pk_mul_f32 v[2:3], v[4:5], v[2:3]
	v_and_b32_e32 v22, 0xffff0000, v1
	v_lshlrev_b32_e32 v1, 16, v1
	v_cvt_pk_bf16_f32 v0, v2, v3
	v_mul_f32_e32 v2, 0xbfb8aa3b, v1
	v_mul_f32_e32 v3, 0xbfb8aa3b, v22
	v_exp_f32_e32 v2, v2
	v_exp_f32_e32 v3, v3
	v_pk_mul_f32 v[4:5], v[6:7], v[32:33] op_sel_hi:[1,0]
	v_pk_add_f32 v[2:3], v[2:3], 1.0 op_sel_hi:[1,0]
	s_nop 0
	v_rcp_f32_e32 v7, v3
	s_nop 0
	v_fma_f32 v23, -v3, v7, 1.0
	v_fmac_f32_e32 v7, v23, v7
	v_mul_f32_e32 v24, v22, v7
	v_fma_f32 v25, -v3, v24, v22
	v_fmac_f32_e32 v24, v25, v7
	v_fma_f32 v6, -v3, v24, v22
	v_fma_f32 v6, v6, v7, v24
	v_div_fixup_f32 v3, v6, v3, v22
	v_rcp_f32_e32 v7, v2
	s_nop 0
	v_fma_f32 v22, -v2, v7, 1.0
	v_fmac_f32_e32 v7, v22, v7
	v_mul_f32_e32 v23, v1, v7
	v_fma_f32 v24, -v2, v23, v1
	v_fmac_f32_e32 v23, v24, v7
	v_fma_f32 v6, -v2, v23, v1
	v_fma_f32 v6, v6, v7, v23
	v_div_fixup_f32 v2, v6, v2, v1
	v_pk_mul_f32 v[2:3], v[4:5], v[2:3]
	v_pk_mul_f32 v[4:5], v[8:9], v[32:33] op_sel_hi:[1,0]
	v_cvt_pk_bf16_f32 v1, v2, v3
	v_lshl_add_u64 v[2:3], v[20:21], 0, v[36:37]
	global_store_dwordx2 v[2:3], v[0:1], off
	s_nop 0
	s_waitcnt lgkmcnt(0)
	v_mov_b32_e32 v0, v216
	v_mov_b32_e32 v1, v217
	v_and_b32_e32 v6, 0xffff0000, v0
	v_lshlrev_b32_e32 v0, 16, v0
	v_mul_f32_e32 v2, 0xbfb8aa3b, v0
	v_mul_f32_e32 v3, 0xbfb8aa3b, v6
	v_exp_f32_e32 v2, v2
	v_exp_f32_e32 v3, v3
	s_nop 0
	v_pk_add_f32 v[2:3], v[2:3], 1.0 op_sel_hi:[1,0]
	s_nop 0
	v_rcp_f32_e32 v8, v3
	s_nop 0
	v_fma_f32 v9, -v3, v8, 1.0
	v_fmac_f32_e32 v8, v9, v8
	v_mul_f32_e32 v22, v6, v8
	v_fma_f32 v23, -v3, v22, v6
	v_fmac_f32_e32 v22, v23, v8
	v_fma_f32 v7, -v3, v22, v6
	v_fma_f32 v7, v7, v8, v22
	v_div_fixup_f32 v3, v7, v3, v6
	v_rcp_f32_e32 v7, v2
	s_nop 0
	v_fma_f32 v8, -v2, v7, 1.0
	v_fmac_f32_e32 v7, v8, v7
	v_mul_f32_e32 v9, v0, v7
	v_fma_f32 v22, -v2, v9, v0
	v_fmac_f32_e32 v9, v22, v7
	v_fma_f32 v6, -v2, v9, v0
	v_fma_f32 v6, v6, v7, v9
	v_div_fixup_f32 v2, v6, v2, v0
	v_pk_mul_f32 v[2:3], v[4:5], v[2:3]
	v_and_b32_e32 v6, 0xffff0000, v1
	v_lshlrev_b32_e32 v1, 16, v1
	v_cvt_pk_bf16_f32 v0, v2, v3
	v_mul_f32_e32 v2, 0xbfb8aa3b, v1
	v_mul_f32_e32 v3, 0xbfb8aa3b, v6
	v_exp_f32_e32 v2, v2
	v_exp_f32_e32 v3, v3
	v_pk_mul_f32 v[4:5], v[10:11], v[32:33] op_sel_hi:[1,0]
	v_pk_add_f32 v[2:3], v[2:3], 1.0 op_sel_hi:[1,0]
	s_nop 0
	v_rcp_f32_e32 v8, v3
	s_nop 0
	v_fma_f32 v9, -v3, v8, 1.0
	v_fmac_f32_e32 v8, v9, v8
	v_mul_f32_e32 v10, v6, v8
	v_fma_f32 v11, -v3, v10, v6
	v_fmac_f32_e32 v10, v11, v8
	v_fma_f32 v7, -v3, v10, v6
	v_fma_f32 v7, v7, v8, v10
	v_div_fixup_f32 v3, v7, v3, v6
	v_rcp_f32_e32 v7, v2
	s_nop 0
	v_fma_f32 v8, -v2, v7, 1.0
	v_fmac_f32_e32 v7, v8, v7
	v_mul_f32_e32 v9, v1, v7
	v_fma_f32 v10, -v2, v9, v1
	v_fmac_f32_e32 v9, v10, v7
	v_fma_f32 v6, -v2, v9, v1
	v_fma_f32 v6, v6, v7, v9
	v_div_fixup_f32 v2, v6, v2, v1
	v_pk_mul_f32 v[2:3], v[4:5], v[2:3]
	v_pk_mul_f32 v[4:5], v[12:13], v[32:33] op_sel_hi:[1,0]
	v_cvt_pk_bf16_f32 v1, v2, v3
	v_lshl_add_u64 v[2:3], v[20:21], 0, v[18:19]
	global_store_dwordx2 v[2:3], v[0:1], off
	s_nop 0
	s_waitcnt lgkmcnt(0)
	v_mov_b32_e32 v0, v218
	v_mov_b32_e32 v1, v219
	v_and_b32_e32 v6, 0xffff0000, v0
	v_lshlrev_b32_e32 v0, 16, v0
	v_mul_f32_e32 v2, 0xbfb8aa3b, v0
	v_mul_f32_e32 v3, 0xbfb8aa3b, v6
	v_exp_f32_e32 v2, v2
	v_exp_f32_e32 v3, v3
	s_nop 0
	v_pk_add_f32 v[2:3], v[2:3], 1.0 op_sel_hi:[1,0]
	s_nop 0
	v_rcp_f32_e32 v8, v3
	s_nop 0
	v_fma_f32 v9, -v3, v8, 1.0
	v_fmac_f32_e32 v8, v9, v8
	v_mul_f32_e32 v10, v6, v8
	v_fma_f32 v11, -v3, v10, v6
	v_fmac_f32_e32 v10, v11, v8
	v_fma_f32 v7, -v3, v10, v6
	v_fma_f32 v7, v7, v8, v10
	v_div_fixup_f32 v3, v7, v3, v6
	v_rcp_f32_e32 v7, v2
	s_nop 0
	v_fma_f32 v8, -v2, v7, 1.0
	v_fmac_f32_e32 v7, v8, v7
	v_mul_f32_e32 v9, v0, v7
	v_fma_f32 v10, -v2, v9, v0
	v_fmac_f32_e32 v9, v10, v7
	v_fma_f32 v6, -v2, v9, v0
	v_fma_f32 v6, v6, v7, v9
	v_div_fixup_f32 v2, v6, v2, v0
	v_pk_mul_f32 v[2:3], v[4:5], v[2:3]
	v_and_b32_e32 v6, 0xffff0000, v1
	v_lshlrev_b32_e32 v1, 16, v1
	v_cvt_pk_bf16_f32 v0, v2, v3
	v_mul_f32_e32 v2, 0xbfb8aa3b, v1
	v_mul_f32_e32 v3, 0xbfb8aa3b, v6
	v_exp_f32_e32 v2, v2
	v_exp_f32_e32 v3, v3
	v_pk_mul_f32 v[4:5], v[14:15], v[32:33] op_sel_hi:[1,0]
	v_pk_add_f32 v[2:3], v[2:3], 1.0 op_sel_hi:[1,0]
	s_nop 0
	v_rcp_f32_e32 v8, v3
	s_nop 0
	v_fma_f32 v9, -v3, v8, 1.0
	v_fmac_f32_e32 v8, v9, v8
	v_mul_f32_e32 v10, v6, v8
	v_fma_f32 v11, -v3, v10, v6
	v_fmac_f32_e32 v10, v11, v8
	v_fma_f32 v7, -v3, v10, v6
	v_fma_f32 v7, v7, v8, v10
	v_div_fixup_f32 v3, v7, v3, v6
	v_rcp_f32_e32 v7, v2
	s_nop 0
	v_fma_f32 v8, -v2, v7, 1.0
	v_fmac_f32_e32 v7, v8, v7
	v_mul_f32_e32 v9, v1, v7
	v_fma_f32 v10, -v2, v9, v1
	v_fmac_f32_e32 v9, v10, v7
	v_fma_f32 v6, -v2, v9, v1
	v_fma_f32 v6, v6, v7, v9
	v_div_fixup_f32 v2, v6, v2, v1
	v_pk_mul_f32 v[2:3], v[4:5], v[2:3]
	s_nop 0
	v_cvt_pk_bf16_f32 v1, v2, v3
	v_lshl_add_u64 v[2:3], v[20:21], 0, v[16:17]
	global_store_dwordx2 v[2:3], v[0:1], off

; template <int MX, bool OUT>
; DI void rec_chunk(const Params& p, int l, int b, int h, int dir, int T0, unsigned char* smem, f32x4 (&St)[4], float& nst, float& dtot, int tid, const RecRaw& raw) {
;     ...
; #pragma unroll
;     for (int ks = 0; ks < 2; ++ks) {
;       const bf16x8 fb = *(const bf16x8*)(smem + L_QS + swz(t, ks * 4 + g));
; #pragma unroll
;       for (int a = 0; a < 4; ++a) {
;         const bf16x8 fa = *(const bf16x8*)(smem + L_STT + swz(16 * a + col, ks * 4 + g));
;         O[a] = MFMA16(fa, fb, O[a]);
;       }
;     }
;     if (MX == 1) {
;       const float inv = 1.f / fmaxf(fabsf(den), 1.f);
; #pragma unroll
;       for (int a = 0; a < 4; ++a)
; #pragma unroll
;         for (int j = 0; j < 4; ++j) O[a][j] *= inv;
;     }
;     if (dir == 0) {
; #pragma unroll
;       for (int a = 0; a < 4; ++a) *(uint2*)(MIX + kblk((int)orow, cb + 16 * a + 4 * g, ROWS)) = make_uint2(pk2(O[a][0], O[a][1]), pk2(O[a][2], O[a][3]));
;     } else {
;       float ss = 0.f;
; #pragma unroll
;       for (int a = 0; a < 4; ++a) {
;         const uint2 u = *(const uint2*)(MIX + kblk((int)orow, cb + 16 * a + 4 * g, ROWS));
;         O[a][0] += __uint_as_float(u.x << 16); O[a][1] += __uint_as_float(u.x & 0xffff0000u);
;         O[a][2] += __uint_as_float(u.y << 16); O[a][3] += __uint_as_float(u.y & 0xffff0000u);
; #pragma unroll
;         for (int j = 0; j < 4; ++j) ss += O[a][j] * O[a][j];
;       }
;       ss += __shfl_xor(ss, 16);
;       ss += __shfl_xor(ss, 32);
;       const float rstd = rsqrtf(ss * (1.f / 64.f) + EPS);
;       const float* gvec = (MX ? p.ml_g : p.hg_g) + l * 64;
; #pragma unroll
;       for (int a = 0; a < 4; ++a) {
;         const int v0 = 16 * a + 4 * g;
;         const uint2 gt = *(const uint2*)(prow + GATE + cb + v0);
;         const float4 gg = *(const float4*)(gvec + v0);
;         float y0 = O[a][0] * rstd * gg.x * siluf_(__uint_as_float(gt.x << 16));
;         float y1 = O[a][1] * rstd * gg.y * siluf_(__uint_as_float(gt.x & 0xffff0000u));
;         float y2 = O[a][2] * rstd * gg.z * siluf_(__uint_as_float(gt.y << 16));
;         float y3 = O[a][3] * rstd * gg.w * siluf_(__uint_as_float(gt.y & 0xffff0000u));
;         if (MX == 1) {
;           const uint2 og = *(const uint2*)(prow + D_OG + h * 64 + v0);
;           y0 *= sigmoidf_(__uint_as_float(og.x << 16)); y1 *= sigmoidf_(__uint_as_float(og.x & 0xffff0000u));
.LBB0_928:
	s_or_b64 exec, exec, s[0:1]
	ds_read_b128 v[42:45], v242 offset:32768
	ds_read_b128 v[46:49], v240 offset:57344
	ds_read_b128 v[50:53], v240 offset:59392
	s_add_i32 s0, s54, -1
	v_mov_b32_e32 v40, s0
	v_cndmask_b32_e64 v40, v93, v40, s[40:41]
	s_waitcnt lgkmcnt(1)
	v_mfma_f32_16x16x32_bf16 v[46:49], v[46:49], v[42:45], v[56:59]
	v_lshlrev_b32_e32 v40, 6, v40
	v_add_u32_e32 v40, s49, v40
	v_mov_b32_e32 v41, v161
	ds_read_b128 v[54:57], v240 offset:61440
	s_waitcnt lgkmcnt(1)
	v_mfma_f32_16x16x32_bf16 v[50:53], v[50:53], v[42:45], v[60:63]
	v_lshl_add_u64 v[40:41], v[40:41], 0, v[84:85]
	s_nop 1
	ds_read_b128 v[58:61], v240 offset:63488
	s_waitcnt lgkmcnt(1)
	v_mfma_f32_16x16x32_bf16 v[54:57], v[54:57], v[42:45], v[64:67]
	s_waitcnt lgkmcnt(0)
	v_mfma_f32_16x16x32_bf16 v[42:45], v[58:61], v[42:45], v[72:75]
	ds_read_b128 v[58:61], v241 offset:32768
	ds_read_b128 v[62:65], v239 offset:57344
	s_waitcnt lgkmcnt(0)
	v_mfma_f32_16x16x32_bf16 v[46:49], v[62:65], v[58:61], v[46:49]
	ds_read_b128 v[62:65], v239 offset:59392
	s_waitcnt lgkmcnt(0)
	v_mfma_f32_16x16x32_bf16 v[50:53], v[62:65], v[58:61], v[50:53]
	ds_read_b128 v[62:65], v239 offset:61440
	s_waitcnt lgkmcnt(0)
	v_mfma_f32_16x16x32_bf16 v[62:65], v[62:65], v[58:61], v[54:57]
	s_nop 2
	ds_read_b128 v[54:57], v239 offset:63488
	s_waitcnt lgkmcnt(0)
	v_mfma_f32_16x16x32_bf16 v[42:45], v[54:57], v[58:61], v[42:45]
	v_add_f32_e32 v54, v95, v100
	v_max_f32_e64 v54, |v54|, 1.0
	v_rcp_f32_e32 v56, v54
	s_mov_b64 s[0:1], -1
	v_fma_f32 v57, -v54, v56, 1.0
	v_fmac_f32_e32 v56, v57, v56
	v_mul_f32_e32 v58, 1.0, v56
	v_fma_f32 v59, -v54, v58, 1.0
	v_fmac_f32_e32 v58, v59, v56
	v_fma_f32 v55, -v54, v58, 1.0
	v_fma_f32 v55, v55, v56, v58
	v_div_fixup_f32 v60, v55, v54, 1.0
	v_pk_mul_f32 v[54:55], v[60:61], v[46:47] op_sel_hi:[0,1]
	v_pk_mul_f32 v[46:47], v[60:61], v[42:43] op_sel_hi:[0,1]
	v_ashrrev_i32_e32 v43, 31, v40
	v_mov_b32_e32 v42, v40
	v_pk_mul_f32 v[58:59], v[60:61], v[48:49] op_sel_hi:[0,1]
	v_pk_mul_f32 v[50:51], v[60:61], v[50:51] op_sel_hi:[0,1]
	v_pk_mul_f32 v[56:57], v[60:61], v[52:53] op_sel_hi:[0,1]
	v_pk_mul_f32 v[48:49], v[60:61], v[62:63] op_sel_hi:[0,1]
	v_pk_mul_f32 v[52:53], v[60:61], v[64:65] op_sel_hi:[0,1]
	v_pk_mul_f32 v[44:45], v[60:61], v[44:45] op_sel_hi:[0,1]
	v_lshl_add_u64 v[60:61], v[42:43], 0, s[42:43]
	v_lshl_add_u64 v[62:63], v[42:43], 0, s[28:29]
	v_lshl_add_u64 v[42:43], v[42:43], 0, s[30:31]
	s_andn2_b64 vcc, exec, s[12:13]
	v_lshlrev_b64 v[64:65], 6, v[60:61]
	v_lshlrev_b64 v[62:63], 6, v[62:63]
	v_lshlrev_b64 v[60:61], 6, v[42:43]
	s_cbranch_vccnz .LBB0_930
	v_lshl_add_u64 v[102:103], v[90:91], 0, v[62:63]
	global_load_dwordx2 v[66:67], v[102:103], off
	v_mov_b64_e32 v[42:43], s[24:25]
	v_mad_u64_u32 v[42:43], s[0:1], v40, s33, v[42:43]
	v_mad_i32_i24 v43, v41, s33, v43
	s_mov_b64 s[0:1], 0x1a20
	v_mov_b32_e32 v93, v161
	v_lshl_add_u64 v[74:75], v[42:43], 0, s[0:1]
	v_lshl_add_u64 v[104:105], v[74:75], 0, s[2:3]
	v_lshl_add_u64 v[74:75], v[74:75], 0, v[92:93]
	v_lshl_add_u64 v[106:107], v[86:87], 0, v[64:65]
	v_lshl_add_u64 v[74:75], v[74:75], 0, s[2:3]
	global_load_dwordx2 v[40:41], v[106:107], off
	s_mov_b32 s21, s3
	v_lshl_add_u64 v[42:43], v[42:43], 0, s[20:21]
	v_lshl_add_u64 v[42:43], v[42:43], 0, v[92:93]
	s_mov_b64 s[0:1], 0x1820
	v_lshl_add_u64 v[104:105], v[104:105], 0, v[92:93]
	global_load_dwordx2 v[74:75], v[74:75], off
	s_waitcnt vmcnt(0) lgkmcnt(0)
	v_lshlrev_b32_e32 v100, 16, v66
	v_and_b32_e32 v101, 0xffff0000, v66
	v_lshlrev_b32_e32 v108, 16, v67
	v_and_b32_e32 v109, 0xffff0000, v67
	v_lshl_add_u64 v[66:67], s[22:23], 0, v[60:61]
	v_lshl_add_u64 v[72:73], v[66:67], 0, v[92:93]
	global_load_dwordx2 v[68:69], v[72:73], off
	v_lshlrev_b32_e32 v128, 16, v40
	v_and_b32_e32 v129, 0xffff0000, v40
	v_lshlrev_b32_e32 v40, 16, v41
	v_and_b32_e32 v41, 0xffff0000, v41
	v_pk_add_f32 v[128:129], v[54:55], v[128:129]
	v_lshlrev_b32_e32 v95, 16, v74
	v_and_b32_e32 v243, 0xffff0000, v74
	v_lshlrev_b32_e32 v130, 16, v75
	v_and_b32_e32 v131, 0xffff0000, v75
	v_lshl_add_u64 v[74:75], v[42:43], 0, s[0:1]
	v_add_co_u32_e32 v42, vcc, s16, v42
	v_mul_f32_e32 v120, 0xbfb8aa3b, v130
	s_nop 0
	v_addc_co_u32_e32 v43, vcc, 0, v43, vcc
	v_mul_f32_e32 v121, 0xbfb8aa3b, v131
	global_load_dwordx2 v[42:43], v[42:43], off offset:2080
	v_exp_f32_e32 v120, v120
	v_exp_f32_e32 v121, v121
	s_waitcnt vmcnt(0) lgkmcnt(0)
; DI size_t kblk(int row, int col, int nrows) { return ((size_t)(col >> 5) * nrows + row) * 32 + (col & 31); }
; DI unsigned pk2(float a, float b) { hwf32x2 f = {a, b}; hwbf16x2 r = __builtin_convertvector(f, hwbf16x2); return __builtin_bit_cast(unsigned, r); }
; DI float sigmoidf_(float z) { return 1.f / (1.f + __expf(-z)); }
; DI float siluf_(float z) { return z / (1.f + __expf(-z)); }
; template <int MX, bool OUT>
; DI void rec_chunk(const Params& p, int l, int b, int h, int dir, int T0, unsigned char* smem, f32x4 (&St)[4], float& nst, float& dtot, int tid, const RecRaw& raw) {
;     ...
;       float ss = 0.f;
; #pragma unroll
;       for (int a = 0; a < 4; ++a) {
;         const uint2 u = *(const uint2*)(MIX + kblk((int)orow, cb + 16 * a + 4 * g, ROWS));
;         O[a][0] += __uint_as_float(u.x << 16); O[a][1] += __uint_as_float(u.x & 0xffff0000u);
;         O[a][2] += __uint_as_float(u.y << 16); O[a][3] += __uint_as_float(u.y & 0xffff0000u);
; #pragma unroll
;         for (int j = 0; j < 4; ++j) ss += O[a][j] * O[a][j];
;       }
;       ss += __shfl_xor(ss, 16);
;       ss += __shfl_xor(ss, 32);
;       const float rstd = rsqrtf(ss * (1.f / 64.f) + EPS);
;       const float* gvec = (MX ? p.ml_g : p.hg_g) + l * 64;
; #pragma unroll
;       for (int a = 0; a < 4; ++a) {
;         const int v0 = 16 * a + 4 * g;
;         const uint2 gt = *(const uint2*)(prow + GATE + cb + v0);
;         const float4 gg = *(const float4*)(gvec + v0);
;         float y0 = O[a][0] * rstd * gg.x * siluf_(__uint_as_float(gt.x << 16));
;         float y1 = O[a][1] * rstd * gg.y * siluf_(__uint_as_float(gt.x & 0xffff0000u));
;         float y2 = O[a][2] * rstd * gg.z * siluf_(__uint_as_float(gt.y << 16));
;         float y3 = O[a][3] * rstd * gg.w * siluf_(__uint_as_float(gt.y & 0xffff0000u));
;         if (MX == 1) {
;           const uint2 og = *(const uint2*)(prow + D_OG + h * 64 + v0);
;           y0 *= sigmoidf_(__uint_as_float(og.x << 16)); y1 *= sigmoidf_(__uint_as_float(og.x & 0xffff0000u));
;           y2 *= sigmoidf_(__uint_as_float(og.y << 16)); y3 *= sigmoidf_(__uint_as_float(og.y & 0xffff0000u));
;         }
;         *(uint2*)(MIX + kblk((int)orow, cb + v0, ROWS)) = make_uint2(pk2(y0, y1), pk2(y2, y3));
	v_lshlrev_b32_e32 v110, 16, v68
	v_and_b32_e32 v111, 0xffff0000, v68
	v_pk_add_f32 v[120:121], v[120:121], 1.0 op_sel_hi:[1,0]
	v_lshlrev_b32_e32 v112, 16, v69
	v_rcp_f32_e32 v133, v121
	v_and_b32_e32 v113, 0xffff0000, v69
	global_load_dwordx2 v[68:69], v[72:73], off offset:32
	v_pk_add_f32 v[110:111], v[48:49], v[110:111]
	v_fma_f32 v244, -v121, v133, 1.0
	v_fmac_f32_e32 v133, v244, v133
	v_mul_f32_e32 v245, v131, v133
	v_fma_f32 v246, -v121, v245, v131
	v_fmac_f32_e32 v245, v246, v133
	v_fma_f32 v132, -v121, v245, v131
	v_fma_f32 v132, v132, v133, v245
	v_div_fixup_f32 v121, v132, v121, v131
	v_rcp_f32_e32 v132, v120
	v_pk_mul_f32 v[250:251], v[110:111], v[110:111]
	v_lshlrev_b32_e32 v118, 16, v42
	v_and_b32_e32 v42, 0xffff0000, v42
	v_fma_f32 v133, -v120, v132, 1.0
	v_fmac_f32_e32 v132, v133, v132
	v_mul_f32_e32 v244, v130, v132
	v_fma_f32 v245, -v120, v244, v130
	v_fmac_f32_e32 v244, v245, v132
	v_fma_f32 v131, -v120, v244, v130
	v_fma_f32 v131, v131, v132, v244
	v_mul_f32_e32 v132, 0xbfb8aa3b, v95
	v_mul_f32_e32 v133, 0xbfb8aa3b, v243
	v_exp_f32_e32 v132, v132
	v_exp_f32_e32 v133, v133
	v_div_fixup_f32 v120, v131, v120, v130
	v_pk_mul_f32 v[130:131], v[128:129], v[128:129]
	v_mul_f32_e32 v118, 0xbfb8aa3b, v118
	v_pk_add_f32 v[132:133], v[132:133], 1.0 op_sel_hi:[1,0]
	v_mul_f32_e32 v42, 0xbfb8aa3b, v42
	v_rcp_f32_e32 v245, v133
	v_add_f32_e32 v93, v130, v131
	v_exp_f32_e32 v126, v118
	v_exp_f32_e32 v127, v42
	v_fma_f32 v246, -v133, v245, 1.0
	v_fmac_f32_e32 v245, v246, v245
	v_mul_f32_e32 v247, v243, v245
	v_fma_f32 v248, -v133, v247, v243
	v_fmac_f32_e32 v247, v248, v245
	v_fma_f32 v244, -v133, v247, v243
	v_fma_f32 v244, v244, v245, v247
	v_div_fixup_f32 v133, v244, v133, v243
	v_rcp_f32_e32 v244, v132
	v_lshlrev_b32_e32 v42, 16, v43
	v_pk_add_f32 v[118:119], v[58:59], v[40:41]
	v_pk_add_f32 v[248:249], v[50:51], v[100:101]
	v_fma_f32 v245, -v132, v244, 1.0
	v_fmac_f32_e32 v244, v245, v244
	v_mul_f32_e32 v246, v95, v244
	v_fma_f32 v247, -v132, v246, v95
	v_fmac_f32_e32 v246, v247, v244
	v_fma_f32 v243, -v132, v246, v95
	v_fma_f32 v243, v243, v244, v246
	v_div_fixup_f32 v132, v243, v132, v95
	v_pk_mul_f32 v[100:101], v[248:249], v[248:249]
	v_mul_f32_e32 v42, 0xbfb8aa3b, v42
	v_pk_mul_f32 v[122:123], v[118:119], v[118:119]
	v_exp_f32_e32 v124, v42
	v_and_b32_e32 v42, 0xffff0000, v43
	v_add_f32_e32 v93, v93, v122
	v_mul_f32_e32 v42, 0xbfb8aa3b, v42
	v_add_f32_e32 v93, v123, v93
	v_pk_add_f32 v[126:127], v[126:127], 1.0 op_sel_hi:[1,0]
	v_exp_f32_e32 v125, v42
	global_load_dwordx4 v[40:43], v[88:89], off
	v_rcp_f32_e32 v243, v127
	v_pk_add_f32 v[124:125], v[124:125], 1.0 op_sel_hi:[1,0]
	v_add_f32_e32 v93, v100, v93
	v_add_f32_e32 v93, v101, v93
	v_fma_f32 v244, -v127, v243, 1.0
	v_fmac_f32_e32 v243, v244, v243
	v_mul_f32_e32 v245, 1.0, v243
	v_fma_f32 v246, -v127, v245, 1.0
	v_fmac_f32_e32 v245, v246, v243
	v_fma_f32 v95, -v127, v245, 1.0
	v_fma_f32 v95, v95, v243, v245
	v_div_fixup_f32 v127, v95, v127, 1.0
	v_rcp_f32_e32 v243, v126
	s_waitcnt vmcnt(0) lgkmcnt(0)
	v_lshlrev_b32_e32 v70, 16, v68
	v_and_b32_e32 v71, 0xffff0000, v68
	v_pk_add_f32 v[70:71], v[46:47], v[70:71]
	v_fma_f32 v244, -v126, v243, 1.0
	v_fmac_f32_e32 v243, v244, v243
	v_mul_f32_e32 v245, 1.0, v243
	v_fma_f32 v246, -v126, v245, 1.0
	v_fmac_f32_e32 v245, v246, v243
	v_fma_f32 v95, -v126, v245, 1.0
	v_fma_f32 v95, v95, v243, v245
	v_div_fixup_f32 v126, v95, v126, 1.0
	v_rcp_f32_e32 v243, v125
	v_lshlrev_b32_e32 v68, 16, v69
	v_and_b32_e32 v69, 0xffff0000, v69
	v_pk_mul_f32 v[114:115], v[70:71], v[70:71]
	v_fma_f32 v244, -v125, v243, 1.0
	v_fmac_f32_e32 v243, v244, v243
	v_mul_f32_e32 v245, 1.0, v243
	v_fma_f32 v246, -v125, v245, 1.0
	v_fmac_f32_e32 v245, v246, v243
	v_fma_f32 v95, -v125, v245, 1.0
	v_fma_f32 v95, v95, v243, v245
	v_div_fixup_f32 v125, v95, v125, 1.0
	v_div_scale_f32 v95, s[0:1], v124, v124, 1.0
	v_rcp_f32_e32 v243, v95
	v_pk_add_f32 v[68:69], v[44:45], v[68:69]
	v_fma_f32 v244, -v95, v243, 1.0
	v_fmac_f32_e32 v243, v244, v243
	v_div_scale_f32 v244, vcc, 1.0, v124, 1.0
	v_mul_f32_e32 v245, v244, v243
	v_fma_f32 v246, -v95, v245, v244
	v_fmac_f32_e32 v245, v246, v243
	v_fma_f32 v95, -v95, v245, v244
	v_div_fmas_f32 v95, v95, v243, v245
	v_pk_add_f32 v[244:245], v[56:57], v[108:109]
	v_pk_add_f32 v[108:109], v[52:53], v[112:113]
	v_pk_mul_f32 v[246:247], v[244:245], v[244:245]
	v_pk_mul_f32 v[112:113], v[108:109], v[108:109]
	v_add_f32_e32 v93, v246, v93
	v_add_f32_e32 v93, v247, v93
	v_add_f32_e32 v93, v250, v93
	v_add_f32_e32 v93, v251, v93
	v_add_f32_e32 v93, v112, v93
	v_add_f32_e32 v93, v113, v93
	v_add_f32_e32 v93, v114, v93
	v_pk_mul_f32 v[116:117], v[68:69], v[68:69]
	v_add_f32_e32 v93, v115, v93
	v_add_f32_e32 v93, v116, v93
	v_add_f32_e32 v93, v117, v93
	v_div_fixup_f32 v124, v95, v124, 1.0
	ds_bpermute_b32 v95, v149, v93
	s_waitcnt lgkmcnt(0)
	v_add_f32_e32 v93, v93, v95
	ds_bpermute_b32 v95, v150, v93
	s_waitcnt lgkmcnt(0)
	v_add_f32_e32 v93, v93, v95
	v_fmamk_f32 v93, v93, 0x3c800000, v162
	v_cmp_gt_f32_e32 vcc, s38, v93
	v_mul_f32_e32 v95, 0x4b800000, v93
	s_nop 0
	v_cndmask_b32_e32 v93, v93, v95, vcc
	v_rsq_f32_e32 v93, v93
	s_nop 0
	v_mul_f32_e32 v95, 0x45800000, v93
	v_cndmask_b32_e32 v100, v93, v95, vcc
	v_pk_mul_f32 v[112:113], v[128:129], v[100:101] op_sel_hi:[1,0]
	s_nop 0
	v_pk_mul_f32 v[40:41], v[40:41], v[112:113]
	v_pk_mul_f32 v[112:113], v[118:119], v[100:101] op_sel_hi:[1,0]
	v_pk_mul_f32 v[40:41], v[132:133], v[40:41]
	v_pk_mul_f32 v[42:43], v[42:43], v[112:113]
	v_pk_mul_f32 v[40:41], v[126:127], v[40:41]
	v_pk_mul_f32 v[42:43], v[120:121], v[42:43]
	v_cvt_pk_bf16_f32 v40, v40, v41
	v_pk_mul_f32 v[42:43], v[124:125], v[42:43]
	s_nop 0
	v_cvt_pk_bf16_f32 v41, v42, v43
	global_store_dwordx2 v[106:107], v[40:41], off
	global_load_dwordx2 v[40:41], v[104:105], off offset:32
	s_nop 0
	global_load_dwordx4 v[112:115], v[88:89], off offset:64
	v_pk_mul_f32 v[106:107], v[248:249], v[100:101] op_sel_hi:[1,0]
	s_waitcnt vmcnt(0) lgkmcnt(0)
; DI size_t kblk(int row, int col, int nrows) { return ((size_t)(col >> 5) * nrows + row) * 32 + (col & 31); }
; DI unsigned pk2(float a, float b) { hwf32x2 f = {a, b}; hwbf16x2 r = __builtin_convertvector(f, hwbf16x2); return __builtin_bit_cast(unsigned, r); }
; DI float sigmoidf_(float z) { return 1.f / (1.f + __expf(-z)); }
; DI float siluf_(float z) { return z / (1.f + __expf(-z)); }
; template <int MX, bool OUT>
; DI void rec_chunk(const Params& p, int l, int b, int h, int dir, int T0, unsigned char* smem, f32x4 (&St)[4], float& nst, float& dtot, int tid, const RecRaw& raw) {
;     ...
;       for (int a = 0; a < 4; ++a) {
;         const int v0 = 16 * a + 4 * g;
;         const uint2 gt = *(const uint2*)(prow + GATE + cb + v0);
;         const float4 gg = *(const float4*)(gvec + v0);
;         float y0 = O[a][0] * rstd * gg.x * siluf_(__uint_as_float(gt.x << 16));
;         float y1 = O[a][1] * rstd * gg.y * siluf_(__uint_as_float(gt.x & 0xffff0000u));
;         float y2 = O[a][2] * rstd * gg.z * siluf_(__uint_as_float(gt.y << 16));
;         float y3 = O[a][3] * rstd * gg.w * siluf_(__uint_as_float(gt.y & 0xffff0000u));
;         if (MX == 1) {
;           const uint2 og = *(const uint2*)(prow + D_OG + h * 64 + v0);
;           y0 *= sigmoidf_(__uint_as_float(og.x << 16)); y1 *= sigmoidf_(__uint_as_float(og.x & 0xffff0000u));
;           y2 *= sigmoidf_(__uint_as_float(og.y << 16)); y3 *= sigmoidf_(__uint_as_float(og.y & 0xffff0000u));
;         }
;         *(uint2*)(MIX + kblk((int)orow, cb + v0, ROWS)) = make_uint2(pk2(y0, y1), pk2(y2, y3));
	v_lshlrev_b32_e32 v93, 16, v40
	v_and_b32_e32 v40, 0xffff0000, v40
	v_mul_f32_e32 v42, 0xbfb8aa3b, v93
	v_mul_f32_e32 v43, 0xbfb8aa3b, v40
	v_exp_f32_e32 v42, v42
	v_exp_f32_e32 v43, v43
	v_pk_mul_f32 v[106:107], v[112:113], v[106:107]
	v_pk_add_f32 v[42:43], v[42:43], 1.0 op_sel_hi:[1,0]
	s_nop 0
	v_rcp_f32_e32 v101, v43
	s_nop 0
	v_fma_f32 v112, -v43, v101, 1.0
	v_fmac_f32_e32 v101, v112, v101
	v_mul_f32_e32 v113, v40, v101
	v_fma_f32 v116, -v43, v113, v40
	v_fmac_f32_e32 v113, v116, v101
	v_fma_f32 v95, -v43, v113, v40
	v_fma_f32 v95, v95, v101, v113
	v_div_fixup_f32 v43, v95, v43, v40
	v_rcp_f32_e32 v95, v42
	s_nop 0
	v_fma_f32 v101, -v42, v95, 1.0
	v_fmac_f32_e32 v95, v101, v95
	v_mul_f32_e32 v112, v93, v95
	v_fma_f32 v113, -v42, v112, v93
	v_fmac_f32_e32 v112, v113, v95
	v_fma_f32 v40, -v42, v112, v93
	v_fma_f32 v40, v40, v95, v112
	v_div_fixup_f32 v42, v40, v42, v93
	v_lshlrev_b32_e32 v93, 16, v41
	v_and_b32_e32 v95, 0xffff0000, v41
	v_mul_f32_e32 v40, 0xbfb8aa3b, v93
	v_mul_f32_e32 v41, 0xbfb8aa3b, v95
	v_exp_f32_e32 v40, v40
	v_exp_f32_e32 v41, v41
	v_pk_mul_f32 v[42:43], v[42:43], v[106:107]
	v_pk_mul_f32 v[106:107], v[244:245], v[100:101] op_sel_hi:[1,0]
	v_pk_add_f32 v[40:41], v[40:41], 1.0 op_sel_hi:[1,0]
	s_nop 0
	v_rcp_f32_e32 v112, v41
	v_pk_mul_f32 v[106:107], v[114:115], v[106:107]
	v_fma_f32 v113, -v41, v112, 1.0
	v_fmac_f32_e32 v112, v113, v112
	v_mul_f32_e32 v114, v95, v112
	v_fma_f32 v115, -v41, v114, v95
	v_fmac_f32_e32 v114, v115, v112
	v_fma_f32 v101, -v41, v114, v95
	v_fma_f32 v101, v101, v112, v114
	v_div_fixup_f32 v41, v101, v41, v95
	v_rcp_f32_e32 v101, v40
	s_nop 0
	v_fma_f32 v112, -v40, v101, 1.0
	v_fmac_f32_e32 v101, v112, v101
	v_mul_f32_e32 v113, v93, v101
	v_fma_f32 v114, -v40, v113, v93
	v_fmac_f32_e32 v113, v114, v101
	v_fma_f32 v95, -v40, v113, v93
	v_fma_f32 v95, v95, v101, v113
	v_div_fixup_f32 v40, v95, v40, v93
	v_pk_mul_f32 v[40:41], v[40:41], v[106:107]
	global_load_dwordx2 v[106:107], v[74:75], off offset:32
	s_waitcnt vmcnt(0) lgkmcnt(0)
	v_lshlrev_b32_e32 v93, 16, v106
	v_mul_f32_e32 v93, 0xbfb8aa3b, v93
	v_exp_f32_e32 v112, v93
	v_and_b32_e32 v93, 0xffff0000, v106
	v_mul_f32_e32 v93, 0xbfb8aa3b, v93
	v_exp_f32_e32 v113, v93
	s_nop 0
	v_pk_add_f32 v[112:113], v[112:113], 1.0 op_sel_hi:[1,0]
	s_nop 0
	v_rcp_f32_e32 v95, v113
	s_nop 0
	v_fma_f32 v101, -v113, v95, 1.0
	v_fmac_f32_e32 v95, v101, v95
	v_mul_f32_e32 v106, 1.0, v95
	v_fma_f32 v114, -v113, v106, 1.0
	v_fmac_f32_e32 v106, v114, v95
	v_fma_f32 v93, -v113, v106, 1.0
	v_fma_f32 v93, v93, v95, v106
	v_div_fixup_f32 v113, v93, v113, 1.0
	v_rcp_f32_e32 v95, v112
	s_nop 0
	v_fma_f32 v101, -v112, v95, 1.0
	v_fmac_f32_e32 v95, v101, v95
	v_mul_f32_e32 v106, 1.0, v95
	v_fma_f32 v114, -v112, v106, 1.0
	v_fmac_f32_e32 v106, v114, v95
	v_fma_f32 v93, -v112, v106, 1.0
	v_fma_f32 v93, v93, v95, v106
	v_div_fixup_f32 v112, v93, v112, 1.0
	v_lshlrev_b32_e32 v93, 16, v107
	v_mul_f32_e32 v93, 0xbfb8aa3b, v93
	v_exp_f32_e32 v106, v93
	v_and_b32_e32 v93, 0xffff0000, v107
	v_mul_f32_e32 v93, 0xbfb8aa3b, v93
	v_exp_f32_e32 v107, v93
	v_pk_mul_f32 v[42:43], v[42:43], v[112:113]
	v_pk_add_f32 v[106:107], v[106:107], 1.0 op_sel_hi:[1,0]
	s_nop 0
	v_rcp_f32_e32 v95, v107
	v_cvt_pk_bf16_f32 v42, v42, v43
	v_fma_f32 v101, -v107, v95, 1.0
	v_fmac_f32_e32 v95, v101, v95
	v_mul_f32_e32 v112, 1.0, v95
	v_fma_f32 v113, -v107, v112, 1.0
	v_fmac_f32_e32 v112, v113, v95
	v_fma_f32 v93, -v107, v112, 1.0
	v_fma_f32 v93, v93, v95, v112
	v_div_fixup_f32 v107, v93, v107, 1.0
	v_rcp_f32_e32 v95, v106
	s_nop 0
	v_fma_f32 v101, -v106, v95, 1.0
	v_fmac_f32_e32 v95, v101, v95
	v_mul_f32_e32 v112, 1.0, v95
	v_fma_f32 v113, -v106, v112, 1.0
	v_fmac_f32_e32 v112, v113, v95
	v_fma_f32 v93, -v106, v112, 1.0
	v_fma_f32 v93, v93, v95, v112
	v_div_fixup_f32 v106, v93, v106, 1.0
	v_pk_mul_f32 v[40:41], v[40:41], v[106:107]
	s_nop 0
	v_cvt_pk_bf16_f32 v43, v40, v41
	global_store_dwordx2 v[102:103], v[42:43], off
	global_load_dwordx2 v[40:41], v[104:105], off offset:64
	global_load_dwordx4 v[112:115], v[88:89], off offset:128
	v_pk_mul_f32 v[102:103], v[110:111], v[100:101] op_sel_hi:[1,0]
	s_waitcnt vmcnt(0) lgkmcnt(0)
	v_lshlrev_b32_e32 v93, 16, v40
	v_and_b32_e32 v40, 0xffff0000, v40
	v_mul_f32_e32 v42, 0xbfb8aa3b, v93
	v_mul_f32_e32 v43, 0xbfb8aa3b, v40
	v_exp_f32_e32 v42, v42
	v_exp_f32_e32 v43, v43
	v_pk_mul_f32 v[102:103], v[102:103], v[112:113]
	v_pk_add_f32 v[42:43], v[42:43], 1.0 op_sel_hi:[1,0]
	s_nop 0
	v_rcp_f32_e32 v101, v43
	s_nop 0
	v_fma_f32 v106, -v43, v101, 1.0
	v_fmac_f32_e32 v101, v106, v101
	v_mul_f32_e32 v107, v40, v101
	v_fma_f32 v110, -v43, v107, v40
	v_fmac_f32_e32 v107, v110, v101
	v_fma_f32 v95, -v43, v107, v40
	v_fma_f32 v95, v95, v101, v107
	v_div_fixup_f32 v43, v95, v43, v40
	v_rcp_f32_e32 v95, v42
	s_nop 0
	v_fma_f32 v101, -v42, v95, 1.0
	v_fmac_f32_e32 v95, v101, v95
	v_mul_f32_e32 v106, v93, v95
	v_fma_f32 v107, -v42, v106, v93
	v_fmac_f32_e32 v106, v107, v95
	v_fma_f32 v40, -v42, v106, v93
	v_fma_f32 v40, v40, v95, v106
	v_div_fixup_f32 v42, v40, v42, v93
	v_lshlrev_b32_e32 v93, 16, v41
	v_and_b32_e32 v95, 0xffff0000, v41
	v_mul_f32_e32 v40, 0xbfb8aa3b, v93
	v_mul_f32_e32 v41, 0xbfb8aa3b, v95
	v_exp_f32_e32 v40, v40
	v_exp_f32_e32 v41, v41
	v_pk_mul_f32 v[42:43], v[102:103], v[42:43]
	v_pk_mul_f32 v[102:103], v[108:109], v[100:101] op_sel_hi:[1,0]
	v_pk_add_f32 v[40:41], v[40:41], 1.0 op_sel_hi:[1,0]
	s_nop 0
	v_rcp_f32_e32 v106, v41
	v_pk_mul_f32 v[102:103], v[102:103], v[114:115]
	v_fma_f32 v107, -v41, v106, 1.0
	v_fmac_f32_e32 v106, v107, v106
	v_mul_f32_e32 v108, v95, v106
	v_fma_f32 v109, -v41, v108, v95
	v_fmac_f32_e32 v108, v109, v106
	v_fma_f32 v101, -v41, v108, v95
	v_fma_f32 v101, v101, v106, v108
	v_div_fixup_f32 v41, v101, v41, v95
	v_rcp_f32_e32 v101, v40
	s_nop 0
	v_fma_f32 v106, -v40, v101, 1.0
	v_fmac_f32_e32 v101, v106, v101
	v_mul_f32_e32 v107, v93, v101
	v_fma_f32 v108, -v40, v107, v93
	v_fmac_f32_e32 v107, v108, v101
	v_fma_f32 v95, -v40, v107, v93
	v_fma_f32 v95, v95, v101, v107
	v_div_fixup_f32 v40, v95, v40, v93
	v_pk_mul_f32 v[40:41], v[102:103], v[40:41]
	global_load_dwordx2 v[102:103], v[74:75], off offset:64
	s_waitcnt vmcnt(0) lgkmcnt(0)
; DI size_t kblk(int row, int col, int nrows) { return ((size_t)(col >> 5) * nrows + row) * 32 + (col & 31); }
; DI unsigned pk2(float a, float b) { hwf32x2 f = {a, b}; hwbf16x2 r = __builtin_convertvector(f, hwbf16x2); return __builtin_bit_cast(unsigned, r); }
; DI float sigmoidf_(float z) { return 1.f / (1.f + __expf(-z)); }
; DI float siluf_(float z) { return z / (1.f + __expf(-z)); }
; template <int MX, bool OUT>
; DI void rec_chunk(const Params& p, int l, int b, int h, int dir, int T0, unsigned char* smem, f32x4 (&St)[4], float& nst, float& dtot, int tid, const RecRaw& raw) {
;     ...
; #pragma unroll
;       for (int a = 0; a < 4; ++a) {
;         const int v0 = 16 * a + 4 * g;
;         const uint2 gt = *(const uint2*)(prow + GATE + cb + v0);
;         const float4 gg = *(const float4*)(gvec + v0);
;         float y0 = O[a][0] * rstd * gg.x * siluf_(__uint_as_float(gt.x << 16));
;         float y1 = O[a][1] * rstd * gg.y * siluf_(__uint_as_float(gt.x & 0xffff0000u));
;         float y2 = O[a][2] * rstd * gg.z * siluf_(__uint_as_float(gt.y << 16));
;         float y3 = O[a][3] * rstd * gg.w * siluf_(__uint_as_float(gt.y & 0xffff0000u));
;         if (MX == 1) {
;           const uint2 og = *(const uint2*)(prow + D_OG + h * 64 + v0);
;           y0 *= sigmoidf_(__uint_as_float(og.x << 16)); y1 *= sigmoidf_(__uint_as_float(og.x & 0xffff0000u));
;           y2 *= sigmoidf_(__uint_as_float(og.y << 16)); y3 *= sigmoidf_(__uint_as_float(og.y & 0xffff0000u));
;         }
;         *(uint2*)(MIX + kblk((int)orow, cb + v0, ROWS)) = make_uint2(pk2(y0, y1), pk2(y2, y3));
	v_lshlrev_b32_e32 v93, 16, v102
	v_mul_f32_e32 v93, 0xbfb8aa3b, v93
	v_exp_f32_e32 v106, v93
	v_and_b32_e32 v93, 0xffff0000, v102
	v_mul_f32_e32 v93, 0xbfb8aa3b, v93
	v_exp_f32_e32 v107, v93
	s_nop 0
	v_pk_add_f32 v[106:107], v[106:107], 1.0 op_sel_hi:[1,0]
	s_nop 0
	v_rcp_f32_e32 v95, v107
	s_nop 0
	v_fma_f32 v101, -v107, v95, 1.0
	v_fmac_f32_e32 v95, v101, v95
	v_mul_f32_e32 v102, 1.0, v95
	v_fma_f32 v108, -v107, v102, 1.0
	v_fmac_f32_e32 v102, v108, v95
	v_fma_f32 v93, -v107, v102, 1.0
	v_fma_f32 v93, v93, v95, v102
	v_div_fixup_f32 v107, v93, v107, 1.0
	v_rcp_f32_e32 v95, v106
	s_nop 0
	v_fma_f32 v101, -v106, v95, 1.0
	v_fmac_f32_e32 v95, v101, v95
	v_mul_f32_e32 v102, 1.0, v95
	v_fma_f32 v108, -v106, v102, 1.0
	v_fmac_f32_e32 v102, v108, v95
	v_fma_f32 v93, -v106, v102, 1.0
	v_fma_f32 v93, v93, v95, v102
	v_div_fixup_f32 v106, v93, v106, 1.0
	v_lshlrev_b32_e32 v93, 16, v103
	v_mul_f32_e32 v93, 0xbfb8aa3b, v93
	v_exp_f32_e32 v102, v93
	v_and_b32_e32 v93, 0xffff0000, v103
	v_mul_f32_e32 v93, 0xbfb8aa3b, v93
	v_exp_f32_e32 v103, v93
	v_pk_mul_f32 v[42:43], v[42:43], v[106:107]
	v_pk_add_f32 v[102:103], v[102:103], 1.0 op_sel_hi:[1,0]
	s_nop 0
	v_rcp_f32_e32 v95, v103
	v_cvt_pk_bf16_f32 v42, v42, v43
	v_fma_f32 v101, -v103, v95, 1.0
	v_fmac_f32_e32 v95, v101, v95
	v_mul_f32_e32 v106, 1.0, v95
	v_fma_f32 v107, -v103, v106, 1.0
	v_fmac_f32_e32 v106, v107, v95
	v_fma_f32 v93, -v103, v106, 1.0
	v_fma_f32 v93, v93, v95, v106
	v_div_fixup_f32 v103, v93, v103, 1.0
	v_rcp_f32_e32 v95, v102
	s_nop 0
	v_fma_f32 v101, -v102, v95, 1.0
	v_fmac_f32_e32 v95, v101, v95
	v_mul_f32_e32 v106, 1.0, v95
	v_fma_f32 v107, -v102, v106, 1.0
	v_fmac_f32_e32 v106, v107, v95
	v_fma_f32 v93, -v102, v106, 1.0
	v_fma_f32 v93, v93, v95, v106
	v_div_fixup_f32 v102, v93, v102, 1.0
	v_pk_mul_f32 v[40:41], v[40:41], v[102:103]
	s_nop 0
	v_cvt_pk_bf16_f32 v43, v40, v41
	global_store_dwordx2 v[72:73], v[42:43], off
	global_load_dwordx2 v[40:41], v[104:105], off offset:96
	s_nop 0
	global_load_dwordx2 v[74:75], v[74:75], off offset:96
	s_waitcnt vmcnt(0) lgkmcnt(0)
	v_lshlrev_b32_e32 v73, 16, v40
	v_and_b32_e32 v93, 0xffff0000, v40
	v_lshlrev_b32_e32 v40, 16, v41
	v_mul_f32_e32 v42, 0xbfb8aa3b, v40
	v_exp_f32_e32 v42, v42
	s_nop 0
	v_add_f32_e32 v42, 1.0, v42
	v_rcp_f32_e32 v72, v42
	s_nop 0
	v_fma_f32 v95, -v42, v72, 1.0
	v_fmac_f32_e32 v72, v95, v72
	v_mul_f32_e32 v101, v40, v72
	v_fma_f32 v102, -v42, v101, v40
	v_fmac_f32_e32 v101, v102, v72
	v_fma_f32 v43, -v42, v101, v40
	v_fma_f32 v43, v43, v72, v101
	v_and_b32_e32 v95, 0xffff0000, v41
	v_div_fixup_f32 v72, v43, v42, v40
	v_mul_f32_e32 v40, 0xbfb8aa3b, v95
	v_exp_f32_e32 v102, v40
	v_lshlrev_b32_e32 v40, 16, v74
	v_mul_f32_e32 v40, 0xbfb8aa3b, v40
	v_exp_f32_e32 v104, v40
	v_and_b32_e32 v40, 0xffff0000, v74
	v_mul_f32_e32 v40, 0xbfb8aa3b, v40
	v_exp_f32_e32 v105, v40
	global_load_dwordx4 v[40:43], v[88:89], off offset:192
	v_pk_mul_f32 v[70:71], v[70:71], v[100:101] op_sel_hi:[1,0]
	v_mul_f32_e32 v74, 0xbfb8aa3b, v73
	v_exp_f32_e32 v106, v74
	s_waitcnt vmcnt(0)
	v_pk_mul_f32 v[40:41], v[70:71], v[40:41]
	v_mul_f32_e32 v70, 0xbfb8aa3b, v93
	v_exp_f32_e32 v107, v70
	s_nop 0
	v_pk_add_f32 v[70:71], v[106:107], 1.0 op_sel_hi:[1,0]
	s_nop 0
	v_rcp_f32_e32 v101, v71
	s_nop 0
	v_fma_f32 v103, -v71, v101, 1.0
	v_fmac_f32_e32 v101, v103, v101
	v_mul_f32_e32 v106, v93, v101
	v_fma_f32 v107, -v71, v106, v93
	v_fmac_f32_e32 v106, v107, v101
	v_fma_f32 v74, -v71, v106, v93
	v_fma_f32 v74, v74, v101, v106
	v_div_fixup_f32 v71, v74, v71, v93
	v_rcp_f32_e32 v93, v70
	s_nop 0
	v_fma_f32 v101, -v70, v93, 1.0
	v_fmac_f32_e32 v93, v101, v93
	v_mul_f32_e32 v103, v73, v93
	v_fma_f32 v106, -v70, v103, v73
	v_fmac_f32_e32 v103, v106, v93
	v_fma_f32 v74, -v70, v103, v73
	v_fma_f32 v74, v74, v93, v103
	v_div_fixup_f32 v70, v74, v70, v73
	v_pk_mul_f32 v[40:41], v[40:41], v[70:71]
	v_pk_add_f32 v[70:71], v[104:105], 1.0 op_sel_hi:[1,0]
	s_nop 0
	v_rcp_f32_e32 v74, v71
	s_nop 0
	v_fma_f32 v93, -v71, v74, 1.0
	v_fmac_f32_e32 v74, v93, v74
	v_mul_f32_e32 v101, 1.0, v74
	v_fma_f32 v103, -v71, v101, 1.0
	v_fmac_f32_e32 v101, v103, v74
	v_fma_f32 v73, -v71, v101, 1.0
	v_fma_f32 v73, v73, v74, v101
	v_div_fixup_f32 v71, v73, v71, 1.0
	v_rcp_f32_e32 v74, v70
	s_nop 0
	v_fma_f32 v93, -v70, v74, 1.0
	v_fmac_f32_e32 v74, v93, v74
	v_mul_f32_e32 v101, 1.0, v74
	v_fma_f32 v103, -v70, v101, 1.0
	v_fmac_f32_e32 v101, v103, v74
	v_fma_f32 v73, -v70, v101, 1.0
	v_fma_f32 v73, v73, v74, v101
	v_div_fixup_f32 v70, v73, v70, 1.0
	v_pk_mul_f32 v[40:41], v[40:41], v[70:71]
	v_lshlrev_b32_e32 v70, 16, v75
	v_mul_f32_e32 v70, 0xbfb8aa3b, v70
	v_exp_f32_e32 v70, v70
	v_cvt_pk_bf16_f32 v40, v40, v41
	v_add_f32_e32 v70, 1.0, v70
	v_rcp_f32_e32 v73, v70
	s_nop 0
	v_fma_f32 v74, -v70, v73, 1.0
	v_fmac_f32_e32 v73, v74, v73
	v_mul_f32_e32 v93, 1.0, v73
	v_fma_f32 v101, -v70, v93, 1.0
	v_fmac_f32_e32 v93, v101, v73
	v_fma_f32 v71, -v70, v93, 1.0
	v_fma_f32 v71, v71, v73, v93
	v_div_fixup_f32 v70, v71, v70, 1.0
	v_and_b32_e32 v71, 0xffff0000, v75
	v_mul_f32_e32 v71, 0xbfb8aa3b, v71
	v_exp_f32_e32 v103, v71
	s_nop 0
	v_pk_add_f32 v[74:75], v[102:103], 1.0 op_sel_hi:[1,0]
	s_nop 0
	v_rcp_f32_e32 v73, v75
	s_nop 0
	v_fma_f32 v93, -v75, v73, 1.0
	v_fmac_f32_e32 v73, v93, v73
	v_mul_f32_e32 v101, 1.0, v73
	v_fma_f32 v102, -v75, v101, 1.0
	v_fmac_f32_e32 v101, v102, v73
	v_fma_f32 v71, -v75, v101, 1.0
	v_fma_f32 v71, v71, v73, v101
	v_div_fixup_f32 v71, v71, v75, 1.0
	v_rcp_f32_e32 v75, v74
	s_mov_b64 s[0:1], 0
	v_fma_f32 v93, -v74, v75, 1.0
	v_fmac_f32_e32 v75, v93, v75
	v_mul_f32_e32 v101, v95, v75
	v_fma_f32 v102, -v74, v101, v95
	v_fmac_f32_e32 v101, v102, v75
	v_fma_f32 v73, -v74, v101, v95
	v_fma_f32 v73, v73, v75, v101
	v_pk_mul_f32 v[68:69], v[68:69], v[100:101] op_sel_hi:[1,0]
	v_div_fixup_f32 v73, v73, v74, v95
	v_pk_mul_f32 v[42:43], v[68:69], v[42:43]
	v_mov_b32_e32 v95, v161
	v_pk_mul_f32 v[42:43], v[42:43], v[72:73]
	v_lshl_add_u64 v[66:67], v[66:67], 0, v[94:95]
	v_pk_mul_f32 v[42:43], v[42:43], v[70:71]
	global_store_dword v[66:67], v40, off

; DI float sigmoidf_(float z) { return 1.f / (1.f + __expf(-z)); }
; DI void rec_setup_lb(const Params& p, int l, int h, unsigned char* smem, int tid) {
;   float* LB = (float*)(smem + L_LB);
;   __syncthreads();
;   if (tid < 64) LB[tid] = (l == 1) ? sigmoidf_(p.hg_lb[256 + h * 64 + tid] - p.hg_lb[h * 64 + tid]) : 0.f;
;   __syncthreads();
; }
.LBB0_939:
	s_and_b64 vcc, exec, s[0:1]
	s_cbranch_vccz .LBB0_803
	v_readlane_b32 s0, v253, 39
	v_mbcnt_lo_u32_b32 v2, -1, 0
	v_mbcnt_hi_u32_b32 v2, -1, v2
	s_waitcnt lgkmcnt(0)
	s_barrier
	v_or_b32_e32 v0, s0, v2
	v_cmp_gt_i32_e32 vcc, 64, v0
	s_and_saveexec_b64 s[0:1], vcc
	s_cbranch_execz .LBB0_944
	v_readlane_b32 s4, v254, 19
	v_readlane_b32 s5, v254, 20
	v_mov_b32_e32 v1, 0
	s_andn2_b64 vcc, exec, s[4:5]
	s_cbranch_vccnz .LBB0_943
	s_lshl_b32 s2, s48, 6
	v_ashrrev_i32_e32 v1, 31, v0
	v_readlane_b32 s52, v253, 23
	v_lshl_add_u64 v[4:5], s[2:3], 0, v[0:1]
	v_readlane_b32 s58, v253, 29
	v_readlane_b32 s59, v253, 30
	v_readlane_b32 s53, v253, 24
	v_readlane_b32 s54, v253, 25
	v_lshl_add_u64 v[4:5], v[4:5], 2, s[58:59]
	global_load_dword v1, v[4:5], off offset:1024
	v_add_u32_e32 v4, s2, v0
	v_ashrrev_i32_e32 v5, 31, v4
	v_lshl_add_u64 v[4:5], v[4:5], 2, s[58:59]
	global_load_dword v3, v[4:5], off
	v_readlane_b32 s55, v253, 26
	v_readlane_b32 s56, v253, 27
	v_readlane_b32 s57, v253, 28
	v_readlane_b32 s60, v253, 31
	v_readlane_b32 s61, v253, 32
	v_readlane_b32 s62, v253, 33
	v_readlane_b32 s63, v253, 34
	v_readlane_b32 s64, v253, 35
	v_readlane_b32 s65, v253, 36
	v_readlane_b32 s66, v253, 37
	v_readlane_b32 s67, v253, 38
	s_waitcnt vmcnt(0)
	v_sub_f32_e32 v1, v1, v3
	v_mul_f32_e32 v1, 0xbfb8aa3b, v1
	v_exp_f32_e32 v1, v1
	s_nop 0
	v_add_f32_e32 v1, 1.0, v1
	v_rcp_f32_e32 v4, v1
	s_nop 0
	v_fma_f32 v5, -v1, v4, 1.0
	v_fmac_f32_e32 v4, v5, v4
	v_mul_f32_e32 v6, 1.0, v4
	v_fma_f32 v7, -v1, v6, 1.0
	v_fmac_f32_e32 v6, v7, v4
	v_fma_f32 v3, -v1, v6, 1.0
	v_fma_f32 v3, v3, v4, v6
	v_div_fixup_f32 v1, v3, v1, 1.0

; template <int MX>
; DI RecRaw rec_load(const Params& p, int b, int h, int dir, int T0, int tid) {
;     ...
;     w.a0 = *(const uint4*)(rp + fcol); w.a1 = *(const uint4*)(rp + fcol + 8);
;     w.b0 = *(const uint4*)(rp + B_Q + h * 64 + k0); w.b1 = *(const uint4*)(rp + B_Q + h * 64 + k0 + 8);
;     w.c0 = *(const uint4*)(rp + B_I + h * 64 + k0); w.c1 = *(const uint4*)(rp + B_I + h * 64 + k0 + 8);
; template <int MX, bool OUT>
; DI void rec_chunk(const Params& p, int l, int b, int h, int dir, int T0, unsigned char* smem, f32x4 (&St)[4], float& nst, float& dtot, int tid, const RecRaw& raw) {
;     ...
;     if (MX == 0) {
; #pragma unroll
;       for (int i = 0; i < 8; ++i) {
; #pragma unroll
;         for (int hh = 0; hh < 2; ++hh) {
;           const int k = 2 * i + hh;
;           float z = __uint_as_float(hh ? (au[i] & 0xffff0000u) : (au[i] << 16));
;           z = fminf(fmaxf(z, -30.f), 30.f);
;           const float e = __expf(-z);
;           const float sg = 1.f / (1.f + e);
;           const float lb = LB[k0 + k];
;           lf[k] = __log2f(lb + (1.f - lb) * sg);
;           kin[k] = (1.f - lb) * (e * sg);
.LBB0_950:
	v_add_co_u32_e64 v95, s[26:27], s84, 1
	s_and_b64 s[26:27], s[26:27], exec
	s_cselect_b32 s34, 3, s83
	s_cselect_b32 s35, 0, s84
	s_and_b64 s[26:27], s[8:9], exec
	s_cselect_b32 s26, s34, s35
	s_lshl_b32 s26, s26, 6
	s_add_i32 s26, s26, s80
	s_ashr_i32 s27, s26, 31
	v_lshl_add_u64 v[16:17], v[82:83], 0, s[26:27]
	v_mov_b64_e32 v[18:19], s[4:5]
	v_mad_u64_u32 v[24:25], s[26:27], v16, s33, v[18:19]
	s_waitcnt vmcnt(0) lgkmcnt(0)
	v_lshlrev_b32_e32 v18, 16, v60
	v_max_f32_e32 v18, v18, v18
	v_med3_f32 v18, v18, s17, v190
	v_mul_f32_e32 v18, 0xbfb8aa3b, v18
	v_exp_f32_e32 v207, v18
	v_and_b32_e32 v60, 0xffff0000, v60
	v_max_f32_e32 v60, v60, v60
	v_med3_f32 v60, v60, s17, v190
	v_add_f32_e32 v64, 1.0, v207
	v_mul_f32_e32 v60, 0xbfb8aa3b, v60
	v_exp_f32_e32 v210, v60
	v_rcp_f32_e32 v66, v64
	v_mad_i32_i24 v25, v17, s33, v25
	v_lshl_add_u64 v[16:17], v[24:25], 0, v[160:161]
	v_add_f32_e32 v60, 1.0, v210
	v_fma_f32 v67, -v64, v66, 1.0
	v_fmac_f32_e32 v66, v67, v66
	v_rcp_f32_e32 v104, v60
	v_mul_f32_e32 v68, 1.0, v66
	v_fma_f32 v69, -v64, v68, 1.0
	v_fmac_f32_e32 v68, v69, v66
	v_fma_f32 v65, -v64, v68, 1.0
	v_fma_f32 v105, -v60, v104, 1.0
	v_fma_f32 v65, v65, v66, v68
	v_fmac_f32_e32 v104, v105, v104
	v_mul_f32_e32 v106, 1.0, v104
	v_fma_f32 v107, -v60, v106, 1.0
	v_fmac_f32_e32 v106, v107, v104
	v_fma_f32 v97, -v60, v106, 1.0
	v_lshlrev_b32_e32 v105, 16, v61
	v_max_f32_e32 v105, v105, v105
	v_med3_f32 v105, v105, s17, v190
	v_mul_f32_e32 v105, 0xbfb8aa3b, v105
	v_exp_f32_e32 v206, v105
	v_fma_f32 v97, v97, v104, v106
	v_div_fixup_f32 v213, v97, v60, 1.0
	v_and_b32_e32 v61, 0xffff0000, v61
	v_add_f32_e32 v60, 1.0, v206
	v_rcp_f32_e32 v104, v60
	v_max_f32_e32 v61, v61, v61
	v_med3_f32 v61, v61, s17, v190
	v_mul_f32_e32 v61, 0xbfb8aa3b, v61
	v_fma_f32 v105, -v60, v104, 1.0
	v_fmac_f32_e32 v104, v105, v104
	v_mul_f32_e32 v106, 1.0, v104
	v_fma_f32 v107, -v60, v106, 1.0
	v_exp_f32_e32 v203, v61
	v_fmac_f32_e32 v106, v107, v104
	v_fma_f32 v97, -v60, v106, 1.0
	v_fma_f32 v61, v97, v104, v106
	v_div_fixup_f32 v208, v61, v60, 1.0
	v_add_f32_e32 v60, 1.0, v203
	v_rcp_f32_e32 v97, v60
	v_lshl_add_u64 v[24:25], v[24:25], 0, s[20:21]
	v_lshl_add_u64 v[24:25], v[24:25], 0, v[98:99]
	global_load_dwordx4 v[20:23], v[16:17], off
	s_nop 0
	global_load_dwordx4 v[16:19], v[16:17], off offset:16
	v_fma_f32 v104, -v60, v97, 1.0
	v_fmac_f32_e32 v97, v104, v97
	v_mul_f32_e32 v105, 1.0, v97
	v_fma_f32 v106, -v60, v105, 1.0
	v_fmac_f32_e32 v105, v106, v97
	v_fma_f32 v61, -v60, v105, 1.0
	v_lshlrev_b32_e32 v104, 16, v62
	v_max_f32_e32 v104, v104, v104
	v_med3_f32 v104, v104, s17, v190
	v_mul_f32_e32 v104, 0xbfb8aa3b, v104
	v_exp_f32_e32 v200, v104
	v_fma_f32 v61, v61, v97, v105
	v_div_fixup_f32 v204, v61, v60, 1.0
	v_and_b32_e32 v62, 0xffff0000, v62
	v_add_f32_e32 v60, 1.0, v200
	v_rcp_f32_e32 v97, v60
	v_max_f32_e32 v62, v62, v62
	v_med3_f32 v62, v62, s17, v190
	v_mul_f32_e32 v62, 0xbfb8aa3b, v62
	v_fma_f32 v104, -v60, v97, 1.0
	v_fmac_f32_e32 v97, v104, v97
	v_mul_f32_e32 v105, 1.0, v97
	v_fma_f32 v106, -v60, v105, 1.0
	v_exp_f32_e32 v119, v62
	v_fmac_f32_e32 v105, v106, v97
	v_fma_f32 v61, -v60, v105, 1.0
	v_fma_f32 v61, v61, v97, v105
	v_div_fixup_f32 v201, v61, v60, 1.0
	v_add_f32_e32 v61, 1.0, v119
	global_load_dwordx4 v[36:39], v[24:25], off offset:1536
	global_load_dwordx4 v[32:35], v[24:25], off offset:1552
	global_load_dwordx4 v[28:31], v[24:25], off offset:3072
	s_nop 0
	global_load_dwordx4 v[24:27], v[24:25], off offset:3088
	v_div_fixup_f32 v211, v65, v64, 1.0
	ds_read_b128 v[68:71], v81
	ds_read_b128 v[100:103], v81 offset:16
	ds_read_b128 v[72:75], v81 offset:32
	ds_read_b128 v[64:67], v81 offset:48
	v_rcp_f32_e32 v97, v61
	s_waitcnt lgkmcnt(0)
	v_sub_f32_e32 v212, 1.0, v68
	v_sub_f32_e32 v202, 1.0, v100
	v_fma_f32 v60, v201, v202, v100
	v_fma_f32 v100, -v61, v97, 1.0
	v_fmac_f32_e32 v97, v100, v97
	v_mul_f32_e32 v104, 1.0, v97
	v_fma_f32 v105, -v61, v104, 1.0
	v_fmac_f32_e32 v104, v105, v97
	v_fma_f32 v62, -v61, v104, 1.0
	v_lshlrev_b32_e32 v100, 16, v63
	v_max_f32_e32 v100, v100, v100
	v_med3_f32 v100, v100, s17, v190
	v_mul_f32_e32 v100, 0xbfb8aa3b, v100
	v_exp_f32_e32 v116, v100
	v_fma_f32 v62, v62, v97, v104
	v_div_fixup_f32 v120, v62, v61, 1.0
	v_sub_f32_e32 v121, 1.0, v101
	v_add_f32_e32 v62, 1.0, v116
	v_rcp_f32_e32 v100, v62
	v_and_b32_e32 v63, 0xffff0000, v63
	v_fma_f32 v61, v120, v121, v101
	v_max_f32_e32 v63, v63, v63
	v_fma_f32 v101, -v62, v100, 1.0
	v_fmac_f32_e32 v100, v101, v100
	v_med3_f32 v63, v63, s17, v190
	v_mul_f32_e32 v104, 1.0, v100
	v_mul_f32_e32 v63, 0xbfb8aa3b, v63
	v_fma_f32 v105, -v62, v104, 1.0
	v_exp_f32_e32 v113, v63
	v_fmac_f32_e32 v104, v105, v100
	v_fma_f32 v97, -v62, v104, 1.0
	v_fma_f32 v63, v97, v100, v104
	v_div_fixup_f32 v117, v63, v62, 1.0
	v_add_f32_e32 v63, 1.0, v113
	v_rcp_f32_e32 v100, v63
	v_sub_f32_e32 v118, 1.0, v102
	v_fma_f32 v62, v117, v118, v102
	v_sub_f32_e32 v115, 1.0, v103
	v_fma_f32 v101, -v63, v100, 1.0
	v_fmac_f32_e32 v100, v101, v100
	v_mul_f32_e32 v102, 1.0, v100
	v_fma_f32 v104, -v63, v102, 1.0
	v_fmac_f32_e32 v102, v104, v100
	v_fma_f32 v97, -v63, v102, 1.0
	v_lshlrev_b32_e32 v101, 16, v56
	v_max_f32_e32 v101, v101, v101
	v_med3_f32 v101, v101, s17, v190
	v_mul_f32_e32 v101, 0xbfb8aa3b, v101
	v_exp_f32_e32 v110, v101
	v_fma_f32 v97, v97, v100, v102
	v_div_fixup_f32 v114, v97, v63, 1.0
	v_and_b32_e32 v56, 0xffff0000, v56
	v_add_f32_e32 v97, 1.0, v110
	v_rcp_f32_e32 v101, v97
	v_max_f32_e32 v56, v56, v56
	v_fmac_f32_e32 v103, v114, v115
	v_med3_f32 v56, v56, s17, v190
	v_fma_f32 v102, -v97, v101, 1.0
	v_fmac_f32_e32 v101, v102, v101
	v_log_f32_e32 v63, v103
	v_mul_f32_e32 v103, 1.0, v101
; template <int MX, bool OUT>
; DI void rec_chunk(const Params& p, int l, int b, int h, int dir, int T0, unsigned char* smem, f32x4 (&St)[4], float& nst, float& dtot, int tid, const RecRaw& raw) {
;     ...
;           const int k = 2 * i + hh;
;           float z = __uint_as_float(hh ? (au[i] & 0xffff0000u) : (au[i] << 16));
;           z = fminf(fmaxf(z, -30.f), 30.f);
;           const float e = __expf(-z);
;           const float sg = 1.f / (1.f + e);
;           const float lb = LB[k0 + k];
;           lf[k] = __log2f(lb + (1.f - lb) * sg);
;           kin[k] = (1.f - lb) * (e * sg);
;           qv[k] = __uint_as_float(hh ? (bu[i] & 0xffff0000u) : (bu[i] << 16)) * 0.125f;
;           vv[k] = __uint_as_float(hh ? (cu[i] & 0xffff0000u) : (cu[i] << 16));
;         }
;       }
;     } else {
;       const float ig = raw.ig, fg = raw.fg;
;       const float lfs = (fg < -20.f) ? fg * 1.4426950408889634f : -__log2f(1.f + __expf(-fg));
;       const float ei = __expf(ig) * 0.125f;
; #pragma unroll
;       for (int i = 0; i < 8; ++i) {
; #pragma unroll
;         for (int hh = 0; hh < 2; ++hh) {
;           const int k = 2 * i + hh;
;           lf[k] = lfs;
;           kin[k] = __uint_as_float(hh ? (au[i] & 0xffff0000u) : (au[i] << 16)) * ei;
;           qv[k] = __uint_as_float(hh ? (bu[i] & 0xffff0000u) : (bu[i] << 16));
;           vv[k] = __uint_as_float(hh ? (cu[i] & 0xffff0000u) : (cu[i] << 16));
;         }
;       }
;     }
; #pragma unroll
;     for (int i = 0; i < 4; ++i) { if (MX == 0) *(float4*)(CUM + tt * 64 + k0 + 4 * i) = make_float4(lf[4 * i], lf[4 * i + 1], lf[4 * i + 2], lf[4 * i + 3]); }
;     ...
;     const int k = tid & 63, part = tid >> 6;
;     float x[16];
;     float acc = 0.f;
;     if (dir == 0) {
; #pragma unroll
;       for (int i = 0; i < 16; ++i) { acc += CUM[(part * 16 + i) * 64 + k]; x[i] = acc; }
;     } else {
; #pragma unroll
;       for (int i = 15; i >= 0; --i) { acc += CUM[(part * 16 + i) * 64 + k]; x[i] = acc; }
;     }
;     TOT[part * 64 + k] = acc;
	v_mul_f32_e32 v56, 0xbfb8aa3b, v56
	v_fma_f32 v104, -v97, v103, 1.0
	v_exp_f32_e32 v107, v56
	v_fmac_f32_e32 v103, v104, v101
	v_fma_f32 v100, -v97, v103, 1.0
	v_fma_f32 v56, v100, v101, v103
	v_div_fixup_f32 v111, v56, v97, 1.0
	v_add_f32_e32 v56, 1.0, v107
	v_rcp_f32_e32 v100, v56
	v_sub_f32_e32 v112, 1.0, v72
	v_fma_f32 v72, v111, v112, v72
	v_log_f32_e32 v216, v72
	v_fma_f32 v72, -v56, v100, 1.0
	v_fmac_f32_e32 v100, v72, v100
	v_mul_f32_e32 v101, 1.0, v100
	v_fma_f32 v102, -v56, v101, 1.0
	v_fmac_f32_e32 v101, v102, v100
	v_fma_f32 v72, -v56, v101, 1.0
	v_lshlrev_b32_e32 v97, 16, v57
	v_max_f32_e32 v97, v97, v97
	v_med3_f32 v97, v97, s17, v190
	v_mul_f32_e32 v97, 0xbfb8aa3b, v97
	v_exp_f32_e32 v104, v97
	v_fma_f32 v72, v72, v100, v101
	v_div_fixup_f32 v108, v72, v56, 1.0
	v_sub_f32_e32 v109, 1.0, v73
	v_add_f32_e32 v56, 1.0, v104
	v_rcp_f32_e32 v97, v56
	v_fma_f32 v73, v108, v109, v73
	v_log_f32_e32 v217, v73
	v_and_b32_e32 v57, 0xffff0000, v57
	v_fma_f32 v73, -v56, v97, 1.0
	v_fmac_f32_e32 v97, v73, v97
	v_max_f32_e32 v57, v57, v57
	v_mul_f32_e32 v100, 1.0, v97
	v_med3_f32 v57, v57, s17, v190
	v_fma_f32 v101, -v56, v100, 1.0
	v_mul_f32_e32 v57, 0xbfb8aa3b, v57
	v_fmac_f32_e32 v100, v101, v97
	v_exp_f32_e32 v101, v57
	v_fma_f32 v72, -v56, v100, 1.0
	v_fma_f32 v57, v72, v97, v100
	v_div_fixup_f32 v105, v57, v56, 1.0
	v_add_f32_e32 v56, 1.0, v101
	v_rcp_f32_e32 v72, v56
	v_sub_f32_e32 v106, 1.0, v74
	v_fma_f32 v73, v105, v106, v74
	v_log_f32_e32 v218, v73
	v_fma_f32 v73, -v56, v72, 1.0
	v_fmac_f32_e32 v72, v73, v72
	v_mul_f32_e32 v74, 1.0, v72
	v_fma_f32 v97, -v56, v74, 1.0
	v_fmac_f32_e32 v74, v97, v72
	v_fma_f32 v57, -v56, v74, 1.0
	v_lshlrev_b32_e32 v73, 16, v58
	v_max_f32_e32 v73, v73, v73
	v_med3_f32 v73, v73, s17, v190
	v_mul_f32_e32 v73, 0xbfb8aa3b, v73
	v_exp_f32_e32 v97, v73
	v_fma_f32 v57, v57, v72, v74
	v_div_fixup_f32 v102, v57, v56, 1.0
	v_sub_f32_e32 v103, 1.0, v75
	v_add_f32_e32 v56, 1.0, v97
	v_rcp_f32_e32 v73, v56
	v_and_b32_e32 v58, 0xffff0000, v58
	v_fmac_f32_e32 v75, v102, v103
	v_max_f32_e32 v58, v58, v58
	v_fma_f32 v72, -v56, v73, 1.0
	v_fmac_f32_e32 v73, v72, v73
	v_mul_f32_e32 v74, 1.0, v73
	v_log_f32_e32 v219, v75
	v_fma_f32 v75, -v56, v74, 1.0
	v_med3_f32 v58, v58, s17, v190
	v_fmac_f32_e32 v74, v75, v73
	v_mul_f32_e32 v58, 0xbfb8aa3b, v58
	v_fma_f32 v57, -v56, v74, 1.0
	v_exp_f32_e32 v72, v58
	v_fma_f32 v57, v57, v73, v74
	v_div_fixup_f32 v75, v57, v56, 1.0
	v_sub_f32_e32 v100, 1.0, v64
	v_add_f32_e32 v56, 1.0, v72
	v_rcp_f32_e32 v58, v56
	v_fma_f32 v64, v75, v100, v64
	v_log_f32_e32 v220, v64
	v_sub_f32_e32 v214, 1.0, v69
	v_fma_f32 v64, -v56, v58, 1.0
	v_fmac_f32_e32 v58, v64, v58
	v_mul_f32_e32 v73, 1.0, v58
	v_fma_f32 v74, -v56, v73, 1.0
	v_fmac_f32_e32 v73, v74, v58
	v_fma_f32 v57, -v56, v73, 1.0
	v_lshlrev_b32_e32 v64, 16, v59
	v_max_f32_e32 v64, v64, v64
	v_med3_f32 v64, v64, s17, v190
	v_mul_f32_e32 v64, 0xbfb8aa3b, v64
	v_exp_f32_e32 v64, v64
	v_fma_f32 v57, v57, v58, v73
	v_div_fixup_f32 v73, v57, v56, 1.0
	v_sub_f32_e32 v74, 1.0, v65
	v_add_f32_e32 v57, 1.0, v64
	v_rcp_f32_e32 v58, v57
	v_fma_f32 v65, v73, v74, v65
	v_log_f32_e32 v221, v65
	v_sub_f32_e32 v209, 1.0, v70
	v_fma_f32 v65, -v57, v58, 1.0
	v_fmac_f32_e32 v58, v65, v58
	v_mul_f32_e32 v215, 1.0, v58
	v_fma_f32 v222, -v57, v215, 1.0
	v_fmac_f32_e32 v215, v222, v58
	v_fma_f32 v65, -v57, v215, 1.0
	v_and_b32_e32 v56, 0xffff0000, v59
	v_max_f32_e32 v56, v56, v56
	v_med3_f32 v56, v56, s17, v190
	v_mul_f32_e32 v56, 0xbfb8aa3b, v56
	v_exp_f32_e32 v56, v56
	v_fma_f32 v58, v65, v58, v215
	v_div_fixup_f32 v59, v58, v57, 1.0
	v_sub_f32_e32 v65, 1.0, v66
	v_add_f32_e32 v57, 1.0, v56
	v_rcp_f32_e32 v215, v57
	v_fma_f32 v66, v59, v65, v66
	v_log_f32_e32 v222, v66
	v_sub_f32_e32 v205, 1.0, v71
	v_fma_f32 v66, -v57, v215, 1.0
	v_fmac_f32_e32 v215, v66, v215
	v_mul_f32_e32 v223, 1.0, v215
	v_fma_f32 v224, -v57, v223, 1.0
	v_fmac_f32_e32 v223, v224, v215
	v_fma_f32 v68, v211, v212, v68
	v_fma_f32 v69, v213, v214, v69
	v_fma_f32 v70, v208, v209, v70
	v_fmac_f32_e32 v71, v204, v205
	v_fma_f32 v58, -v57, v223, 1.0
	v_log_f32_e32 v68, v68
	v_log_f32_e32 v69, v69
	v_log_f32_e32 v70, v70
	v_log_f32_e32 v71, v71
	v_fma_f32 v58, v58, v215, v223
	v_log_f32_e32 v60, v60
	v_log_f32_e32 v61, v61
	v_log_f32_e32 v62, v62
	v_div_fixup_f32 v57, v58, v57, 1.0
	v_sub_f32_e32 v58, 1.0, v67
	v_fmac_f32_e32 v67, v57, v58
	v_log_f32_e32 v223, v67
	ds_write_b128 v122, v[68:71]
	ds_write_b128 v122, v[60:63] offset:16
	ds_write_b128 v122, v[216:219] offset:32
	ds_write_b128 v122, v[220:223] offset:48
	v_cndmask_b32_e64 v60, 0, 1, s[10:11]
	v_cmp_ne_u32_e64 s[78:79], 1, v60
	s_andn2_b64 vcc, exec, s[10:11]
	s_mov_b64 s[26:27], -1
	s_waitcnt lgkmcnt(0)
	s_barrier
	s_cbranch_vccnz .LBB0_952
	ds_read2st64_b32 v[60:61], v123 offset0:14 offset1:15
	s_mov_b64 s[26:27], 0
	ds_read2st64_b32 v[62:63], v123 offset0:8 offset1:9
	ds_read2st64_b32 v[216:217], v123 offset0:6 offset1:7
	ds_read2st64_b32 v[218:219], v123 offset0:2 offset1:3
	ds_read2st64_b32 v[220:221], v123 offset1:1
	s_waitcnt lgkmcnt(0)
	v_add_f32_e32 v70, 0, v61
	v_add_f32_e32 v71, v70, v60
	ds_read2st64_b32 v[60:61], v123 offset0:12 offset1:13
	s_waitcnt lgkmcnt(0)
	v_add_f32_e32 v66, v71, v61
	v_add_f32_e32 v67, v66, v60
	ds_read2st64_b32 v[60:61], v123 offset0:10 offset1:11
	s_waitcnt lgkmcnt(0)
	v_add_f32_e32 v68, v67, v61
	v_add_f32_e32 v69, v68, v60
	v_add_f32_e32 v60, v69, v63
	v_add_f32_e32 v61, v60, v62
	v_add_f32_e32 v62, v61, v217
	v_add_f32_e32 v63, v62, v216
	ds_read2st64_b32 v[216:217], v123 offset0:4 offset1:5
	s_waitcnt lgkmcnt(0)
	v_add_f32_e32 v215, v63, v217
	v_add_f32_e32 v216, v215, v216
	v_add_f32_e32 v217, v216, v219
	v_add_f32_e32 v218, v217, v218
	v_add_f32_e32 v219, v218, v221
	v_add_f32_e32 v220, v219, v220
